# next tile's first LDS-DMA group requested before the epilogue; first three waits of the peeled iteration count the epilogue stores out (vmcnt 8+S), on v027
# baseline (speedup 1.0000x reference)
.Lmy_nobar2_2:
	ds_read_b128 v[152:155], v157
	ds_read_b128 v[160:163], v157 offset:1024
	ds_read_b128 v[164:167], v157 offset:2048
	ds_read_b128 v[168:171], v157 offset:3072
	ds_read_b128 v[172:175], v158
	ds_read_b128 v[176:179], v158 offset:1024
	ds_read_b128 v[180:183], v158 offset:2048
	ds_read_b128 v[184:187], v158 offset:3072
	s_add_u32 s34, s50, 0xfffc0080
	s_addc_u32 s35, s51, -1
	s_cmp_eq_u32 s86, 12
	s_cselect_b32 s55, s7, s35
	s_cselect_b32 s54, s8, s34
	s_cselect_b32 s53, s12, s41
	s_cselect_b32 s52, s13, s29
	v_lshl_add_u64 v[220:221], s[50:51], 0, v[144:145]
	s_add_i32 m0, s63, 0xc000
	ds_read_b128 v[188:191], v159
	ds_read_b128 v[192:195], v159 offset:1024
	ds_read_b128 v[196:199], v159 offset:2048
	ds_read_b128 v[200:203], v159 offset:3072
	ds_read_b128 v[204:207], v159 offset:4096
	ds_read_b128 v[208:211], v159 offset:5120
	ds_read_b128 v[212:215], v159 offset:6144
	ds_read_b128 v[216:219], v159 offset:7168
	s_cmp_lg_u32 s84, 1
	s_cbranch_scc1 .Lmy_sk_2_0
	global_load_lds_dwordx4 v[220:221], off
.Lmy_sk_2_0:
	v_lshl_add_u64 v[220:221], s[50:51], 0, v[146:147]
	s_add_i32 m0, s63, 0xe000
	s_nop 0
	s_cmp_lg_u32 s84, 1
	s_cbranch_scc1 .Lmy_sk_2_1
	global_load_lds_dwordx4 v[220:221], off
.Lmy_sk_2_1:
	s_cmp_lg_u32 s84, 1
	s_cbranch_scc1 .Lmy_rl_2_0
	s_waitcnt vmcnt(8)
	s_branch .Lmy_rj_2_0
.Lmy_rl_2_0:
	s_waitcnt vmcnt(16)
.Lmy_rj_2_0:
	s_waitcnt lgkmcnt(0)
	s_barrier
	s_setprio 1
	s_waitcnt lgkmcnt(0)
	v_mfma_f32_16x16x32_bf16 v[124:127], v[152:155], v[188:191], 0
	v_mfma_f32_16x16x32_bf16 v[120:123], v[164:167], v[188:191], 0
	v_mfma_f32_16x16x32_bf16 v[108:111], v[152:155], v[196:199], 0
	v_mfma_f32_16x16x32_bf16 v[104:107], v[164:167], v[196:199], 0
	v_mfma_f32_16x16x32_bf16 v[92:95], v[152:155], v[204:207], 0
	v_mfma_f32_16x16x32_bf16 v[88:91], v[164:167], v[204:207], 0
	v_mfma_f32_16x16x32_bf16 v[76:79], v[152:155], v[212:215], 0
	v_mfma_f32_16x16x32_bf16 v[72:75], v[164:167], v[212:215], 0
	v_mfma_f32_16x16x32_bf16 v[124:127], v[160:163], v[192:195], v[124:127]
	v_mfma_f32_16x16x32_bf16 v[120:123], v[168:171], v[192:195], v[120:123]
	v_mfma_f32_16x16x32_bf16 v[108:111], v[160:163], v[200:203], v[108:111]
	v_mfma_f32_16x16x32_bf16 v[104:107], v[168:171], v[200:203], v[104:107]
	v_mfma_f32_16x16x32_bf16 v[92:95], v[160:163], v[208:211], v[92:95]
	v_mfma_f32_16x16x32_bf16 v[88:91], v[168:171], v[208:211], v[88:91]
	v_mfma_f32_16x16x32_bf16 v[76:79], v[160:163], v[216:219], v[76:79]
	v_mfma_f32_16x16x32_bf16 v[72:75], v[168:171], v[216:219], v[72:75]
	s_setprio 0
	s_setprio 1
	v_mfma_f32_16x16x32_bf16 v[116:119], v[172:175], v[188:191], 0
	v_mfma_f32_16x16x32_bf16 v[112:115], v[180:183], v[188:191], 0
	v_mfma_f32_16x16x32_bf16 v[100:103], v[172:175], v[196:199], 0
	v_mfma_f32_16x16x32_bf16 v[96:99], v[180:183], v[196:199], 0
	v_mfma_f32_16x16x32_bf16 v[84:87], v[172:175], v[204:207], 0
	v_mfma_f32_16x16x32_bf16 v[80:83], v[180:183], v[204:207], 0
	v_mfma_f32_16x16x32_bf16 v[68:71], v[172:175], v[212:215], 0
	v_mfma_f32_16x16x32_bf16 v[64:67], v[180:183], v[212:215], 0
	v_mfma_f32_16x16x32_bf16 v[116:119], v[176:179], v[192:195], v[116:119]
	v_mfma_f32_16x16x32_bf16 v[112:115], v[184:187], v[192:195], v[112:115]
	v_mfma_f32_16x16x32_bf16 v[100:103], v[176:179], v[200:203], v[100:103]
	v_mfma_f32_16x16x32_bf16 v[96:99], v[184:187], v[200:203], v[96:99]
	v_mfma_f32_16x16x32_bf16 v[84:87], v[176:179], v[208:211], v[84:87]
	v_mfma_f32_16x16x32_bf16 v[80:83], v[184:187], v[208:211], v[80:83]
	v_mfma_f32_16x16x32_bf16 v[68:71], v[176:179], v[216:219], v[68:71]
	v_mfma_f32_16x16x32_bf16 v[64:67], v[184:187], v[216:219], v[64:67]
	s_setprio 0
	s_barrier
	s_add_i32 s34, s82, s58
	v_lshl_add_u64 v[220:221], s[52:53], 0, v[136:137]
	s_mov_b32 m0, s34
	ds_read_b128 v[188:191], v159 offset:16384
	ds_read_b128 v[192:195], v159 offset:17408
	ds_read_b128 v[196:199], v159 offset:18432
	ds_read_b128 v[200:203], v159 offset:19456
	ds_read_b128 v[204:207], v159 offset:20480
	ds_read_b128 v[208:211], v159 offset:21504
	ds_read_b128 v[212:215], v159 offset:22528
	ds_read_b128 v[216:219], v159 offset:23552
	global_load_lds_dwordx4 v[220:221], off
	s_add_i32 m0, s34, 0x2000
	s_add_u32 s34, s52, 0x40000
	v_lshl_add_u64 v[222:223], s[52:53], 0, v[140:141]
	s_addc_u32 s35, s53, 0
	s_add_i32 s87, s83, s58
	global_load_lds_dwordx4 v[222:223], off
	v_lshl_add_u64 v[224:225], s[34:35], 0, v[136:137]
	s_mov_b32 m0, s87
	v_lshl_add_u64 v[226:227], s[54:55], 0, v[138:139]
	global_load_lds_dwordx4 v[224:225], off
	v_lshl_add_u64 v[224:225], s[34:35], 0, v[140:141]
	s_add_i32 m0, s87, 0x2000
	s_nop 0
	global_load_lds_dwordx4 v[224:225], off
	v_lshl_add_u64 v[224:225], s[54:55], 0, v[134:135]
	s_mov_b32 m0, s63
	s_nop 0
	global_load_lds_dwordx4 v[224:225], off
	s_mov_b32 m0, s64
	s_nop 0
	global_load_lds_dwordx4 v[226:227], off
	s_cmp_lg_u32 s84, 1
	s_cbranch_scc1 .Lmy_rl_2_1
	s_waitcnt vmcnt(8)
	s_branch .Lmy_rj_2_1

.Lmy_rj_2_1:
	s_waitcnt lgkmcnt(0)
	s_barrier
	s_setprio 1
	s_waitcnt lgkmcnt(0)
	v_mfma_f32_16x16x32_bf16 v[60:63], v[152:155], v[188:191], 0
	v_mfma_f32_16x16x32_bf16 v[56:59], v[164:167], v[188:191], 0
	v_mfma_f32_16x16x32_bf16 v[44:47], v[152:155], v[196:199], 0
	v_mfma_f32_16x16x32_bf16 v[40:43], v[164:167], v[196:199], 0
	v_mfma_f32_16x16x32_bf16 v[28:31], v[152:155], v[204:207], 0
	v_mfma_f32_16x16x32_bf16 v[24:27], v[164:167], v[204:207], 0
	v_mfma_f32_16x16x32_bf16 v[12:15], v[152:155], v[212:215], 0
	v_mfma_f32_16x16x32_bf16 v[8:11], v[164:167], v[212:215], 0
	v_mfma_f32_16x16x32_bf16 v[60:63], v[160:163], v[192:195], v[60:63]
	v_mfma_f32_16x16x32_bf16 v[56:59], v[168:171], v[192:195], v[56:59]
	v_mfma_f32_16x16x32_bf16 v[44:47], v[160:163], v[200:203], v[44:47]
	v_mfma_f32_16x16x32_bf16 v[40:43], v[168:171], v[200:203], v[40:43]
	v_mfma_f32_16x16x32_bf16 v[28:31], v[160:163], v[208:211], v[28:31]
	v_mfma_f32_16x16x32_bf16 v[24:27], v[168:171], v[208:211], v[24:27]
	v_mfma_f32_16x16x32_bf16 v[12:15], v[160:163], v[216:219], v[12:15]
	v_mfma_f32_16x16x32_bf16 v[8:11], v[168:171], v[216:219], v[8:11]
	s_setprio 0
	s_setprio 1
	v_mfma_f32_16x16x32_bf16 v[52:55], v[172:175], v[188:191], 0
	v_mfma_f32_16x16x32_bf16 v[48:51], v[180:183], v[188:191], 0
	v_mfma_f32_16x16x32_bf16 v[36:39], v[172:175], v[196:199], 0
	v_mfma_f32_16x16x32_bf16 v[32:35], v[180:183], v[196:199], 0
	v_mfma_f32_16x16x32_bf16 v[20:23], v[172:175], v[204:207], 0
	v_mfma_f32_16x16x32_bf16 v[16:19], v[180:183], v[204:207], 0
	v_mfma_f32_16x16x32_bf16 v[4:7], v[172:175], v[212:215], 0
	v_mfma_f32_16x16x32_bf16 v[0:3], v[180:183], v[212:215], 0
	v_mfma_f32_16x16x32_bf16 v[52:55], v[176:179], v[192:195], v[52:55]
	v_mfma_f32_16x16x32_bf16 v[48:51], v[184:187], v[192:195], v[48:51]
	v_mfma_f32_16x16x32_bf16 v[36:39], v[176:179], v[200:203], v[36:39]
	v_mfma_f32_16x16x32_bf16 v[32:35], v[184:187], v[200:203], v[32:35]
	v_mfma_f32_16x16x32_bf16 v[20:23], v[176:179], v[208:211], v[20:23]
	v_mfma_f32_16x16x32_bf16 v[16:19], v[184:187], v[208:211], v[16:19]
	v_mfma_f32_16x16x32_bf16 v[4:7], v[176:179], v[216:219], v[4:7]
	v_mfma_f32_16x16x32_bf16 v[0:3], v[184:187], v[216:219], v[0:3]
	s_setprio 0
	s_barrier
	s_add_i32 s87, 0, 0x18000
	v_add_u32_e32 v142, s87, v133
	s_add_i32 s88, 0, 0x1c000
	ds_read_b128 v[152:155], v142
	ds_read_b128 v[160:163], v142 offset:1024
	ds_read_b128 v[164:167], v142 offset:2048
	ds_read_b128 v[168:171], v142 offset:3072
	v_add_u32_e32 v142, s88, v133
	ds_read_b128 v[172:175], v142
	ds_read_b128 v[176:179], v142 offset:1024
	ds_read_b128 v[180:183], v142 offset:2048
	ds_read_b128 v[184:187], v142 offset:3072
	s_add_u32 s34, s54, 0x40000
	s_addc_u32 s35, s55, 0
	s_mov_b32 m0, s65
	v_lshl_add_u64 v[228:229], s[34:35], 0, v[134:135]
	ds_read_b128 v[188:191], v159 offset:32768
	ds_read_b128 v[192:195], v159 offset:33792
	ds_read_b128 v[196:199], v159 offset:34816
	ds_read_b128 v[200:203], v159 offset:35840
	ds_read_b128 v[204:207], v159 offset:36864
	ds_read_b128 v[208:211], v159 offset:37888
	ds_read_b128 v[212:215], v159 offset:38912
	ds_read_b128 v[216:219], v159 offset:39936
	global_load_lds_dwordx4 v[228:229], off
	v_lshl_add_u64 v[228:229], s[34:35], 0, v[138:139]
	s_mov_b32 m0, s66
	s_nop 0
	global_load_lds_dwordx4 v[228:229], off
	s_cmp_lg_u32 s84, 1
	s_cbranch_scc1 .Lmy_rl_2_2
	s_waitcnt vmcnt(8)
	s_branch .Lmy_rj_2_2

.Lmy_rj_2_2:
	s_waitcnt lgkmcnt(0)
	s_barrier
	s_setprio 1
	s_waitcnt lgkmcnt(0)
	v_mfma_f32_16x16x32_bf16 v[124:127], v[152:155], v[188:191], v[124:127]
	v_mfma_f32_16x16x32_bf16 v[120:123], v[164:167], v[188:191], v[120:123]
	v_mfma_f32_16x16x32_bf16 v[108:111], v[152:155], v[196:199], v[108:111]
	v_mfma_f32_16x16x32_bf16 v[104:107], v[164:167], v[196:199], v[104:107]
	v_mfma_f32_16x16x32_bf16 v[92:95], v[152:155], v[204:207], v[92:95]
	v_mfma_f32_16x16x32_bf16 v[88:91], v[164:167], v[204:207], v[88:91]
	v_mfma_f32_16x16x32_bf16 v[76:79], v[152:155], v[212:215], v[76:79]
	v_mfma_f32_16x16x32_bf16 v[72:75], v[164:167], v[212:215], v[72:75]
	v_mfma_f32_16x16x32_bf16 v[124:127], v[160:163], v[192:195], v[124:127]
	v_mfma_f32_16x16x32_bf16 v[120:123], v[168:171], v[192:195], v[120:123]
	v_mfma_f32_16x16x32_bf16 v[108:111], v[160:163], v[200:203], v[108:111]
	v_mfma_f32_16x16x32_bf16 v[104:107], v[168:171], v[200:203], v[104:107]
	v_mfma_f32_16x16x32_bf16 v[92:95], v[160:163], v[208:211], v[92:95]
	v_mfma_f32_16x16x32_bf16 v[88:91], v[168:171], v[208:211], v[88:91]
	v_mfma_f32_16x16x32_bf16 v[76:79], v[160:163], v[216:219], v[76:79]
	v_mfma_f32_16x16x32_bf16 v[72:75], v[168:171], v[216:219], v[72:75]
	s_setprio 0
	s_setprio 1
	v_mfma_f32_16x16x32_bf16 v[116:119], v[172:175], v[188:191], v[116:119]
	v_mfma_f32_16x16x32_bf16 v[112:115], v[180:183], v[188:191], v[112:115]
	v_mfma_f32_16x16x32_bf16 v[100:103], v[172:175], v[196:199], v[100:103]
	v_mfma_f32_16x16x32_bf16 v[96:99], v[180:183], v[196:199], v[96:99]
	v_mfma_f32_16x16x32_bf16 v[84:87], v[172:175], v[204:207], v[84:87]
	v_mfma_f32_16x16x32_bf16 v[80:83], v[180:183], v[204:207], v[80:83]
	v_mfma_f32_16x16x32_bf16 v[68:71], v[172:175], v[212:215], v[68:71]
	v_mfma_f32_16x16x32_bf16 v[64:67], v[180:183], v[212:215], v[64:67]
	v_mfma_f32_16x16x32_bf16 v[116:119], v[176:179], v[192:195], v[116:119]
	v_mfma_f32_16x16x32_bf16 v[112:115], v[184:187], v[192:195], v[112:115]
	v_mfma_f32_16x16x32_bf16 v[100:103], v[176:179], v[200:203], v[100:103]
	v_mfma_f32_16x16x32_bf16 v[96:99], v[184:187], v[200:203], v[96:99]
	v_mfma_f32_16x16x32_bf16 v[84:87], v[176:179], v[208:211], v[84:87]
	v_mfma_f32_16x16x32_bf16 v[80:83], v[184:187], v[208:211], v[80:83]
	v_mfma_f32_16x16x32_bf16 v[68:71], v[176:179], v[216:219], v[68:71]
	v_mfma_f32_16x16x32_bf16 v[64:67], v[184:187], v[216:219], v[64:67]
	s_setprio 0
	s_barrier
	s_add_i32 s34, s87, s58
	v_lshl_add_u64 v[220:221], v[220:221], 0, s[22:23]
	s_mov_b32 m0, s34
	ds_read_b128 v[188:191], v159 offset:49152
	ds_read_b128 v[192:195], v159 offset:50176
	ds_read_b128 v[196:199], v159 offset:51200
	ds_read_b128 v[200:203], v159 offset:52224
	ds_read_b128 v[204:207], v159 offset:53248
	ds_read_b128 v[208:211], v159 offset:54272
	ds_read_b128 v[212:215], v159 offset:55296
	ds_read_b128 v[216:219], v159 offset:56320
	global_load_lds_dwordx4 v[220:221], off
	s_add_i32 m0, s34, 0x2000
	s_add_u32 s34, s52, 0x40080
	v_lshl_add_u64 v[220:221], v[222:223], 0, s[22:23]
	s_addc_u32 s35, s53, 0
	s_add_i32 s52, s88, s58
	global_load_lds_dwordx4 v[220:221], off
	v_lshl_add_u64 v[220:221], s[34:35], 0, v[136:137]
	s_mov_b32 m0, s52
	s_nop 0
	global_load_lds_dwordx4 v[220:221], off
	v_lshl_add_u64 v[220:221], s[34:35], 0, v[140:141]
	s_add_i32 m0, s52, 0x2000
	s_nop 0
	global_load_lds_dwordx4 v[220:221], off
	v_lshl_add_u64 v[220:221], v[224:225], 0, s[22:23]
	s_mov_b32 m0, s79
	s_nop 0
	global_load_lds_dwordx4 v[220:221], off
	v_lshl_add_u64 v[220:221], v[226:227], 0, s[22:23]
	s_mov_b32 m0, s81
	s_nop 0
	global_load_lds_dwordx4 v[220:221], off
	s_waitcnt vmcnt(8)
	s_waitcnt lgkmcnt(0)
	s_barrier
	s_setprio 1
	s_waitcnt lgkmcnt(0)
	v_mfma_f32_16x16x32_bf16 v[60:63], v[152:155], v[188:191], v[60:63]
	v_mfma_f32_16x16x32_bf16 v[56:59], v[164:167], v[188:191], v[56:59]
	v_mfma_f32_16x16x32_bf16 v[44:47], v[152:155], v[196:199], v[44:47]
	v_mfma_f32_16x16x32_bf16 v[40:43], v[164:167], v[196:199], v[40:43]
	v_mfma_f32_16x16x32_bf16 v[28:31], v[152:155], v[204:207], v[28:31]
	v_mfma_f32_16x16x32_bf16 v[24:27], v[164:167], v[204:207], v[24:27]
	v_mfma_f32_16x16x32_bf16 v[12:15], v[152:155], v[212:215], v[12:15]
	v_mfma_f32_16x16x32_bf16 v[8:11], v[164:167], v[212:215], v[8:11]
	v_mfma_f32_16x16x32_bf16 v[60:63], v[160:163], v[192:195], v[60:63]
	v_mfma_f32_16x16x32_bf16 v[56:59], v[168:171], v[192:195], v[56:59]
	v_mfma_f32_16x16x32_bf16 v[44:47], v[160:163], v[200:203], v[44:47]
	v_mfma_f32_16x16x32_bf16 v[40:43], v[168:171], v[200:203], v[40:43]
	v_mfma_f32_16x16x32_bf16 v[28:31], v[160:163], v[208:211], v[28:31]
	v_mfma_f32_16x16x32_bf16 v[24:27], v[168:171], v[208:211], v[24:27]
	v_mfma_f32_16x16x32_bf16 v[12:15], v[160:163], v[216:219], v[12:15]
	v_mfma_f32_16x16x32_bf16 v[8:11], v[168:171], v[216:219], v[8:11]
	s_setprio 0
	s_setprio 1
	v_mfma_f32_16x16x32_bf16 v[52:55], v[172:175], v[188:191], v[52:55]
	v_mfma_f32_16x16x32_bf16 v[48:51], v[180:183], v[188:191], v[48:51]
	v_mfma_f32_16x16x32_bf16 v[36:39], v[172:175], v[196:199], v[36:39]
	v_mfma_f32_16x16x32_bf16 v[32:35], v[180:183], v[196:199], v[32:35]
	v_mfma_f32_16x16x32_bf16 v[20:23], v[172:175], v[204:207], v[20:23]
	v_mfma_f32_16x16x32_bf16 v[16:19], v[180:183], v[204:207], v[16:19]
	v_mfma_f32_16x16x32_bf16 v[4:7], v[172:175], v[212:215], v[4:7]
	v_mfma_f32_16x16x32_bf16 v[0:3], v[180:183], v[212:215], v[0:3]
	v_mfma_f32_16x16x32_bf16 v[52:55], v[176:179], v[192:195], v[52:55]
	v_mfma_f32_16x16x32_bf16 v[48:51], v[184:187], v[192:195], v[48:51]
	v_mfma_f32_16x16x32_bf16 v[36:39], v[176:179], v[200:203], v[36:39]
	v_mfma_f32_16x16x32_bf16 v[32:35], v[184:187], v[200:203], v[32:35]
	v_mfma_f32_16x16x32_bf16 v[20:23], v[176:179], v[208:211], v[20:23]
	v_mfma_f32_16x16x32_bf16 v[16:19], v[184:187], v[208:211], v[16:19]
	v_mfma_f32_16x16x32_bf16 v[4:7], v[176:179], v[216:219], v[4:7]
	v_mfma_f32_16x16x32_bf16 v[0:3], v[184:187], v[216:219], v[0:3]
	s_setprio 0
	s_barrier
	s_add_i32 s86, s86, 2
	s_add_u32 s50, s50, 0x100
	s_addc_u32 s51, s51, 0
	s_add_u32 s29, s29, 0x100
	s_addc_u32 s41, s41, 0

.Lmy_nobar_2:
	s_add_i32 s86, s86, 2
	s_add_u32 s50, s50, 0x100
	s_addc_u32 s51, s51, 0
	s_add_u32 s29, s29, 0x100
	s_addc_u32 s41, s41, 0
	s_cmp_gt_u32 s86, 13
	s_cbranch_scc0 .LBB0_211
	s_add_u32 s100, s8, 0x40080
	s_addc_u32 s101, s7, 0
	s_add_i32 m0, s63, 0xc000
	v_lshl_add_u64 v[220:221], s[100:101], 0, v[144:145]
	global_load_lds_dwordx4 v[220:221], off
	s_add_i32 m0, s63, 0xe000
	v_lshl_add_u64 v[220:221], s[100:101], 0, v[146:147]
	global_load_lds_dwordx4 v[220:221], off
	s_and_b64 vcc, exec, s[26:27]
	s_cbranch_vccz .LBB0_214
	s_nop 0

.Lmy_nobar2_4:
	ds_read_b128 v[148:151], v154
	ds_read_b128 v[160:163], v154 offset:1024
	ds_read_b128 v[164:167], v154 offset:2048
	ds_read_b128 v[168:171], v154 offset:3072
	ds_read_b128 v[172:175], v155
	ds_read_b128 v[176:179], v155 offset:1024
	ds_read_b128 v[180:183], v155 offset:2048
	ds_read_b128 v[184:187], v155 offset:3072
	s_add_u32 s34, s50, 0xfffc0080
	s_addc_u32 s35, s51, -1
	s_cmp_eq_u32 s85, 12
	s_cselect_b32 s55, s12, s35
	s_cselect_b32 s54, s13, s34
	s_cselect_b32 s53, s27, s77
	s_cselect_b32 s52, s29, s49
	v_lshl_add_u64 v[220:221], s[50:51], 0, v[140:141]
	s_add_i32 m0, s58, 0xc000
	ds_read_b128 v[188:191], v157
	ds_read_b128 v[192:195], v157 offset:1024
	ds_read_b128 v[196:199], v157 offset:2048
	ds_read_b128 v[200:203], v157 offset:3072
	ds_read_b128 v[204:207], v157 offset:4096
	ds_read_b128 v[208:211], v157 offset:5120
	ds_read_b128 v[212:215], v157 offset:6144
	ds_read_b128 v[216:219], v157 offset:7168
	s_cmp_lg_u32 s84, 1
	s_cbranch_scc1 .Lmy_sk_4_0
	global_load_lds_dwordx4 v[220:221], off
.Lmy_sk_4_0:
	v_lshl_add_u64 v[220:221], s[50:51], 0, v[142:143]
	s_add_i32 m0, s58, 0xe000
	s_nop 0
	s_cmp_lg_u32 s84, 1
	s_cbranch_scc1 .Lmy_sk_4_1
	global_load_lds_dwordx4 v[220:221], off

.Lmy_rl_4_0:
	s_waitcnt vmcnt(40)
.Lmy_rj_4_0:
	s_waitcnt lgkmcnt(0)
	s_barrier
	s_setprio 1
	s_waitcnt lgkmcnt(0)
	v_mfma_f32_16x16x32_bf16 v[124:127], v[148:151], v[188:191], 0
	v_mfma_f32_16x16x32_bf16 v[120:123], v[164:167], v[188:191], 0
	v_mfma_f32_16x16x32_bf16 v[108:111], v[148:151], v[196:199], 0
	v_mfma_f32_16x16x32_bf16 v[104:107], v[164:167], v[196:199], 0
	v_mfma_f32_16x16x32_bf16 v[92:95], v[148:151], v[204:207], 0
	v_mfma_f32_16x16x32_bf16 v[88:91], v[164:167], v[204:207], 0
	v_mfma_f32_16x16x32_bf16 v[76:79], v[148:151], v[212:215], 0
	v_mfma_f32_16x16x32_bf16 v[72:75], v[164:167], v[212:215], 0
	v_mfma_f32_16x16x32_bf16 v[124:127], v[160:163], v[192:195], v[124:127]
	v_mfma_f32_16x16x32_bf16 v[120:123], v[168:171], v[192:195], v[120:123]
	v_mfma_f32_16x16x32_bf16 v[108:111], v[160:163], v[200:203], v[108:111]
	v_mfma_f32_16x16x32_bf16 v[104:107], v[168:171], v[200:203], v[104:107]
	v_mfma_f32_16x16x32_bf16 v[92:95], v[160:163], v[208:211], v[92:95]
	v_mfma_f32_16x16x32_bf16 v[88:91], v[168:171], v[208:211], v[88:91]
	v_mfma_f32_16x16x32_bf16 v[76:79], v[160:163], v[216:219], v[76:79]
	v_mfma_f32_16x16x32_bf16 v[72:75], v[168:171], v[216:219], v[72:75]
	s_setprio 0
	s_setprio 1
	v_mfma_f32_16x16x32_bf16 v[116:119], v[172:175], v[188:191], 0
	v_mfma_f32_16x16x32_bf16 v[112:115], v[180:183], v[188:191], 0
	v_mfma_f32_16x16x32_bf16 v[100:103], v[172:175], v[196:199], 0
	v_mfma_f32_16x16x32_bf16 v[96:99], v[180:183], v[196:199], 0
	v_mfma_f32_16x16x32_bf16 v[84:87], v[172:175], v[204:207], 0
	v_mfma_f32_16x16x32_bf16 v[80:83], v[180:183], v[204:207], 0
	v_mfma_f32_16x16x32_bf16 v[68:71], v[172:175], v[212:215], 0
	v_mfma_f32_16x16x32_bf16 v[64:67], v[180:183], v[212:215], 0
	v_mfma_f32_16x16x32_bf16 v[116:119], v[176:179], v[192:195], v[116:119]
	v_mfma_f32_16x16x32_bf16 v[112:115], v[184:187], v[192:195], v[112:115]
	v_mfma_f32_16x16x32_bf16 v[100:103], v[176:179], v[200:203], v[100:103]
	v_mfma_f32_16x16x32_bf16 v[96:99], v[184:187], v[200:203], v[96:99]
	v_mfma_f32_16x16x32_bf16 v[84:87], v[176:179], v[208:211], v[84:87]
	v_mfma_f32_16x16x32_bf16 v[80:83], v[184:187], v[208:211], v[80:83]
	v_mfma_f32_16x16x32_bf16 v[68:71], v[176:179], v[216:219], v[68:71]
	v_mfma_f32_16x16x32_bf16 v[64:67], v[184:187], v[216:219], v[64:67]
	s_setprio 0
	s_barrier
	s_add_i32 s34, s82, s57
	v_lshl_add_u64 v[220:221], s[52:53], 0, v[134:135]
	s_mov_b32 m0, s34
	ds_read_b128 v[188:191], v157 offset:16384
	ds_read_b128 v[192:195], v157 offset:17408
	ds_read_b128 v[196:199], v157 offset:18432
	ds_read_b128 v[200:203], v157 offset:19456
	ds_read_b128 v[204:207], v157 offset:20480
	ds_read_b128 v[208:211], v157 offset:21504
	ds_read_b128 v[212:215], v157 offset:22528
	ds_read_b128 v[216:219], v157 offset:23552
	global_load_lds_dwordx4 v[220:221], off
	s_add_i32 m0, s34, 0x2000
	s_add_u32 s34, s52, 0x40000
	v_lshl_add_u64 v[222:223], s[52:53], 0, v[138:139]
	s_addc_u32 s35, s53, 0
	s_add_i32 s86, s83, s57
	global_load_lds_dwordx4 v[222:223], off
	v_lshl_add_u64 v[224:225], s[34:35], 0, v[134:135]
	s_mov_b32 m0, s86
	v_lshl_add_u64 v[226:227], s[54:55], 0, v[136:137]
	global_load_lds_dwordx4 v[224:225], off
	v_lshl_add_u64 v[224:225], s[34:35], 0, v[138:139]
	s_add_i32 m0, s86, 0x2000
	s_nop 0
	global_load_lds_dwordx4 v[224:225], off
	v_lshl_add_u64 v[224:225], s[54:55], 0, v[132:133]
	s_mov_b32 m0, s58
	s_nop 0
	global_load_lds_dwordx4 v[224:225], off
	s_mov_b32 m0, s59
	s_nop 0
	global_load_lds_dwordx4 v[226:227], off
	s_cmp_lg_u32 s84, 1
	s_cbranch_scc1 .Lmy_rl_4_1
	s_waitcnt vmcnt(8)
	s_branch .Lmy_rj_4_1

.Lmy_rj_4_1:
	s_waitcnt lgkmcnt(0)
	s_barrier
	s_setprio 1
	s_waitcnt lgkmcnt(0)
	v_mfma_f32_16x16x32_bf16 v[60:63], v[148:151], v[188:191], 0
	v_mfma_f32_16x16x32_bf16 v[56:59], v[164:167], v[188:191], 0
	v_mfma_f32_16x16x32_bf16 v[44:47], v[148:151], v[196:199], 0
	v_mfma_f32_16x16x32_bf16 v[40:43], v[164:167], v[196:199], 0
	v_mfma_f32_16x16x32_bf16 v[28:31], v[148:151], v[204:207], 0
	v_mfma_f32_16x16x32_bf16 v[24:27], v[164:167], v[204:207], 0
	v_mfma_f32_16x16x32_bf16 v[12:15], v[148:151], v[212:215], 0
	v_mfma_f32_16x16x32_bf16 v[8:11], v[164:167], v[212:215], 0
	v_mfma_f32_16x16x32_bf16 v[60:63], v[160:163], v[192:195], v[60:63]
	v_mfma_f32_16x16x32_bf16 v[56:59], v[168:171], v[192:195], v[56:59]
	v_mfma_f32_16x16x32_bf16 v[44:47], v[160:163], v[200:203], v[44:47]
	v_mfma_f32_16x16x32_bf16 v[40:43], v[168:171], v[200:203], v[40:43]
	v_mfma_f32_16x16x32_bf16 v[28:31], v[160:163], v[208:211], v[28:31]
	v_mfma_f32_16x16x32_bf16 v[24:27], v[168:171], v[208:211], v[24:27]
	v_mfma_f32_16x16x32_bf16 v[12:15], v[160:163], v[216:219], v[12:15]
	v_mfma_f32_16x16x32_bf16 v[8:11], v[168:171], v[216:219], v[8:11]
	s_setprio 0
	s_setprio 1
	v_mfma_f32_16x16x32_bf16 v[52:55], v[172:175], v[188:191], 0
	v_mfma_f32_16x16x32_bf16 v[48:51], v[180:183], v[188:191], 0
	v_mfma_f32_16x16x32_bf16 v[36:39], v[172:175], v[196:199], 0
	v_mfma_f32_16x16x32_bf16 v[32:35], v[180:183], v[196:199], 0
	v_mfma_f32_16x16x32_bf16 v[20:23], v[172:175], v[204:207], 0
	v_mfma_f32_16x16x32_bf16 v[16:19], v[180:183], v[204:207], 0
	v_mfma_f32_16x16x32_bf16 v[4:7], v[172:175], v[212:215], 0
	v_mfma_f32_16x16x32_bf16 v[0:3], v[180:183], v[212:215], 0
	v_mfma_f32_16x16x32_bf16 v[52:55], v[176:179], v[192:195], v[52:55]
	v_mfma_f32_16x16x32_bf16 v[48:51], v[184:187], v[192:195], v[48:51]
	v_mfma_f32_16x16x32_bf16 v[36:39], v[176:179], v[200:203], v[36:39]
	v_mfma_f32_16x16x32_bf16 v[32:35], v[184:187], v[200:203], v[32:35]
	v_mfma_f32_16x16x32_bf16 v[20:23], v[176:179], v[208:211], v[20:23]
	v_mfma_f32_16x16x32_bf16 v[16:19], v[184:187], v[208:211], v[16:19]
	v_mfma_f32_16x16x32_bf16 v[4:7], v[176:179], v[216:219], v[4:7]
	v_mfma_f32_16x16x32_bf16 v[0:3], v[184:187], v[216:219], v[0:3]
	s_setprio 0
	s_barrier
	s_add_i32 s86, 0, 0x18000
	v_add_u32_e32 v159, s86, v152
	s_add_i32 s87, 0, 0x1c000
	ds_read_b128 v[148:151], v159
	ds_read_b128 v[160:163], v159 offset:1024
	ds_read_b128 v[164:167], v159 offset:2048
	ds_read_b128 v[168:171], v159 offset:3072
	v_add_u32_e32 v159, s87, v152
	ds_read_b128 v[172:175], v159
	ds_read_b128 v[176:179], v159 offset:1024
	ds_read_b128 v[180:183], v159 offset:2048
	ds_read_b128 v[184:187], v159 offset:3072
	s_add_u32 s34, s54, 0x40000
	s_addc_u32 s35, s55, 0
	s_mov_b32 m0, s62
	v_lshl_add_u64 v[228:229], s[34:35], 0, v[132:133]
	ds_read_b128 v[188:191], v157 offset:32768
	ds_read_b128 v[192:195], v157 offset:33792
	ds_read_b128 v[196:199], v157 offset:34816
	ds_read_b128 v[200:203], v157 offset:35840
	ds_read_b128 v[204:207], v157 offset:36864
	ds_read_b128 v[208:211], v157 offset:37888
	ds_read_b128 v[212:215], v157 offset:38912
	ds_read_b128 v[216:219], v157 offset:39936
	global_load_lds_dwordx4 v[228:229], off
	v_lshl_add_u64 v[228:229], s[34:35], 0, v[136:137]
	s_mov_b32 m0, s63
	s_nop 0
	global_load_lds_dwordx4 v[228:229], off
	s_cmp_lg_u32 s84, 1
	s_cbranch_scc1 .Lmy_rl_4_2
	s_waitcnt vmcnt(8)
	s_branch .Lmy_rj_4_2

.Lmy_rj_4_2:
	s_waitcnt lgkmcnt(0)
	s_barrier
	s_setprio 1
	s_waitcnt lgkmcnt(0)
	v_mfma_f32_16x16x32_bf16 v[124:127], v[148:151], v[188:191], v[124:127]
	v_mfma_f32_16x16x32_bf16 v[120:123], v[164:167], v[188:191], v[120:123]
	v_mfma_f32_16x16x32_bf16 v[108:111], v[148:151], v[196:199], v[108:111]
	v_mfma_f32_16x16x32_bf16 v[104:107], v[164:167], v[196:199], v[104:107]
	v_mfma_f32_16x16x32_bf16 v[92:95], v[148:151], v[204:207], v[92:95]
	v_mfma_f32_16x16x32_bf16 v[88:91], v[164:167], v[204:207], v[88:91]
	v_mfma_f32_16x16x32_bf16 v[76:79], v[148:151], v[212:215], v[76:79]
	v_mfma_f32_16x16x32_bf16 v[72:75], v[164:167], v[212:215], v[72:75]
	v_mfma_f32_16x16x32_bf16 v[124:127], v[160:163], v[192:195], v[124:127]
	v_mfma_f32_16x16x32_bf16 v[120:123], v[168:171], v[192:195], v[120:123]
	v_mfma_f32_16x16x32_bf16 v[108:111], v[160:163], v[200:203], v[108:111]
	v_mfma_f32_16x16x32_bf16 v[104:107], v[168:171], v[200:203], v[104:107]
	v_mfma_f32_16x16x32_bf16 v[92:95], v[160:163], v[208:211], v[92:95]
	v_mfma_f32_16x16x32_bf16 v[88:91], v[168:171], v[208:211], v[88:91]
	v_mfma_f32_16x16x32_bf16 v[76:79], v[160:163], v[216:219], v[76:79]
	v_mfma_f32_16x16x32_bf16 v[72:75], v[168:171], v[216:219], v[72:75]
	s_setprio 0
	s_setprio 1
	v_mfma_f32_16x16x32_bf16 v[116:119], v[172:175], v[188:191], v[116:119]
	v_mfma_f32_16x16x32_bf16 v[112:115], v[180:183], v[188:191], v[112:115]
	v_mfma_f32_16x16x32_bf16 v[100:103], v[172:175], v[196:199], v[100:103]
	v_mfma_f32_16x16x32_bf16 v[96:99], v[180:183], v[196:199], v[96:99]
	v_mfma_f32_16x16x32_bf16 v[84:87], v[172:175], v[204:207], v[84:87]
	v_mfma_f32_16x16x32_bf16 v[80:83], v[180:183], v[204:207], v[80:83]
	v_mfma_f32_16x16x32_bf16 v[68:71], v[172:175], v[212:215], v[68:71]
	v_mfma_f32_16x16x32_bf16 v[64:67], v[180:183], v[212:215], v[64:67]
	v_mfma_f32_16x16x32_bf16 v[116:119], v[176:179], v[192:195], v[116:119]
	v_mfma_f32_16x16x32_bf16 v[112:115], v[184:187], v[192:195], v[112:115]
	v_mfma_f32_16x16x32_bf16 v[100:103], v[176:179], v[200:203], v[100:103]
	v_mfma_f32_16x16x32_bf16 v[96:99], v[184:187], v[200:203], v[96:99]
	v_mfma_f32_16x16x32_bf16 v[84:87], v[176:179], v[208:211], v[84:87]
	v_mfma_f32_16x16x32_bf16 v[80:83], v[184:187], v[208:211], v[80:83]
	v_mfma_f32_16x16x32_bf16 v[68:71], v[176:179], v[216:219], v[68:71]
	v_mfma_f32_16x16x32_bf16 v[64:67], v[184:187], v[216:219], v[64:67]
	s_setprio 0
	s_barrier
	s_add_i32 s34, s86, s57
	v_lshl_add_u64 v[220:221], v[220:221], 0, s[10:11]
	s_mov_b32 m0, s34
	ds_read_b128 v[188:191], v157 offset:49152
	ds_read_b128 v[192:195], v157 offset:50176
	ds_read_b128 v[196:199], v157 offset:51200
	ds_read_b128 v[200:203], v157 offset:52224
	ds_read_b128 v[204:207], v157 offset:53248
	ds_read_b128 v[208:211], v157 offset:54272
	ds_read_b128 v[212:215], v157 offset:55296
	ds_read_b128 v[216:219], v157 offset:56320
	global_load_lds_dwordx4 v[220:221], off
	s_add_i32 m0, s34, 0x2000
	s_add_u32 s34, s52, 0x40080
	v_lshl_add_u64 v[220:221], v[222:223], 0, s[10:11]
	s_addc_u32 s35, s53, 0
	s_add_i32 s52, s87, s57
	global_load_lds_dwordx4 v[220:221], off
	v_lshl_add_u64 v[220:221], s[34:35], 0, v[134:135]
	s_mov_b32 m0, s52
	s_nop 0
	global_load_lds_dwordx4 v[220:221], off
	v_lshl_add_u64 v[220:221], s[34:35], 0, v[138:139]
	s_add_i32 m0, s52, 0x2000
	s_nop 0
	global_load_lds_dwordx4 v[220:221], off
	v_lshl_add_u64 v[220:221], v[224:225], 0, s[10:11]
	s_mov_b32 m0, s65
	s_nop 0
	global_load_lds_dwordx4 v[220:221], off
	v_lshl_add_u64 v[220:221], v[226:227], 0, s[10:11]
	s_mov_b32 m0, s66
	s_nop 0
	global_load_lds_dwordx4 v[220:221], off
	s_waitcnt vmcnt(8)
	s_waitcnt lgkmcnt(0)
	s_barrier
	s_setprio 1
	s_waitcnt lgkmcnt(0)
	v_mfma_f32_16x16x32_bf16 v[60:63], v[148:151], v[188:191], v[60:63]
	v_mfma_f32_16x16x32_bf16 v[56:59], v[164:167], v[188:191], v[56:59]
	v_mfma_f32_16x16x32_bf16 v[44:47], v[148:151], v[196:199], v[44:47]
	v_mfma_f32_16x16x32_bf16 v[40:43], v[164:167], v[196:199], v[40:43]
	v_mfma_f32_16x16x32_bf16 v[28:31], v[148:151], v[204:207], v[28:31]
	v_mfma_f32_16x16x32_bf16 v[24:27], v[164:167], v[204:207], v[24:27]
	v_mfma_f32_16x16x32_bf16 v[12:15], v[148:151], v[212:215], v[12:15]
	v_mfma_f32_16x16x32_bf16 v[8:11], v[164:167], v[212:215], v[8:11]
	v_mfma_f32_16x16x32_bf16 v[60:63], v[160:163], v[192:195], v[60:63]
	v_mfma_f32_16x16x32_bf16 v[56:59], v[168:171], v[192:195], v[56:59]
	v_mfma_f32_16x16x32_bf16 v[44:47], v[160:163], v[200:203], v[44:47]
	v_mfma_f32_16x16x32_bf16 v[40:43], v[168:171], v[200:203], v[40:43]
	v_mfma_f32_16x16x32_bf16 v[28:31], v[160:163], v[208:211], v[28:31]
	v_mfma_f32_16x16x32_bf16 v[24:27], v[168:171], v[208:211], v[24:27]
	v_mfma_f32_16x16x32_bf16 v[12:15], v[160:163], v[216:219], v[12:15]
	v_mfma_f32_16x16x32_bf16 v[8:11], v[168:171], v[216:219], v[8:11]
	s_setprio 0
	s_setprio 1
	v_mfma_f32_16x16x32_bf16 v[52:55], v[172:175], v[188:191], v[52:55]
	v_mfma_f32_16x16x32_bf16 v[48:51], v[180:183], v[188:191], v[48:51]
	v_mfma_f32_16x16x32_bf16 v[36:39], v[172:175], v[196:199], v[36:39]
	v_mfma_f32_16x16x32_bf16 v[32:35], v[180:183], v[196:199], v[32:35]
	v_mfma_f32_16x16x32_bf16 v[20:23], v[172:175], v[204:207], v[20:23]
	v_mfma_f32_16x16x32_bf16 v[16:19], v[180:183], v[204:207], v[16:19]
	v_mfma_f32_16x16x32_bf16 v[4:7], v[172:175], v[212:215], v[4:7]
	v_mfma_f32_16x16x32_bf16 v[0:3], v[180:183], v[212:215], v[0:3]
	v_mfma_f32_16x16x32_bf16 v[52:55], v[176:179], v[192:195], v[52:55]
	v_mfma_f32_16x16x32_bf16 v[48:51], v[184:187], v[192:195], v[48:51]
	v_mfma_f32_16x16x32_bf16 v[36:39], v[176:179], v[200:203], v[36:39]
	v_mfma_f32_16x16x32_bf16 v[32:35], v[184:187], v[200:203], v[32:35]
	v_mfma_f32_16x16x32_bf16 v[20:23], v[176:179], v[208:211], v[20:23]
	v_mfma_f32_16x16x32_bf16 v[16:19], v[184:187], v[208:211], v[16:19]
	v_mfma_f32_16x16x32_bf16 v[4:7], v[176:179], v[216:219], v[4:7]
	v_mfma_f32_16x16x32_bf16 v[0:3], v[184:187], v[216:219], v[0:3]
	s_setprio 0
	s_barrier
	s_add_i32 s85, s85, 2
	s_add_u32 s50, s50, 0x100
	s_addc_u32 s51, s51, 0
	s_add_u32 s49, s49, 0x100
	s_addc_u32 s77, s77, 0

.Lmy_nobar_4:
	s_add_i32 s85, s85, 2
	s_add_u32 s50, s50, 0x100
	s_addc_u32 s51, s51, 0
	s_add_u32 s49, s49, 0x100
	s_addc_u32 s77, s77, 0
	s_cmp_gt_u32 s85, 13
	s_cbranch_scc0 .LBB0_386
	s_add_u32 s100, s13, 0x40080
	s_addc_u32 s101, s12, 0
	s_add_i32 m0, s58, 0xc000
	v_lshl_add_u64 v[220:221], s[100:101], 0, v[140:141]
	global_load_lds_dwordx4 v[220:221], off
	s_add_i32 m0, s58, 0xe000
	v_lshl_add_u64 v[220:221], s[100:101], 0, v[142:143]
	global_load_lds_dwordx4 v[220:221], off
	s_and_b64 vcc, exec, s[22:23]
	s_cbranch_vccz .LBB0_389
	s_nop 0

.Lmy_nobar2_5:
	ds_read_b128 v[148:151], v155
	ds_read_b128 v[160:163], v155 offset:1024
	ds_read_b128 v[164:167], v155 offset:2048
	ds_read_b128 v[168:171], v155 offset:3072
	ds_read_b128 v[172:175], v157
	ds_read_b128 v[176:179], v157 offset:1024
	ds_read_b128 v[180:183], v157 offset:2048
	ds_read_b128 v[184:187], v157 offset:3072
	s_add_u32 s34, s42, 0xfffc0080
	s_addc_u32 s35, s43, -1
	s_cmp_eq_u32 s85, 12
	s_cselect_b32 s51, s23, s35
	s_cselect_b32 s50, s81, s34
	s_cselect_b32 s49, s11, s84
	s_cselect_b32 s48, s82, s83
	v_lshl_add_u64 v[220:221], s[42:43], 0, v[140:141]
	s_add_i32 m0, s41, 0xc000
	ds_read_b128 v[188:191], v158
	ds_read_b128 v[192:195], v158 offset:1024
	ds_read_b128 v[196:199], v158 offset:2048
	ds_read_b128 v[200:203], v158 offset:3072
	ds_read_b128 v[204:207], v158 offset:4096
	ds_read_b128 v[208:211], v158 offset:5120
	ds_read_b128 v[212:215], v158 offset:6144
	ds_read_b128 v[216:219], v158 offset:7168
	s_cmp_lg_u32 s77, 1
	s_cbranch_scc1 .Lmy_sk_5_0
	global_load_lds_dwordx4 v[220:221], off
.Lmy_sk_5_0:
	v_lshl_add_u64 v[220:221], s[42:43], 0, v[142:143]
	s_add_i32 m0, s41, 0xe000
	s_nop 0
	s_cmp_lg_u32 s77, 1
	s_cbranch_scc1 .Lmy_sk_5_1
	global_load_lds_dwordx4 v[220:221], off
.Lmy_sk_5_1:
	s_cmp_lg_u32 s77, 1
	s_cbranch_scc1 .Lmy_rl_5_0
	s_waitcnt vmcnt(8)
	s_branch .Lmy_rj_5_0

.Lmy_rj_5_0:
	s_waitcnt lgkmcnt(0)
	s_barrier
	s_setprio 1
	s_waitcnt lgkmcnt(0)
	v_mfma_f32_16x16x32_bf16 v[124:127], v[148:151], v[188:191], 0
	v_mfma_f32_16x16x32_bf16 v[120:123], v[164:167], v[188:191], 0
	v_mfma_f32_16x16x32_bf16 v[108:111], v[148:151], v[196:199], 0
	v_mfma_f32_16x16x32_bf16 v[104:107], v[164:167], v[196:199], 0
	v_mfma_f32_16x16x32_bf16 v[92:95], v[148:151], v[204:207], 0
	v_mfma_f32_16x16x32_bf16 v[88:91], v[164:167], v[204:207], 0
	v_mfma_f32_16x16x32_bf16 v[76:79], v[148:151], v[212:215], 0
	v_mfma_f32_16x16x32_bf16 v[72:75], v[164:167], v[212:215], 0
	v_mfma_f32_16x16x32_bf16 v[124:127], v[160:163], v[192:195], v[124:127]
	v_mfma_f32_16x16x32_bf16 v[120:123], v[168:171], v[192:195], v[120:123]
	v_mfma_f32_16x16x32_bf16 v[108:111], v[160:163], v[200:203], v[108:111]
	v_mfma_f32_16x16x32_bf16 v[104:107], v[168:171], v[200:203], v[104:107]
	v_mfma_f32_16x16x32_bf16 v[92:95], v[160:163], v[208:211], v[92:95]
	v_mfma_f32_16x16x32_bf16 v[88:91], v[168:171], v[208:211], v[88:91]
	v_mfma_f32_16x16x32_bf16 v[76:79], v[160:163], v[216:219], v[76:79]
	v_mfma_f32_16x16x32_bf16 v[72:75], v[168:171], v[216:219], v[72:75]
	s_setprio 0
	s_setprio 1
	v_mfma_f32_16x16x32_bf16 v[116:119], v[172:175], v[188:191], 0
	v_mfma_f32_16x16x32_bf16 v[112:115], v[180:183], v[188:191], 0
	v_mfma_f32_16x16x32_bf16 v[100:103], v[172:175], v[196:199], 0
	v_mfma_f32_16x16x32_bf16 v[96:99], v[180:183], v[196:199], 0
	v_mfma_f32_16x16x32_bf16 v[84:87], v[172:175], v[204:207], 0
	v_mfma_f32_16x16x32_bf16 v[80:83], v[180:183], v[204:207], 0
	v_mfma_f32_16x16x32_bf16 v[68:71], v[172:175], v[212:215], 0
	v_mfma_f32_16x16x32_bf16 v[64:67], v[180:183], v[212:215], 0
	v_mfma_f32_16x16x32_bf16 v[116:119], v[176:179], v[192:195], v[116:119]
	v_mfma_f32_16x16x32_bf16 v[112:115], v[184:187], v[192:195], v[112:115]
	v_mfma_f32_16x16x32_bf16 v[100:103], v[176:179], v[200:203], v[100:103]
	v_mfma_f32_16x16x32_bf16 v[96:99], v[184:187], v[200:203], v[96:99]
	v_mfma_f32_16x16x32_bf16 v[84:87], v[176:179], v[208:211], v[84:87]
	v_mfma_f32_16x16x32_bf16 v[80:83], v[184:187], v[208:211], v[80:83]
	v_mfma_f32_16x16x32_bf16 v[68:71], v[176:179], v[216:219], v[68:71]
	v_mfma_f32_16x16x32_bf16 v[64:67], v[184:187], v[216:219], v[64:67]
	s_setprio 0
	s_barrier
	s_add_i32 s34, s65, s54
	v_lshl_add_u64 v[220:221], s[48:49], 0, v[136:137]
	s_mov_b32 m0, s34
	ds_read_b128 v[188:191], v158 offset:16384
	ds_read_b128 v[192:195], v158 offset:17408
	ds_read_b128 v[196:199], v158 offset:18432
	ds_read_b128 v[200:203], v158 offset:19456
	ds_read_b128 v[204:207], v158 offset:20480
	ds_read_b128 v[208:211], v158 offset:21504
	ds_read_b128 v[212:215], v158 offset:22528
	ds_read_b128 v[216:219], v158 offset:23552
	global_load_lds_dwordx4 v[220:221], off
	s_add_i32 m0, s34, 0x2000
	s_add_u32 s34, s48, 0x40000
	v_lshl_add_u64 v[222:223], s[48:49], 0, v[132:133]
	s_addc_u32 s35, s49, 0
	s_add_i32 s86, s66, s54
	global_load_lds_dwordx4 v[222:223], off
	v_lshl_add_u64 v[224:225], s[34:35], 0, v[136:137]
	s_mov_b32 m0, s86
	v_lshl_add_u64 v[226:227], s[50:51], 0, v[134:135]
	global_load_lds_dwordx4 v[224:225], off
	v_lshl_add_u64 v[224:225], s[34:35], 0, v[132:133]
	s_add_i32 m0, s86, 0x2000
	s_nop 0
	global_load_lds_dwordx4 v[224:225], off
	v_lshl_add_u64 v[224:225], s[50:51], 0, v[138:139]
	s_mov_b32 m0, s41
	s_nop 0
	global_load_lds_dwordx4 v[224:225], off
	s_mov_b32 m0, s58
	s_nop 0
	global_load_lds_dwordx4 v[226:227], off
	s_cmp_lg_u32 s77, 1
	s_cbranch_scc1 .Lmy_rl_5_1
	s_waitcnt vmcnt(8)
	s_branch .Lmy_rj_5_1

.Lmy_rj_5_1:
	s_waitcnt lgkmcnt(0)
	s_barrier
	s_setprio 1
	s_waitcnt lgkmcnt(0)
	v_mfma_f32_16x16x32_bf16 v[60:63], v[148:151], v[188:191], 0
	v_mfma_f32_16x16x32_bf16 v[56:59], v[164:167], v[188:191], 0
	v_mfma_f32_16x16x32_bf16 v[44:47], v[148:151], v[196:199], 0
	v_mfma_f32_16x16x32_bf16 v[40:43], v[164:167], v[196:199], 0
	v_mfma_f32_16x16x32_bf16 v[28:31], v[148:151], v[204:207], 0
	v_mfma_f32_16x16x32_bf16 v[24:27], v[164:167], v[204:207], 0
	v_mfma_f32_16x16x32_bf16 v[12:15], v[148:151], v[212:215], 0
	v_mfma_f32_16x16x32_bf16 v[8:11], v[164:167], v[212:215], 0
	v_mfma_f32_16x16x32_bf16 v[60:63], v[160:163], v[192:195], v[60:63]
	v_mfma_f32_16x16x32_bf16 v[56:59], v[168:171], v[192:195], v[56:59]
	v_mfma_f32_16x16x32_bf16 v[44:47], v[160:163], v[200:203], v[44:47]
	v_mfma_f32_16x16x32_bf16 v[40:43], v[168:171], v[200:203], v[40:43]
	v_mfma_f32_16x16x32_bf16 v[28:31], v[160:163], v[208:211], v[28:31]
	v_mfma_f32_16x16x32_bf16 v[24:27], v[168:171], v[208:211], v[24:27]
	v_mfma_f32_16x16x32_bf16 v[12:15], v[160:163], v[216:219], v[12:15]
	v_mfma_f32_16x16x32_bf16 v[8:11], v[168:171], v[216:219], v[8:11]
	s_setprio 0
	s_setprio 1
	v_mfma_f32_16x16x32_bf16 v[52:55], v[172:175], v[188:191], 0
	v_mfma_f32_16x16x32_bf16 v[48:51], v[180:183], v[188:191], 0
	v_mfma_f32_16x16x32_bf16 v[36:39], v[172:175], v[196:199], 0
	v_mfma_f32_16x16x32_bf16 v[32:35], v[180:183], v[196:199], 0
	v_mfma_f32_16x16x32_bf16 v[20:23], v[172:175], v[204:207], 0
	v_mfma_f32_16x16x32_bf16 v[16:19], v[180:183], v[204:207], 0
	v_mfma_f32_16x16x32_bf16 v[4:7], v[172:175], v[212:215], 0
	v_mfma_f32_16x16x32_bf16 v[0:3], v[180:183], v[212:215], 0
	v_mfma_f32_16x16x32_bf16 v[52:55], v[176:179], v[192:195], v[52:55]
	v_mfma_f32_16x16x32_bf16 v[48:51], v[184:187], v[192:195], v[48:51]
	v_mfma_f32_16x16x32_bf16 v[36:39], v[176:179], v[200:203], v[36:39]
	v_mfma_f32_16x16x32_bf16 v[32:35], v[184:187], v[200:203], v[32:35]
	v_mfma_f32_16x16x32_bf16 v[20:23], v[176:179], v[208:211], v[20:23]
	v_mfma_f32_16x16x32_bf16 v[16:19], v[184:187], v[208:211], v[16:19]
	v_mfma_f32_16x16x32_bf16 v[4:7], v[176:179], v[216:219], v[4:7]
	v_mfma_f32_16x16x32_bf16 v[0:3], v[184:187], v[216:219], v[0:3]
	s_setprio 0
	s_barrier
	s_add_i32 s86, 0, 0x18000
	v_add_u32_e32 v159, s86, v152
	s_add_i32 s87, 0, 0x1c000
	ds_read_b128 v[148:151], v159
	ds_read_b128 v[160:163], v159 offset:1024
	ds_read_b128 v[164:167], v159 offset:2048
	ds_read_b128 v[168:171], v159 offset:3072
	v_add_u32_e32 v159, s87, v152
	ds_read_b128 v[172:175], v159
	ds_read_b128 v[176:179], v159 offset:1024
	ds_read_b128 v[180:183], v159 offset:2048
	ds_read_b128 v[184:187], v159 offset:3072
	s_add_u32 s34, s50, 0x40000
	s_addc_u32 s35, s51, 0
	s_mov_b32 m0, s59
	v_lshl_add_u64 v[228:229], s[34:35], 0, v[138:139]
	ds_read_b128 v[188:191], v158 offset:32768
	ds_read_b128 v[192:195], v158 offset:33792
	ds_read_b128 v[196:199], v158 offset:34816
	ds_read_b128 v[200:203], v158 offset:35840
	ds_read_b128 v[204:207], v158 offset:36864
	ds_read_b128 v[208:211], v158 offset:37888
	ds_read_b128 v[212:215], v158 offset:38912
	ds_read_b128 v[216:219], v158 offset:39936
	global_load_lds_dwordx4 v[228:229], off
	v_lshl_add_u64 v[228:229], s[34:35], 0, v[134:135]
	s_mov_b32 m0, s62
	s_nop 0
	global_load_lds_dwordx4 v[228:229], off
	s_cmp_lg_u32 s77, 1
	s_cbranch_scc1 .Lmy_rl_5_2
	s_waitcnt vmcnt(8)
	s_branch .Lmy_rj_5_2

.Lmy_rj_5_2:
	s_waitcnt lgkmcnt(0)
	s_barrier
	s_setprio 1
	s_waitcnt lgkmcnt(0)
	v_mfma_f32_16x16x32_bf16 v[124:127], v[148:151], v[188:191], v[124:127]
	v_mfma_f32_16x16x32_bf16 v[120:123], v[164:167], v[188:191], v[120:123]
	v_mfma_f32_16x16x32_bf16 v[108:111], v[148:151], v[196:199], v[108:111]
	v_mfma_f32_16x16x32_bf16 v[104:107], v[164:167], v[196:199], v[104:107]
	v_mfma_f32_16x16x32_bf16 v[92:95], v[148:151], v[204:207], v[92:95]
	v_mfma_f32_16x16x32_bf16 v[88:91], v[164:167], v[204:207], v[88:91]
	v_mfma_f32_16x16x32_bf16 v[76:79], v[148:151], v[212:215], v[76:79]
	v_mfma_f32_16x16x32_bf16 v[72:75], v[164:167], v[212:215], v[72:75]
	v_mfma_f32_16x16x32_bf16 v[124:127], v[160:163], v[192:195], v[124:127]
	v_mfma_f32_16x16x32_bf16 v[120:123], v[168:171], v[192:195], v[120:123]
	v_mfma_f32_16x16x32_bf16 v[108:111], v[160:163], v[200:203], v[108:111]
	v_mfma_f32_16x16x32_bf16 v[104:107], v[168:171], v[200:203], v[104:107]
	v_mfma_f32_16x16x32_bf16 v[92:95], v[160:163], v[208:211], v[92:95]
	v_mfma_f32_16x16x32_bf16 v[88:91], v[168:171], v[208:211], v[88:91]
	v_mfma_f32_16x16x32_bf16 v[76:79], v[160:163], v[216:219], v[76:79]
	v_mfma_f32_16x16x32_bf16 v[72:75], v[168:171], v[216:219], v[72:75]
	s_setprio 0
	s_setprio 1
	v_mfma_f32_16x16x32_bf16 v[116:119], v[172:175], v[188:191], v[116:119]
	v_mfma_f32_16x16x32_bf16 v[112:115], v[180:183], v[188:191], v[112:115]
	v_mfma_f32_16x16x32_bf16 v[100:103], v[172:175], v[196:199], v[100:103]
	v_mfma_f32_16x16x32_bf16 v[96:99], v[180:183], v[196:199], v[96:99]
	v_mfma_f32_16x16x32_bf16 v[84:87], v[172:175], v[204:207], v[84:87]
	v_mfma_f32_16x16x32_bf16 v[80:83], v[180:183], v[204:207], v[80:83]
	v_mfma_f32_16x16x32_bf16 v[68:71], v[172:175], v[212:215], v[68:71]
	v_mfma_f32_16x16x32_bf16 v[64:67], v[180:183], v[212:215], v[64:67]
	v_mfma_f32_16x16x32_bf16 v[116:119], v[176:179], v[192:195], v[116:119]
	v_mfma_f32_16x16x32_bf16 v[112:115], v[184:187], v[192:195], v[112:115]
	v_mfma_f32_16x16x32_bf16 v[100:103], v[176:179], v[200:203], v[100:103]
	v_mfma_f32_16x16x32_bf16 v[96:99], v[184:187], v[200:203], v[96:99]
	v_mfma_f32_16x16x32_bf16 v[84:87], v[176:179], v[208:211], v[84:87]
	v_mfma_f32_16x16x32_bf16 v[80:83], v[184:187], v[208:211], v[80:83]
	v_mfma_f32_16x16x32_bf16 v[68:71], v[176:179], v[216:219], v[68:71]
	v_mfma_f32_16x16x32_bf16 v[64:67], v[184:187], v[216:219], v[64:67]
	s_setprio 0
	s_barrier
	s_add_i32 s34, s86, s54
	v_lshl_add_u64 v[220:221], v[220:221], 0, s[6:7]
	s_mov_b32 m0, s34
	ds_read_b128 v[188:191], v158 offset:49152
	ds_read_b128 v[192:195], v158 offset:50176
	ds_read_b128 v[196:199], v158 offset:51200
	ds_read_b128 v[200:203], v158 offset:52224
	ds_read_b128 v[204:207], v158 offset:53248
	ds_read_b128 v[208:211], v158 offset:54272
	ds_read_b128 v[212:215], v158 offset:55296
	ds_read_b128 v[216:219], v158 offset:56320
	global_load_lds_dwordx4 v[220:221], off
	s_add_i32 m0, s34, 0x2000
	s_add_u32 s34, s48, 0x40080
	v_lshl_add_u64 v[220:221], v[222:223], 0, s[6:7]
	s_addc_u32 s35, s49, 0
	s_add_i32 s48, s87, s54
	global_load_lds_dwordx4 v[220:221], off
	v_lshl_add_u64 v[220:221], s[34:35], 0, v[136:137]
	s_mov_b32 m0, s48
	s_nop 0
	global_load_lds_dwordx4 v[220:221], off
	v_lshl_add_u64 v[220:221], s[34:35], 0, v[132:133]
	s_add_i32 m0, s48, 0x2000
	s_nop 0
	global_load_lds_dwordx4 v[220:221], off
	v_lshl_add_u64 v[220:221], v[224:225], 0, s[6:7]
	s_mov_b32 m0, s63
	s_nop 0
	global_load_lds_dwordx4 v[220:221], off
	v_lshl_add_u64 v[220:221], v[226:227], 0, s[6:7]
	s_mov_b32 m0, s64
	s_nop 0
	global_load_lds_dwordx4 v[220:221], off
	s_waitcnt vmcnt(8)
	s_waitcnt lgkmcnt(0)
	s_barrier
	s_setprio 1
	s_waitcnt lgkmcnt(0)
	v_mfma_f32_16x16x32_bf16 v[60:63], v[148:151], v[188:191], v[60:63]
	v_mfma_f32_16x16x32_bf16 v[56:59], v[164:167], v[188:191], v[56:59]
	v_mfma_f32_16x16x32_bf16 v[44:47], v[148:151], v[196:199], v[44:47]
	v_mfma_f32_16x16x32_bf16 v[40:43], v[164:167], v[196:199], v[40:43]
	v_mfma_f32_16x16x32_bf16 v[28:31], v[148:151], v[204:207], v[28:31]
	v_mfma_f32_16x16x32_bf16 v[24:27], v[164:167], v[204:207], v[24:27]
	v_mfma_f32_16x16x32_bf16 v[12:15], v[148:151], v[212:215], v[12:15]
	v_mfma_f32_16x16x32_bf16 v[8:11], v[164:167], v[212:215], v[8:11]
	v_mfma_f32_16x16x32_bf16 v[60:63], v[160:163], v[192:195], v[60:63]
	v_mfma_f32_16x16x32_bf16 v[56:59], v[168:171], v[192:195], v[56:59]
	v_mfma_f32_16x16x32_bf16 v[44:47], v[160:163], v[200:203], v[44:47]
	v_mfma_f32_16x16x32_bf16 v[40:43], v[168:171], v[200:203], v[40:43]
	v_mfma_f32_16x16x32_bf16 v[28:31], v[160:163], v[208:211], v[28:31]
	v_mfma_f32_16x16x32_bf16 v[24:27], v[168:171], v[208:211], v[24:27]
	v_mfma_f32_16x16x32_bf16 v[12:15], v[160:163], v[216:219], v[12:15]
	v_mfma_f32_16x16x32_bf16 v[8:11], v[168:171], v[216:219], v[8:11]
	s_setprio 0
	s_setprio 1
	v_mfma_f32_16x16x32_bf16 v[52:55], v[172:175], v[188:191], v[52:55]
	v_mfma_f32_16x16x32_bf16 v[48:51], v[180:183], v[188:191], v[48:51]
	v_mfma_f32_16x16x32_bf16 v[36:39], v[172:175], v[196:199], v[36:39]
	v_mfma_f32_16x16x32_bf16 v[32:35], v[180:183], v[196:199], v[32:35]
	v_mfma_f32_16x16x32_bf16 v[20:23], v[172:175], v[204:207], v[20:23]
	v_mfma_f32_16x16x32_bf16 v[16:19], v[180:183], v[204:207], v[16:19]
	v_mfma_f32_16x16x32_bf16 v[4:7], v[172:175], v[212:215], v[4:7]
	v_mfma_f32_16x16x32_bf16 v[0:3], v[180:183], v[212:215], v[0:3]
	v_mfma_f32_16x16x32_bf16 v[52:55], v[176:179], v[192:195], v[52:55]
	v_mfma_f32_16x16x32_bf16 v[48:51], v[184:187], v[192:195], v[48:51]
	v_mfma_f32_16x16x32_bf16 v[36:39], v[176:179], v[200:203], v[36:39]
	v_mfma_f32_16x16x32_bf16 v[32:35], v[184:187], v[200:203], v[32:35]
	v_mfma_f32_16x16x32_bf16 v[20:23], v[176:179], v[208:211], v[20:23]
	v_mfma_f32_16x16x32_bf16 v[16:19], v[184:187], v[208:211], v[16:19]
	v_mfma_f32_16x16x32_bf16 v[4:7], v[176:179], v[216:219], v[4:7]
	v_mfma_f32_16x16x32_bf16 v[0:3], v[184:187], v[216:219], v[0:3]
	s_setprio 0
	s_barrier
	s_add_i32 s85, s85, 2
	s_add_u32 s42, s42, 0x100
	s_addc_u32 s43, s43, 0
	s_add_u32 s83, s83, 0x100
	s_addc_u32 s84, s84, 0

.Lmy_nobar_5:
	s_add_i32 s85, s85, 2
	s_add_u32 s42, s42, 0x100
	s_addc_u32 s43, s43, 0
	s_add_u32 s83, s83, 0x100
	s_addc_u32 s84, s84, 0
	s_cmp_gt_u32 s85, 13
	s_cbranch_scc0 .LBB0_476
	s_add_u32 s100, s81, 0x40080
	s_addc_u32 s101, s23, 0
	s_add_i32 m0, s41, 0xc000
	v_lshl_add_u64 v[220:221], s[100:101], 0, v[140:141]
	global_load_lds_dwordx4 v[220:221], off
	s_add_i32 m0, s41, 0xe000
	v_lshl_add_u64 v[220:221], s[100:101], 0, v[142:143]
	global_load_lds_dwordx4 v[220:221], off
	s_and_b64 vcc, exec, s[8:9]
	s_cbranch_vccz .LBB0_479
	s_nop 0

.Lmy_nobar2_6:
	ds_read_b128 v[148:151], v154
	ds_read_b128 v[160:163], v154 offset:1024
	ds_read_b128 v[164:167], v154 offset:2048
	ds_read_b128 v[168:171], v154 offset:3072
	ds_read_b128 v[172:175], v155
	ds_read_b128 v[176:179], v155 offset:1024
	ds_read_b128 v[180:183], v155 offset:2048
	ds_read_b128 v[184:187], v155 offset:3072
	s_add_u32 s34, s40, 0xfff50080
	s_addc_u32 s35, s41, -1
	s_cmp_eq_u32 s81, 40
	s_cselect_b32 s49, s1, s35
	s_cselect_b32 s48, s0, s34
	s_cselect_b32 s43, s29, s77
	s_cselect_b32 s42, s28, s13
	v_lshl_add_u64 v[220:221], s[40:41], 0, v[140:141]
	s_add_i32 m0, s52, 0xc000
	ds_read_b128 v[188:191], v157
	ds_read_b128 v[192:195], v157 offset:1024
	ds_read_b128 v[196:199], v157 offset:2048
	ds_read_b128 v[200:203], v157 offset:3072
	ds_read_b128 v[204:207], v157 offset:4096
	ds_read_b128 v[208:211], v157 offset:5120
	ds_read_b128 v[212:215], v157 offset:6144
	ds_read_b128 v[216:219], v157 offset:7168
	s_cmp_lg_u32 s66, 1
	s_cbranch_scc1 .Lmy_sk_6_0
	global_load_lds_dwordx4 v[220:221], off
.Lmy_sk_6_0:
	v_lshl_add_u64 v[220:221], s[40:41], 0, v[142:143]
	s_add_i32 m0, s52, 0xe000
	s_nop 0
	s_cmp_lg_u32 s66, 1
	s_cbranch_scc1 .Lmy_sk_6_1
	global_load_lds_dwordx4 v[220:221], off
.Lmy_sk_6_1:
	s_cmp_lg_u32 s66, 1
	s_cbranch_scc1 .Lmy_rl_6_0
	s_waitcnt vmcnt(8)
	s_branch .Lmy_rj_6_0

.Lmy_rj_6_0:
	s_waitcnt lgkmcnt(0)
	s_barrier
	s_setprio 1
	s_waitcnt lgkmcnt(0)
	v_mfma_f32_16x16x32_bf16 v[124:127], v[148:151], v[188:191], 0
	v_mfma_f32_16x16x32_bf16 v[120:123], v[164:167], v[188:191], 0
	v_mfma_f32_16x16x32_bf16 v[108:111], v[148:151], v[196:199], 0
	v_mfma_f32_16x16x32_bf16 v[104:107], v[164:167], v[196:199], 0
	v_mfma_f32_16x16x32_bf16 v[92:95], v[148:151], v[204:207], 0
	v_mfma_f32_16x16x32_bf16 v[88:91], v[164:167], v[204:207], 0
	v_mfma_f32_16x16x32_bf16 v[76:79], v[148:151], v[212:215], 0
	v_mfma_f32_16x16x32_bf16 v[72:75], v[164:167], v[212:215], 0
	v_mfma_f32_16x16x32_bf16 v[124:127], v[160:163], v[192:195], v[124:127]
	v_mfma_f32_16x16x32_bf16 v[120:123], v[168:171], v[192:195], v[120:123]
	v_mfma_f32_16x16x32_bf16 v[108:111], v[160:163], v[200:203], v[108:111]
	v_mfma_f32_16x16x32_bf16 v[104:107], v[168:171], v[200:203], v[104:107]
	v_mfma_f32_16x16x32_bf16 v[92:95], v[160:163], v[208:211], v[92:95]
	v_mfma_f32_16x16x32_bf16 v[88:91], v[168:171], v[208:211], v[88:91]
	v_mfma_f32_16x16x32_bf16 v[76:79], v[160:163], v[216:219], v[76:79]
	v_mfma_f32_16x16x32_bf16 v[72:75], v[168:171], v[216:219], v[72:75]
	s_setprio 0
	s_setprio 1
	v_mfma_f32_16x16x32_bf16 v[116:119], v[172:175], v[188:191], 0
	v_mfma_f32_16x16x32_bf16 v[112:115], v[180:183], v[188:191], 0
	v_mfma_f32_16x16x32_bf16 v[100:103], v[172:175], v[196:199], 0
	v_mfma_f32_16x16x32_bf16 v[96:99], v[180:183], v[196:199], 0
	v_mfma_f32_16x16x32_bf16 v[84:87], v[172:175], v[204:207], 0
	v_mfma_f32_16x16x32_bf16 v[80:83], v[180:183], v[204:207], 0
	v_mfma_f32_16x16x32_bf16 v[68:71], v[172:175], v[212:215], 0
	v_mfma_f32_16x16x32_bf16 v[64:67], v[180:183], v[212:215], 0
	v_mfma_f32_16x16x32_bf16 v[116:119], v[176:179], v[192:195], v[116:119]
	v_mfma_f32_16x16x32_bf16 v[112:115], v[184:187], v[192:195], v[112:115]
	v_mfma_f32_16x16x32_bf16 v[100:103], v[176:179], v[200:203], v[100:103]
	v_mfma_f32_16x16x32_bf16 v[96:99], v[184:187], v[200:203], v[96:99]
	v_mfma_f32_16x16x32_bf16 v[84:87], v[176:179], v[208:211], v[84:87]
	v_mfma_f32_16x16x32_bf16 v[80:83], v[184:187], v[208:211], v[80:83]
	v_mfma_f32_16x16x32_bf16 v[68:71], v[176:179], v[216:219], v[68:71]
	v_mfma_f32_16x16x32_bf16 v[64:67], v[184:187], v[216:219], v[64:67]
	s_setprio 0
	s_barrier
	s_add_i32 s34, s64, s51
	v_lshl_add_u64 v[220:221], s[42:43], 0, v[134:135]
	s_mov_b32 m0, s34
	ds_read_b128 v[188:191], v157 offset:16384
	ds_read_b128 v[192:195], v157 offset:17408
	ds_read_b128 v[196:199], v157 offset:18432
	ds_read_b128 v[200:203], v157 offset:19456
	ds_read_b128 v[204:207], v157 offset:20480
	ds_read_b128 v[208:211], v157 offset:21504
	ds_read_b128 v[212:215], v157 offset:22528
	ds_read_b128 v[216:219], v157 offset:23552
	global_load_lds_dwordx4 v[220:221], off
	s_add_i32 m0, s34, 0x2000
	s_add_u32 s34, s42, 0xb0000
	v_lshl_add_u64 v[222:223], s[42:43], 0, v[138:139]
	s_addc_u32 s35, s43, 0
	s_add_i32 s82, s65, s51
	global_load_lds_dwordx4 v[222:223], off
	v_lshl_add_u64 v[224:225], s[34:35], 0, v[134:135]
	s_mov_b32 m0, s82
	v_lshl_add_u64 v[226:227], s[48:49], 0, v[136:137]
	global_load_lds_dwordx4 v[224:225], off
	v_lshl_add_u64 v[224:225], s[34:35], 0, v[138:139]
	s_add_i32 m0, s82, 0x2000
	s_nop 0
	global_load_lds_dwordx4 v[224:225], off
	v_lshl_add_u64 v[224:225], s[48:49], 0, v[132:133]
	s_mov_b32 m0, s52
	s_nop 0
	global_load_lds_dwordx4 v[224:225], off
	s_mov_b32 m0, s53
	s_nop 0
	global_load_lds_dwordx4 v[226:227], off
	s_cmp_lg_u32 s66, 1
	s_cbranch_scc1 .Lmy_rl_6_1
	s_waitcnt vmcnt(8)
	s_branch .Lmy_rj_6_1

.Lmy_rj_6_1:
	s_waitcnt lgkmcnt(0)
	s_barrier
	s_setprio 1
	s_waitcnt lgkmcnt(0)
	v_mfma_f32_16x16x32_bf16 v[60:63], v[148:151], v[188:191], 0
	v_mfma_f32_16x16x32_bf16 v[56:59], v[164:167], v[188:191], 0
	v_mfma_f32_16x16x32_bf16 v[44:47], v[148:151], v[196:199], 0
	v_mfma_f32_16x16x32_bf16 v[40:43], v[164:167], v[196:199], 0
	v_mfma_f32_16x16x32_bf16 v[28:31], v[148:151], v[204:207], 0
	v_mfma_f32_16x16x32_bf16 v[24:27], v[164:167], v[204:207], 0
	v_mfma_f32_16x16x32_bf16 v[12:15], v[148:151], v[212:215], 0
	v_mfma_f32_16x16x32_bf16 v[8:11], v[164:167], v[212:215], 0
	v_mfma_f32_16x16x32_bf16 v[60:63], v[160:163], v[192:195], v[60:63]
	v_mfma_f32_16x16x32_bf16 v[56:59], v[168:171], v[192:195], v[56:59]
	v_mfma_f32_16x16x32_bf16 v[44:47], v[160:163], v[200:203], v[44:47]
	v_mfma_f32_16x16x32_bf16 v[40:43], v[168:171], v[200:203], v[40:43]
	v_mfma_f32_16x16x32_bf16 v[28:31], v[160:163], v[208:211], v[28:31]
	v_mfma_f32_16x16x32_bf16 v[24:27], v[168:171], v[208:211], v[24:27]
	v_mfma_f32_16x16x32_bf16 v[12:15], v[160:163], v[216:219], v[12:15]
	v_mfma_f32_16x16x32_bf16 v[8:11], v[168:171], v[216:219], v[8:11]
	s_setprio 0
	s_setprio 1
	v_mfma_f32_16x16x32_bf16 v[52:55], v[172:175], v[188:191], 0
	v_mfma_f32_16x16x32_bf16 v[48:51], v[180:183], v[188:191], 0
	v_mfma_f32_16x16x32_bf16 v[36:39], v[172:175], v[196:199], 0
	v_mfma_f32_16x16x32_bf16 v[32:35], v[180:183], v[196:199], 0
	v_mfma_f32_16x16x32_bf16 v[20:23], v[172:175], v[204:207], 0
	v_mfma_f32_16x16x32_bf16 v[16:19], v[180:183], v[204:207], 0
	v_mfma_f32_16x16x32_bf16 v[4:7], v[172:175], v[212:215], 0
	v_mfma_f32_16x16x32_bf16 v[0:3], v[180:183], v[212:215], 0
	v_mfma_f32_16x16x32_bf16 v[52:55], v[176:179], v[192:195], v[52:55]
	v_mfma_f32_16x16x32_bf16 v[48:51], v[184:187], v[192:195], v[48:51]
	v_mfma_f32_16x16x32_bf16 v[36:39], v[176:179], v[200:203], v[36:39]
	v_mfma_f32_16x16x32_bf16 v[32:35], v[184:187], v[200:203], v[32:35]
	v_mfma_f32_16x16x32_bf16 v[20:23], v[176:179], v[208:211], v[20:23]
	v_mfma_f32_16x16x32_bf16 v[16:19], v[184:187], v[208:211], v[16:19]
	v_mfma_f32_16x16x32_bf16 v[4:7], v[176:179], v[216:219], v[4:7]
	v_mfma_f32_16x16x32_bf16 v[0:3], v[184:187], v[216:219], v[0:3]
	s_setprio 0
	s_barrier
	s_add_i32 s82, 0, 0x18000
	v_add_u32_e32 v159, s82, v152
	s_add_i32 s83, 0, 0x1c000
	ds_read_b128 v[148:151], v159
	ds_read_b128 v[160:163], v159 offset:1024
	ds_read_b128 v[164:167], v159 offset:2048
	ds_read_b128 v[168:171], v159 offset:3072
	v_add_u32_e32 v159, s83, v152
	ds_read_b128 v[172:175], v159
	ds_read_b128 v[176:179], v159 offset:1024
	ds_read_b128 v[180:183], v159 offset:2048
	ds_read_b128 v[184:187], v159 offset:3072
	s_add_u32 s34, s48, 0xb0000
	s_addc_u32 s35, s49, 0
	s_mov_b32 m0, s54
	v_lshl_add_u64 v[228:229], s[34:35], 0, v[132:133]
	ds_read_b128 v[188:191], v157 offset:32768
	ds_read_b128 v[192:195], v157 offset:33792
	ds_read_b128 v[196:199], v157 offset:34816
	ds_read_b128 v[200:203], v157 offset:35840
	ds_read_b128 v[204:207], v157 offset:36864
	ds_read_b128 v[208:211], v157 offset:37888
	ds_read_b128 v[212:215], v157 offset:38912
	ds_read_b128 v[216:219], v157 offset:39936
	global_load_lds_dwordx4 v[228:229], off
	v_lshl_add_u64 v[228:229], s[34:35], 0, v[136:137]
	s_mov_b32 m0, s55
	s_nop 0
	global_load_lds_dwordx4 v[228:229], off
	s_cmp_lg_u32 s66, 1
	s_cbranch_scc1 .Lmy_rl_6_2
	s_waitcnt vmcnt(8)
	s_branch .Lmy_rj_6_2

.Lmy_rj_6_2:
	s_waitcnt lgkmcnt(0)
	s_barrier
	s_setprio 1
	s_waitcnt lgkmcnt(0)
	v_mfma_f32_16x16x32_bf16 v[124:127], v[148:151], v[188:191], v[124:127]
	v_mfma_f32_16x16x32_bf16 v[120:123], v[164:167], v[188:191], v[120:123]
	v_mfma_f32_16x16x32_bf16 v[108:111], v[148:151], v[196:199], v[108:111]
	v_mfma_f32_16x16x32_bf16 v[104:107], v[164:167], v[196:199], v[104:107]
	v_mfma_f32_16x16x32_bf16 v[92:95], v[148:151], v[204:207], v[92:95]
	v_mfma_f32_16x16x32_bf16 v[88:91], v[164:167], v[204:207], v[88:91]
	v_mfma_f32_16x16x32_bf16 v[76:79], v[148:151], v[212:215], v[76:79]
	v_mfma_f32_16x16x32_bf16 v[72:75], v[164:167], v[212:215], v[72:75]
	v_mfma_f32_16x16x32_bf16 v[124:127], v[160:163], v[192:195], v[124:127]
	v_mfma_f32_16x16x32_bf16 v[120:123], v[168:171], v[192:195], v[120:123]
	v_mfma_f32_16x16x32_bf16 v[108:111], v[160:163], v[200:203], v[108:111]
	v_mfma_f32_16x16x32_bf16 v[104:107], v[168:171], v[200:203], v[104:107]
	v_mfma_f32_16x16x32_bf16 v[92:95], v[160:163], v[208:211], v[92:95]
	v_mfma_f32_16x16x32_bf16 v[88:91], v[168:171], v[208:211], v[88:91]
	v_mfma_f32_16x16x32_bf16 v[76:79], v[160:163], v[216:219], v[76:79]
	v_mfma_f32_16x16x32_bf16 v[72:75], v[168:171], v[216:219], v[72:75]
	s_setprio 0
	s_setprio 1
	v_mfma_f32_16x16x32_bf16 v[116:119], v[172:175], v[188:191], v[116:119]
	v_mfma_f32_16x16x32_bf16 v[112:115], v[180:183], v[188:191], v[112:115]
	v_mfma_f32_16x16x32_bf16 v[100:103], v[172:175], v[196:199], v[100:103]
	v_mfma_f32_16x16x32_bf16 v[96:99], v[180:183], v[196:199], v[96:99]
	v_mfma_f32_16x16x32_bf16 v[84:87], v[172:175], v[204:207], v[84:87]
	v_mfma_f32_16x16x32_bf16 v[80:83], v[180:183], v[204:207], v[80:83]
	v_mfma_f32_16x16x32_bf16 v[68:71], v[172:175], v[212:215], v[68:71]
	v_mfma_f32_16x16x32_bf16 v[64:67], v[180:183], v[212:215], v[64:67]
	v_mfma_f32_16x16x32_bf16 v[116:119], v[176:179], v[192:195], v[116:119]
	v_mfma_f32_16x16x32_bf16 v[112:115], v[184:187], v[192:195], v[112:115]
	v_mfma_f32_16x16x32_bf16 v[100:103], v[176:179], v[200:203], v[100:103]
	v_mfma_f32_16x16x32_bf16 v[96:99], v[184:187], v[200:203], v[96:99]
	v_mfma_f32_16x16x32_bf16 v[84:87], v[176:179], v[208:211], v[84:87]
	v_mfma_f32_16x16x32_bf16 v[80:83], v[184:187], v[208:211], v[80:83]
	v_mfma_f32_16x16x32_bf16 v[68:71], v[176:179], v[216:219], v[68:71]
	v_mfma_f32_16x16x32_bf16 v[64:67], v[184:187], v[216:219], v[64:67]
	s_setprio 0
	s_barrier
	s_add_i32 s34, s82, s51
	v_lshl_add_u64 v[220:221], v[220:221], 0, s[22:23]
	s_mov_b32 m0, s34
	ds_read_b128 v[188:191], v157 offset:49152
	ds_read_b128 v[192:195], v157 offset:50176
	ds_read_b128 v[196:199], v157 offset:51200
	ds_read_b128 v[200:203], v157 offset:52224
	ds_read_b128 v[204:207], v157 offset:53248
	ds_read_b128 v[208:211], v157 offset:54272
	ds_read_b128 v[212:215], v157 offset:55296
	ds_read_b128 v[216:219], v157 offset:56320
	global_load_lds_dwordx4 v[220:221], off
	s_add_i32 m0, s34, 0x2000
	s_add_u32 s34, s42, 0xb0080
	v_lshl_add_u64 v[220:221], v[222:223], 0, s[22:23]
	s_addc_u32 s35, s43, 0
	s_add_i32 s42, s83, s51
	global_load_lds_dwordx4 v[220:221], off
	v_lshl_add_u64 v[220:221], s[34:35], 0, v[134:135]
	s_mov_b32 m0, s42
	s_nop 0
	global_load_lds_dwordx4 v[220:221], off
	v_lshl_add_u64 v[220:221], s[34:35], 0, v[138:139]
	s_add_i32 m0, s42, 0x2000
	s_nop 0
	global_load_lds_dwordx4 v[220:221], off
	v_lshl_add_u64 v[220:221], v[224:225], 0, s[22:23]
	s_mov_b32 m0, s57
	s_nop 0
	global_load_lds_dwordx4 v[220:221], off
	v_lshl_add_u64 v[220:221], v[226:227], 0, s[22:23]
	s_mov_b32 m0, s58
	s_nop 0
	global_load_lds_dwordx4 v[220:221], off
	s_waitcnt vmcnt(8)
	s_waitcnt lgkmcnt(0)
	s_barrier
	s_setprio 1
	s_waitcnt lgkmcnt(0)
	v_mfma_f32_16x16x32_bf16 v[60:63], v[148:151], v[188:191], v[60:63]
	v_mfma_f32_16x16x32_bf16 v[56:59], v[164:167], v[188:191], v[56:59]
	v_mfma_f32_16x16x32_bf16 v[44:47], v[148:151], v[196:199], v[44:47]
	v_mfma_f32_16x16x32_bf16 v[40:43], v[164:167], v[196:199], v[40:43]
	v_mfma_f32_16x16x32_bf16 v[28:31], v[148:151], v[204:207], v[28:31]
	v_mfma_f32_16x16x32_bf16 v[24:27], v[164:167], v[204:207], v[24:27]
	v_mfma_f32_16x16x32_bf16 v[12:15], v[148:151], v[212:215], v[12:15]
	v_mfma_f32_16x16x32_bf16 v[8:11], v[164:167], v[212:215], v[8:11]
	v_mfma_f32_16x16x32_bf16 v[60:63], v[160:163], v[192:195], v[60:63]
	v_mfma_f32_16x16x32_bf16 v[56:59], v[168:171], v[192:195], v[56:59]
	v_mfma_f32_16x16x32_bf16 v[44:47], v[160:163], v[200:203], v[44:47]
	v_mfma_f32_16x16x32_bf16 v[40:43], v[168:171], v[200:203], v[40:43]
	v_mfma_f32_16x16x32_bf16 v[28:31], v[160:163], v[208:211], v[28:31]
	v_mfma_f32_16x16x32_bf16 v[24:27], v[168:171], v[208:211], v[24:27]
	v_mfma_f32_16x16x32_bf16 v[12:15], v[160:163], v[216:219], v[12:15]
	v_mfma_f32_16x16x32_bf16 v[8:11], v[168:171], v[216:219], v[8:11]
	s_setprio 0
	s_setprio 1
	v_mfma_f32_16x16x32_bf16 v[52:55], v[172:175], v[188:191], v[52:55]
	v_mfma_f32_16x16x32_bf16 v[48:51], v[180:183], v[188:191], v[48:51]
	v_mfma_f32_16x16x32_bf16 v[36:39], v[172:175], v[196:199], v[36:39]
	v_mfma_f32_16x16x32_bf16 v[32:35], v[180:183], v[196:199], v[32:35]
	v_mfma_f32_16x16x32_bf16 v[20:23], v[172:175], v[204:207], v[20:23]
	v_mfma_f32_16x16x32_bf16 v[16:19], v[180:183], v[204:207], v[16:19]
	v_mfma_f32_16x16x32_bf16 v[4:7], v[172:175], v[212:215], v[4:7]
	v_mfma_f32_16x16x32_bf16 v[0:3], v[180:183], v[212:215], v[0:3]
	v_mfma_f32_16x16x32_bf16 v[52:55], v[176:179], v[192:195], v[52:55]
	v_mfma_f32_16x16x32_bf16 v[48:51], v[184:187], v[192:195], v[48:51]
	v_mfma_f32_16x16x32_bf16 v[36:39], v[176:179], v[200:203], v[36:39]
	v_mfma_f32_16x16x32_bf16 v[32:35], v[184:187], v[200:203], v[32:35]
	v_mfma_f32_16x16x32_bf16 v[20:23], v[176:179], v[208:211], v[20:23]
	v_mfma_f32_16x16x32_bf16 v[16:19], v[184:187], v[208:211], v[16:19]
	v_mfma_f32_16x16x32_bf16 v[4:7], v[176:179], v[216:219], v[4:7]
	v_mfma_f32_16x16x32_bf16 v[0:3], v[184:187], v[216:219], v[0:3]
	s_setprio 0
	s_barrier
	s_add_i32 s81, s81, 2
	s_add_u32 s40, s40, 0x100
	s_addc_u32 s41, s41, 0
	s_add_u32 s13, s13, 0x100
	s_addc_u32 s77, s77, 0

.Lmy_nobar_6:
	s_add_i32 s81, s81, 2
	s_add_u32 s40, s40, 0x100
	s_addc_u32 s41, s41, 0
	s_add_u32 s13, s13, 0x100
	s_addc_u32 s77, s77, 0
	s_cmp_gt_u32 s81, 41
	s_cbranch_scc0 .LBB0_562
	s_add_u32 s100, s0, 0xb0080
	s_addc_u32 s101, s1, 0
	s_add_i32 m0, s52, 0xc000
	v_lshl_add_u64 v[220:221], s[100:101], 0, v[140:141]
	global_load_lds_dwordx4 v[220:221], off
	s_add_i32 m0, s52, 0xe000
	v_lshl_add_u64 v[220:221], s[100:101], 0, v[142:143]
	global_load_lds_dwordx4 v[220:221], off
	s_and_b64 vcc, exec, s[26:27]
	s_cbranch_vccz .LBB0_565
	s_nop 0

.Lmy_nobar2_7:
	ds_read_b128 v[148:151], v160
	ds_read_b128 v[152:155], v160 offset:1024
	ds_read_b128 v[164:167], v160 offset:2048
	ds_read_b128 v[168:171], v160 offset:3072
	ds_read_b128 v[172:175], v161
	ds_read_b128 v[176:179], v161 offset:1024
	ds_read_b128 v[180:183], v161 offset:2048
	ds_read_b128 v[184:187], v161 offset:3072
	s_add_u32 s34, s52, 0xfffc0080
	s_addc_u32 s35, s53, -1
	s_cmp_eq_u32 s77, 12
	s_cselect_b32 s57, s9, s35
	s_cselect_b32 s56, s10, s34
	s_cselect_b32 s55, s12, s43
	s_cselect_b32 s54, s13, s41
	v_lshl_add_u64 v[220:221], s[52:53], 0, v[140:141]
	s_add_i32 m0, s65, 0xc000
	ds_read_b128 v[188:191], v162
	ds_read_b128 v[192:195], v162 offset:1024
	ds_read_b128 v[196:199], v162 offset:2048
	ds_read_b128 v[200:203], v162 offset:3072
	ds_read_b128 v[204:207], v162 offset:4096
	ds_read_b128 v[208:211], v162 offset:5120
	ds_read_b128 v[212:215], v162 offset:6144
	ds_read_b128 v[216:219], v162 offset:7168
	s_cmp_lg_u32 s93, 1
	s_cbranch_scc1 .Lmy_sk_7_0
	global_load_lds_dwordx4 v[220:221], off
.Lmy_sk_7_0:
	v_lshl_add_u64 v[220:221], s[52:53], 0, v[142:143]
	s_add_i32 m0, s65, 0xe000
	s_nop 0
	s_cmp_lg_u32 s93, 1
	s_cbranch_scc1 .Lmy_sk_7_1
	global_load_lds_dwordx4 v[220:221], off
.Lmy_sk_7_1:
	s_cmp_lg_u32 s93, 1
	s_cbranch_scc1 .Lmy_rl_7_0
	s_waitcnt vmcnt(8)
	s_branch .Lmy_rj_7_0
.Lmy_rl_7_0:
	s_waitcnt vmcnt(24)
.Lmy_rj_7_0:
	s_waitcnt lgkmcnt(0)
	s_barrier
	s_setprio 1
	s_waitcnt lgkmcnt(0)
	v_mfma_f32_16x16x32_bf16 v[124:127], v[148:151], v[188:191], 0
	v_mfma_f32_16x16x32_bf16 v[120:123], v[164:167], v[188:191], 0
	v_mfma_f32_16x16x32_bf16 v[108:111], v[148:151], v[196:199], 0
	v_mfma_f32_16x16x32_bf16 v[104:107], v[164:167], v[196:199], 0
	v_mfma_f32_16x16x32_bf16 v[92:95], v[148:151], v[204:207], 0
	v_mfma_f32_16x16x32_bf16 v[88:91], v[164:167], v[204:207], 0
	v_mfma_f32_16x16x32_bf16 v[76:79], v[148:151], v[212:215], 0
	v_mfma_f32_16x16x32_bf16 v[72:75], v[164:167], v[212:215], 0
	v_mfma_f32_16x16x32_bf16 v[124:127], v[152:155], v[192:195], v[124:127]
	v_mfma_f32_16x16x32_bf16 v[120:123], v[168:171], v[192:195], v[120:123]
	v_mfma_f32_16x16x32_bf16 v[108:111], v[152:155], v[200:203], v[108:111]
	v_mfma_f32_16x16x32_bf16 v[104:107], v[168:171], v[200:203], v[104:107]
	v_mfma_f32_16x16x32_bf16 v[92:95], v[152:155], v[208:211], v[92:95]
	v_mfma_f32_16x16x32_bf16 v[88:91], v[168:171], v[208:211], v[88:91]
	v_mfma_f32_16x16x32_bf16 v[76:79], v[152:155], v[216:219], v[76:79]
	v_mfma_f32_16x16x32_bf16 v[72:75], v[168:171], v[216:219], v[72:75]
	s_setprio 0
	s_setprio 1
	v_mfma_f32_16x16x32_bf16 v[116:119], v[172:175], v[188:191], 0
	v_mfma_f32_16x16x32_bf16 v[112:115], v[180:183], v[188:191], 0
	v_mfma_f32_16x16x32_bf16 v[100:103], v[172:175], v[196:199], 0
	v_mfma_f32_16x16x32_bf16 v[96:99], v[180:183], v[196:199], 0
	v_mfma_f32_16x16x32_bf16 v[84:87], v[172:175], v[204:207], 0
	v_mfma_f32_16x16x32_bf16 v[80:83], v[180:183], v[204:207], 0
	v_mfma_f32_16x16x32_bf16 v[68:71], v[172:175], v[212:215], 0
	v_mfma_f32_16x16x32_bf16 v[64:67], v[180:183], v[212:215], 0
	v_mfma_f32_16x16x32_bf16 v[116:119], v[176:179], v[192:195], v[116:119]
	v_mfma_f32_16x16x32_bf16 v[112:115], v[184:187], v[192:195], v[112:115]
	v_mfma_f32_16x16x32_bf16 v[100:103], v[176:179], v[200:203], v[100:103]
	v_mfma_f32_16x16x32_bf16 v[96:99], v[184:187], v[200:203], v[96:99]
	v_mfma_f32_16x16x32_bf16 v[84:87], v[176:179], v[208:211], v[84:87]
	v_mfma_f32_16x16x32_bf16 v[80:83], v[184:187], v[208:211], v[80:83]
	v_mfma_f32_16x16x32_bf16 v[68:71], v[176:179], v[216:219], v[68:71]
	v_mfma_f32_16x16x32_bf16 v[64:67], v[184:187], v[216:219], v[64:67]
	s_setprio 0
	s_barrier
	s_add_i32 s34, s88, s62
	v_lshl_add_u64 v[220:221], s[54:55], 0, v[134:135]
	s_mov_b32 m0, s34
	ds_read_b128 v[188:191], v162 offset:16384
	ds_read_b128 v[192:195], v162 offset:17408
	ds_read_b128 v[196:199], v162 offset:18432
	ds_read_b128 v[200:203], v162 offset:19456
	ds_read_b128 v[204:207], v162 offset:20480
	ds_read_b128 v[208:211], v162 offset:21504
	ds_read_b128 v[212:215], v162 offset:22528
	ds_read_b128 v[216:219], v162 offset:23552
	global_load_lds_dwordx4 v[220:221], off
	s_add_i32 m0, s34, 0x2000
	s_add_u32 s34, s54, 0x40000
	v_lshl_add_u64 v[222:223], s[54:55], 0, v[138:139]
	s_addc_u32 s35, s55, 0
	s_add_i32 s90, s89, s62
	global_load_lds_dwordx4 v[222:223], off
	v_lshl_add_u64 v[224:225], s[34:35], 0, v[134:135]
	s_mov_b32 m0, s90
	v_lshl_add_u64 v[226:227], s[56:57], 0, v[136:137]
	global_load_lds_dwordx4 v[224:225], off
	v_lshl_add_u64 v[224:225], s[34:35], 0, v[138:139]
	s_add_i32 m0, s90, 0x2000
	s_nop 0
	global_load_lds_dwordx4 v[224:225], off
	v_lshl_add_u64 v[224:225], s[56:57], 0, v[132:133]
	s_mov_b32 m0, s65
	s_nop 0
	global_load_lds_dwordx4 v[224:225], off
	s_mov_b32 m0, s66
	s_nop 0
	global_load_lds_dwordx4 v[226:227], off
	s_cmp_lg_u32 s93, 1
	s_cbranch_scc1 .Lmy_rl_7_1
	s_waitcnt vmcnt(8)
	s_branch .Lmy_rj_7_1

.Lmy_rj_7_1:
	s_waitcnt lgkmcnt(0)
	s_barrier
	s_setprio 1
	s_waitcnt lgkmcnt(0)
	v_mfma_f32_16x16x32_bf16 v[60:63], v[148:151], v[188:191], 0
	v_mfma_f32_16x16x32_bf16 v[56:59], v[164:167], v[188:191], 0
	v_mfma_f32_16x16x32_bf16 v[44:47], v[148:151], v[196:199], 0
	v_mfma_f32_16x16x32_bf16 v[40:43], v[164:167], v[196:199], 0
	v_mfma_f32_16x16x32_bf16 v[28:31], v[148:151], v[204:207], 0
	v_mfma_f32_16x16x32_bf16 v[24:27], v[164:167], v[204:207], 0
	v_mfma_f32_16x16x32_bf16 v[12:15], v[148:151], v[212:215], 0
	v_mfma_f32_16x16x32_bf16 v[8:11], v[164:167], v[212:215], 0
	v_mfma_f32_16x16x32_bf16 v[60:63], v[152:155], v[192:195], v[60:63]
	v_mfma_f32_16x16x32_bf16 v[56:59], v[168:171], v[192:195], v[56:59]
	v_mfma_f32_16x16x32_bf16 v[44:47], v[152:155], v[200:203], v[44:47]
	v_mfma_f32_16x16x32_bf16 v[40:43], v[168:171], v[200:203], v[40:43]
	v_mfma_f32_16x16x32_bf16 v[28:31], v[152:155], v[208:211], v[28:31]
	v_mfma_f32_16x16x32_bf16 v[24:27], v[168:171], v[208:211], v[24:27]
	v_mfma_f32_16x16x32_bf16 v[12:15], v[152:155], v[216:219], v[12:15]
	v_mfma_f32_16x16x32_bf16 v[8:11], v[168:171], v[216:219], v[8:11]
	s_setprio 0
	s_setprio 1
	v_mfma_f32_16x16x32_bf16 v[52:55], v[172:175], v[188:191], 0
	v_mfma_f32_16x16x32_bf16 v[48:51], v[180:183], v[188:191], 0
	v_mfma_f32_16x16x32_bf16 v[36:39], v[172:175], v[196:199], 0
	v_mfma_f32_16x16x32_bf16 v[32:35], v[180:183], v[196:199], 0
	v_mfma_f32_16x16x32_bf16 v[20:23], v[172:175], v[204:207], 0
	v_mfma_f32_16x16x32_bf16 v[16:19], v[180:183], v[204:207], 0
	v_mfma_f32_16x16x32_bf16 v[4:7], v[172:175], v[212:215], 0
	v_mfma_f32_16x16x32_bf16 v[0:3], v[180:183], v[212:215], 0
	v_mfma_f32_16x16x32_bf16 v[52:55], v[176:179], v[192:195], v[52:55]
	v_mfma_f32_16x16x32_bf16 v[48:51], v[184:187], v[192:195], v[48:51]
	v_mfma_f32_16x16x32_bf16 v[36:39], v[176:179], v[200:203], v[36:39]
	v_mfma_f32_16x16x32_bf16 v[32:35], v[184:187], v[200:203], v[32:35]
	v_mfma_f32_16x16x32_bf16 v[20:23], v[176:179], v[208:211], v[20:23]
	v_mfma_f32_16x16x32_bf16 v[16:19], v[184:187], v[208:211], v[16:19]
	v_mfma_f32_16x16x32_bf16 v[4:7], v[176:179], v[216:219], v[4:7]
	v_mfma_f32_16x16x32_bf16 v[0:3], v[184:187], v[216:219], v[0:3]
	s_setprio 0
	s_barrier
	s_add_i32 s90, 0, 0x18000
	s_add_i32 s95, 0, 0x1c000
	v_add_u32_e32 v168, s90, v157
	v_add_u32_e32 v184, s95, v157
	ds_read_b128 v[148:151], v168
	ds_read_b128 v[152:155], v168 offset:1024
	ds_read_b128 v[164:167], v168 offset:2048
	ds_read_b128 v[168:171], v168 offset:3072
	ds_read_b128 v[172:175], v184
	ds_read_b128 v[176:179], v184 offset:1024
	ds_read_b128 v[180:183], v184 offset:2048
	ds_read_b128 v[184:187], v184 offset:3072
	s_add_u32 s34, s56, 0x40000
	s_addc_u32 s35, s57, 0
	s_mov_b32 m0, s67
	v_lshl_add_u64 v[228:229], s[34:35], 0, v[132:133]
	ds_read_b128 v[188:191], v162 offset:32768
	ds_read_b128 v[192:195], v162 offset:33792
	ds_read_b128 v[196:199], v162 offset:34816
	ds_read_b128 v[200:203], v162 offset:35840
	ds_read_b128 v[204:207], v162 offset:36864
	ds_read_b128 v[208:211], v162 offset:37888
	ds_read_b128 v[212:215], v162 offset:38912
	ds_read_b128 v[216:219], v162 offset:39936
	global_load_lds_dwordx4 v[228:229], off
	v_lshl_add_u64 v[228:229], s[34:35], 0, v[136:137]
	s_mov_b32 m0, s79
	s_nop 0
	global_load_lds_dwordx4 v[228:229], off
	s_cmp_lg_u32 s93, 1
	s_cbranch_scc1 .Lmy_rl_7_2
	s_waitcnt vmcnt(8)
	s_branch .Lmy_rj_7_2

.Lmy_rj_7_2:
	s_waitcnt lgkmcnt(0)
	s_barrier
	s_setprio 1
	s_waitcnt lgkmcnt(0)
	v_mfma_f32_16x16x32_bf16 v[124:127], v[148:151], v[188:191], v[124:127]
	v_mfma_f32_16x16x32_bf16 v[120:123], v[164:167], v[188:191], v[120:123]
	v_mfma_f32_16x16x32_bf16 v[108:111], v[148:151], v[196:199], v[108:111]
	v_mfma_f32_16x16x32_bf16 v[104:107], v[164:167], v[196:199], v[104:107]
	v_mfma_f32_16x16x32_bf16 v[92:95], v[148:151], v[204:207], v[92:95]
	v_mfma_f32_16x16x32_bf16 v[88:91], v[164:167], v[204:207], v[88:91]
	v_mfma_f32_16x16x32_bf16 v[76:79], v[148:151], v[212:215], v[76:79]
	v_mfma_f32_16x16x32_bf16 v[72:75], v[164:167], v[212:215], v[72:75]
	v_mfma_f32_16x16x32_bf16 v[124:127], v[152:155], v[192:195], v[124:127]
	v_mfma_f32_16x16x32_bf16 v[120:123], v[168:171], v[192:195], v[120:123]
	v_mfma_f32_16x16x32_bf16 v[108:111], v[152:155], v[200:203], v[108:111]
	v_mfma_f32_16x16x32_bf16 v[104:107], v[168:171], v[200:203], v[104:107]
	v_mfma_f32_16x16x32_bf16 v[92:95], v[152:155], v[208:211], v[92:95]
	v_mfma_f32_16x16x32_bf16 v[88:91], v[168:171], v[208:211], v[88:91]
	v_mfma_f32_16x16x32_bf16 v[76:79], v[152:155], v[216:219], v[76:79]
	v_mfma_f32_16x16x32_bf16 v[72:75], v[168:171], v[216:219], v[72:75]
	s_setprio 0
	s_setprio 1
	v_mfma_f32_16x16x32_bf16 v[116:119], v[172:175], v[188:191], v[116:119]
	v_mfma_f32_16x16x32_bf16 v[112:115], v[180:183], v[188:191], v[112:115]
	v_mfma_f32_16x16x32_bf16 v[100:103], v[172:175], v[196:199], v[100:103]
	v_mfma_f32_16x16x32_bf16 v[96:99], v[180:183], v[196:199], v[96:99]
	v_mfma_f32_16x16x32_bf16 v[84:87], v[172:175], v[204:207], v[84:87]
	v_mfma_f32_16x16x32_bf16 v[80:83], v[180:183], v[204:207], v[80:83]
	v_mfma_f32_16x16x32_bf16 v[68:71], v[172:175], v[212:215], v[68:71]
	v_mfma_f32_16x16x32_bf16 v[64:67], v[180:183], v[212:215], v[64:67]
	v_mfma_f32_16x16x32_bf16 v[116:119], v[176:179], v[192:195], v[116:119]
	v_mfma_f32_16x16x32_bf16 v[112:115], v[184:187], v[192:195], v[112:115]
	v_mfma_f32_16x16x32_bf16 v[100:103], v[176:179], v[200:203], v[100:103]
	v_mfma_f32_16x16x32_bf16 v[96:99], v[184:187], v[200:203], v[96:99]
	v_mfma_f32_16x16x32_bf16 v[84:87], v[176:179], v[208:211], v[84:87]
	v_mfma_f32_16x16x32_bf16 v[80:83], v[184:187], v[208:211], v[80:83]
	v_mfma_f32_16x16x32_bf16 v[68:71], v[176:179], v[216:219], v[68:71]
	v_mfma_f32_16x16x32_bf16 v[64:67], v[184:187], v[216:219], v[64:67]
	s_setprio 0
	s_barrier
	s_add_i32 s34, s90, s62
	v_lshl_add_u64 v[220:221], v[220:221], 0, s[26:27]
	s_mov_b32 m0, s34
	ds_read_b128 v[188:191], v162 offset:49152
	ds_read_b128 v[192:195], v162 offset:50176
	ds_read_b128 v[196:199], v162 offset:51200
	ds_read_b128 v[200:203], v162 offset:52224
	ds_read_b128 v[204:207], v162 offset:53248
	ds_read_b128 v[208:211], v162 offset:54272
	ds_read_b128 v[212:215], v162 offset:55296
	ds_read_b128 v[216:219], v162 offset:56320
	global_load_lds_dwordx4 v[220:221], off
	s_add_i32 m0, s34, 0x2000
	s_add_u32 s34, s54, 0x40080
	v_lshl_add_u64 v[220:221], v[222:223], 0, s[26:27]
	s_addc_u32 s35, s55, 0
	s_add_i32 s54, s95, s62
	global_load_lds_dwordx4 v[220:221], off
	v_lshl_add_u64 v[220:221], s[34:35], 0, v[134:135]
	s_mov_b32 m0, s54
	s_nop 0
	global_load_lds_dwordx4 v[220:221], off
	v_lshl_add_u64 v[220:221], s[34:35], 0, v[138:139]
	s_add_i32 m0, s54, 0x2000
	s_nop 0
	global_load_lds_dwordx4 v[220:221], off
	v_lshl_add_u64 v[220:221], v[224:225], 0, s[26:27]
	s_mov_b32 m0, s83
	s_nop 0
	global_load_lds_dwordx4 v[220:221], off
	v_lshl_add_u64 v[220:221], v[226:227], 0, s[26:27]
	s_mov_b32 m0, s84
	s_nop 0
	global_load_lds_dwordx4 v[220:221], off
	s_waitcnt vmcnt(8)
	s_waitcnt lgkmcnt(0)
	s_barrier
	s_setprio 1
	s_waitcnt lgkmcnt(0)
	v_mfma_f32_16x16x32_bf16 v[60:63], v[148:151], v[188:191], v[60:63]
	v_mfma_f32_16x16x32_bf16 v[56:59], v[164:167], v[188:191], v[56:59]
	v_mfma_f32_16x16x32_bf16 v[44:47], v[148:151], v[196:199], v[44:47]
	v_mfma_f32_16x16x32_bf16 v[40:43], v[164:167], v[196:199], v[40:43]
	v_mfma_f32_16x16x32_bf16 v[28:31], v[148:151], v[204:207], v[28:31]
	v_mfma_f32_16x16x32_bf16 v[24:27], v[164:167], v[204:207], v[24:27]
	v_mfma_f32_16x16x32_bf16 v[12:15], v[148:151], v[212:215], v[12:15]
	v_mfma_f32_16x16x32_bf16 v[8:11], v[164:167], v[212:215], v[8:11]
	v_mfma_f32_16x16x32_bf16 v[60:63], v[152:155], v[192:195], v[60:63]
	v_mfma_f32_16x16x32_bf16 v[56:59], v[168:171], v[192:195], v[56:59]
	v_mfma_f32_16x16x32_bf16 v[44:47], v[152:155], v[200:203], v[44:47]
	v_mfma_f32_16x16x32_bf16 v[40:43], v[168:171], v[200:203], v[40:43]
	v_mfma_f32_16x16x32_bf16 v[28:31], v[152:155], v[208:211], v[28:31]
	v_mfma_f32_16x16x32_bf16 v[24:27], v[168:171], v[208:211], v[24:27]
	v_mfma_f32_16x16x32_bf16 v[12:15], v[152:155], v[216:219], v[12:15]
	v_mfma_f32_16x16x32_bf16 v[8:11], v[168:171], v[216:219], v[8:11]
	s_setprio 0
	s_setprio 1
	v_mfma_f32_16x16x32_bf16 v[52:55], v[172:175], v[188:191], v[52:55]
	v_mfma_f32_16x16x32_bf16 v[48:51], v[180:183], v[188:191], v[48:51]
	v_mfma_f32_16x16x32_bf16 v[36:39], v[172:175], v[196:199], v[36:39]
	v_mfma_f32_16x16x32_bf16 v[32:35], v[180:183], v[196:199], v[32:35]
	v_mfma_f32_16x16x32_bf16 v[20:23], v[172:175], v[204:207], v[20:23]
	v_mfma_f32_16x16x32_bf16 v[16:19], v[180:183], v[204:207], v[16:19]
	v_mfma_f32_16x16x32_bf16 v[4:7], v[172:175], v[212:215], v[4:7]
	v_mfma_f32_16x16x32_bf16 v[0:3], v[180:183], v[212:215], v[0:3]
	v_mfma_f32_16x16x32_bf16 v[52:55], v[176:179], v[192:195], v[52:55]
	v_mfma_f32_16x16x32_bf16 v[48:51], v[184:187], v[192:195], v[48:51]
	v_mfma_f32_16x16x32_bf16 v[36:39], v[176:179], v[200:203], v[36:39]
	v_mfma_f32_16x16x32_bf16 v[32:35], v[184:187], v[200:203], v[32:35]
	v_mfma_f32_16x16x32_bf16 v[20:23], v[176:179], v[208:211], v[20:23]
	v_mfma_f32_16x16x32_bf16 v[16:19], v[184:187], v[208:211], v[16:19]
	v_mfma_f32_16x16x32_bf16 v[4:7], v[176:179], v[216:219], v[4:7]
	v_mfma_f32_16x16x32_bf16 v[0:3], v[184:187], v[216:219], v[0:3]
	s_setprio 0
	s_barrier
	s_add_i32 s77, s77, 2
	s_add_u32 s52, s52, 0x100
	s_addc_u32 s53, s53, 0
	s_add_u32 s41, s41, 0x100
	s_addc_u32 s43, s43, 0

.Lmy_nobar_7:
	s_add_i32 s77, s77, 2
	s_add_u32 s52, s52, 0x100
	s_addc_u32 s53, s53, 0
	s_add_u32 s41, s41, 0x100
	s_addc_u32 s43, s43, 0
	s_cmp_gt_u32 s77, 13
	s_cbranch_scc0 .LBB0_655
	s_add_u32 s100, s10, 0x40080
	s_addc_u32 s101, s9, 0
	s_add_i32 m0, s65, 0xc000
	v_lshl_add_u64 v[220:221], s[100:101], 0, v[140:141]
	global_load_lds_dwordx4 v[220:221], off
	s_add_i32 m0, s65, 0xe000
	v_lshl_add_u64 v[220:221], s[100:101], 0, v[142:143]
	global_load_lds_dwordx4 v[220:221], off
	s_and_b64 vcc, exec, s[28:29]
	s_cbranch_vccz .LBB0_658
	s_nop 0

.Lmy_nobar2_9:
	ds_read_b128 v[148:151], v154
	ds_read_b128 v[160:163], v154 offset:1024
	ds_read_b128 v[164:167], v154 offset:2048
	ds_read_b128 v[168:171], v154 offset:3072
	ds_read_b128 v[172:175], v155
	ds_read_b128 v[176:179], v155 offset:1024
	ds_read_b128 v[180:183], v155 offset:2048
	ds_read_b128 v[184:187], v155 offset:3072
	s_add_u32 s34, s40, 0xfffc0080
	s_addc_u32 s35, s41, -1
	s_cmp_eq_u32 s77, 12
	s_cselect_b32 s49, s12, s35
	s_cselect_b32 s48, s13, s34
	s_cselect_b32 s43, s27, s67
	s_cselect_b32 s42, s29, s39
	v_lshl_add_u64 v[220:221], s[40:41], 0, v[140:141]
	s_add_i32 m0, s52, 0xc000
	ds_read_b128 v[188:191], v157
	ds_read_b128 v[192:195], v157 offset:1024
	ds_read_b128 v[196:199], v157 offset:2048
	ds_read_b128 v[200:203], v157 offset:3072
	ds_read_b128 v[204:207], v157 offset:4096
	ds_read_b128 v[208:211], v157 offset:5120
	ds_read_b128 v[212:215], v157 offset:6144
	ds_read_b128 v[216:219], v157 offset:7168
	s_cmp_lg_u32 s66, 1
	s_cbranch_scc1 .Lmy_sk_9_0
	global_load_lds_dwordx4 v[220:221], off

.Lmy_rj_9_0:
	s_waitcnt lgkmcnt(0)
	s_barrier
	s_setprio 1
	s_waitcnt lgkmcnt(0)
	v_mfma_f32_16x16x32_bf16 v[124:127], v[148:151], v[188:191], 0
	v_mfma_f32_16x16x32_bf16 v[120:123], v[164:167], v[188:191], 0
	v_mfma_f32_16x16x32_bf16 v[108:111], v[148:151], v[196:199], 0
	v_mfma_f32_16x16x32_bf16 v[104:107], v[164:167], v[196:199], 0
	v_mfma_f32_16x16x32_bf16 v[92:95], v[148:151], v[204:207], 0
	v_mfma_f32_16x16x32_bf16 v[88:91], v[164:167], v[204:207], 0
	v_mfma_f32_16x16x32_bf16 v[76:79], v[148:151], v[212:215], 0
	v_mfma_f32_16x16x32_bf16 v[72:75], v[164:167], v[212:215], 0
	v_mfma_f32_16x16x32_bf16 v[124:127], v[160:163], v[192:195], v[124:127]
	v_mfma_f32_16x16x32_bf16 v[120:123], v[168:171], v[192:195], v[120:123]
	v_mfma_f32_16x16x32_bf16 v[108:111], v[160:163], v[200:203], v[108:111]
	v_mfma_f32_16x16x32_bf16 v[104:107], v[168:171], v[200:203], v[104:107]
	v_mfma_f32_16x16x32_bf16 v[92:95], v[160:163], v[208:211], v[92:95]
	v_mfma_f32_16x16x32_bf16 v[88:91], v[168:171], v[208:211], v[88:91]
	v_mfma_f32_16x16x32_bf16 v[76:79], v[160:163], v[216:219], v[76:79]
	v_mfma_f32_16x16x32_bf16 v[72:75], v[168:171], v[216:219], v[72:75]
	s_setprio 0
	s_setprio 1
	v_mfma_f32_16x16x32_bf16 v[116:119], v[172:175], v[188:191], 0
	v_mfma_f32_16x16x32_bf16 v[112:115], v[180:183], v[188:191], 0
	v_mfma_f32_16x16x32_bf16 v[100:103], v[172:175], v[196:199], 0
	v_mfma_f32_16x16x32_bf16 v[96:99], v[180:183], v[196:199], 0
	v_mfma_f32_16x16x32_bf16 v[84:87], v[172:175], v[204:207], 0
	v_mfma_f32_16x16x32_bf16 v[80:83], v[180:183], v[204:207], 0
	v_mfma_f32_16x16x32_bf16 v[68:71], v[172:175], v[212:215], 0
	v_mfma_f32_16x16x32_bf16 v[64:67], v[180:183], v[212:215], 0
	v_mfma_f32_16x16x32_bf16 v[116:119], v[176:179], v[192:195], v[116:119]
	v_mfma_f32_16x16x32_bf16 v[112:115], v[184:187], v[192:195], v[112:115]
	v_mfma_f32_16x16x32_bf16 v[100:103], v[176:179], v[200:203], v[100:103]
	v_mfma_f32_16x16x32_bf16 v[96:99], v[184:187], v[200:203], v[96:99]
	v_mfma_f32_16x16x32_bf16 v[84:87], v[176:179], v[208:211], v[84:87]
	v_mfma_f32_16x16x32_bf16 v[80:83], v[184:187], v[208:211], v[80:83]
	v_mfma_f32_16x16x32_bf16 v[68:71], v[176:179], v[216:219], v[68:71]
	v_mfma_f32_16x16x32_bf16 v[64:67], v[184:187], v[216:219], v[64:67]
	s_setprio 0
	s_barrier
	s_add_i32 s34, s64, s51
	v_lshl_add_u64 v[220:221], s[42:43], 0, v[134:135]
	s_mov_b32 m0, s34
	ds_read_b128 v[188:191], v157 offset:16384
	ds_read_b128 v[192:195], v157 offset:17408
	ds_read_b128 v[196:199], v157 offset:18432
	ds_read_b128 v[200:203], v157 offset:19456
	ds_read_b128 v[204:207], v157 offset:20480
	ds_read_b128 v[208:211], v157 offset:21504
	ds_read_b128 v[212:215], v157 offset:22528
	ds_read_b128 v[216:219], v157 offset:23552
	global_load_lds_dwordx4 v[220:221], off
	s_add_i32 m0, s34, 0x2000
	s_add_u32 s34, s42, 0x40000
	v_lshl_add_u64 v[222:223], s[42:43], 0, v[138:139]
	s_addc_u32 s35, s43, 0
	s_add_i32 s79, s65, s51
	global_load_lds_dwordx4 v[222:223], off
	v_lshl_add_u64 v[224:225], s[34:35], 0, v[134:135]
	s_mov_b32 m0, s79
	v_lshl_add_u64 v[226:227], s[48:49], 0, v[136:137]
	global_load_lds_dwordx4 v[224:225], off
	v_lshl_add_u64 v[224:225], s[34:35], 0, v[138:139]
	s_add_i32 m0, s79, 0x2000
	s_nop 0
	global_load_lds_dwordx4 v[224:225], off
	v_lshl_add_u64 v[224:225], s[48:49], 0, v[132:133]
	s_mov_b32 m0, s52
	s_nop 0
	global_load_lds_dwordx4 v[224:225], off
	s_mov_b32 m0, s53
	s_nop 0
	global_load_lds_dwordx4 v[226:227], off
	s_cmp_lg_u32 s66, 1
	s_cbranch_scc1 .Lmy_rl_9_1
	s_waitcnt vmcnt(8)
	s_branch .Lmy_rj_9_1

.Lmy_rj_9_1:
	s_waitcnt lgkmcnt(0)
	s_barrier
	s_setprio 1
	s_waitcnt lgkmcnt(0)
	v_mfma_f32_16x16x32_bf16 v[60:63], v[148:151], v[188:191], 0
	v_mfma_f32_16x16x32_bf16 v[56:59], v[164:167], v[188:191], 0
	v_mfma_f32_16x16x32_bf16 v[44:47], v[148:151], v[196:199], 0
	v_mfma_f32_16x16x32_bf16 v[40:43], v[164:167], v[196:199], 0
	v_mfma_f32_16x16x32_bf16 v[28:31], v[148:151], v[204:207], 0
	v_mfma_f32_16x16x32_bf16 v[24:27], v[164:167], v[204:207], 0
	v_mfma_f32_16x16x32_bf16 v[12:15], v[148:151], v[212:215], 0
	v_mfma_f32_16x16x32_bf16 v[8:11], v[164:167], v[212:215], 0
	v_mfma_f32_16x16x32_bf16 v[60:63], v[160:163], v[192:195], v[60:63]
	v_mfma_f32_16x16x32_bf16 v[56:59], v[168:171], v[192:195], v[56:59]
	v_mfma_f32_16x16x32_bf16 v[44:47], v[160:163], v[200:203], v[44:47]
	v_mfma_f32_16x16x32_bf16 v[40:43], v[168:171], v[200:203], v[40:43]
	v_mfma_f32_16x16x32_bf16 v[28:31], v[160:163], v[208:211], v[28:31]
	v_mfma_f32_16x16x32_bf16 v[24:27], v[168:171], v[208:211], v[24:27]
	v_mfma_f32_16x16x32_bf16 v[12:15], v[160:163], v[216:219], v[12:15]
	v_mfma_f32_16x16x32_bf16 v[8:11], v[168:171], v[216:219], v[8:11]
	s_setprio 0
	s_setprio 1
	v_mfma_f32_16x16x32_bf16 v[52:55], v[172:175], v[188:191], 0
	v_mfma_f32_16x16x32_bf16 v[48:51], v[180:183], v[188:191], 0
	v_mfma_f32_16x16x32_bf16 v[36:39], v[172:175], v[196:199], 0
	v_mfma_f32_16x16x32_bf16 v[32:35], v[180:183], v[196:199], 0
	v_mfma_f32_16x16x32_bf16 v[20:23], v[172:175], v[204:207], 0
	v_mfma_f32_16x16x32_bf16 v[16:19], v[180:183], v[204:207], 0
	v_mfma_f32_16x16x32_bf16 v[4:7], v[172:175], v[212:215], 0
	v_mfma_f32_16x16x32_bf16 v[0:3], v[180:183], v[212:215], 0
	v_mfma_f32_16x16x32_bf16 v[52:55], v[176:179], v[192:195], v[52:55]
	v_mfma_f32_16x16x32_bf16 v[48:51], v[184:187], v[192:195], v[48:51]
	v_mfma_f32_16x16x32_bf16 v[36:39], v[176:179], v[200:203], v[36:39]
	v_mfma_f32_16x16x32_bf16 v[32:35], v[184:187], v[200:203], v[32:35]
	v_mfma_f32_16x16x32_bf16 v[20:23], v[176:179], v[208:211], v[20:23]
	v_mfma_f32_16x16x32_bf16 v[16:19], v[184:187], v[208:211], v[16:19]
	v_mfma_f32_16x16x32_bf16 v[4:7], v[176:179], v[216:219], v[4:7]
	v_mfma_f32_16x16x32_bf16 v[0:3], v[184:187], v[216:219], v[0:3]
	s_setprio 0
	s_barrier
	s_add_i32 s79, 0, 0x18000
	v_add_u32_e32 v159, s79, v152
	s_add_i32 s81, 0, 0x1c000
	ds_read_b128 v[148:151], v159
	ds_read_b128 v[160:163], v159 offset:1024
	ds_read_b128 v[164:167], v159 offset:2048
	ds_read_b128 v[168:171], v159 offset:3072
	v_add_u32_e32 v159, s81, v152
	ds_read_b128 v[172:175], v159
	ds_read_b128 v[176:179], v159 offset:1024
	ds_read_b128 v[180:183], v159 offset:2048
	ds_read_b128 v[184:187], v159 offset:3072
	s_add_u32 s34, s48, 0x40000
	s_addc_u32 s35, s49, 0
	s_mov_b32 m0, s54
	v_lshl_add_u64 v[228:229], s[34:35], 0, v[132:133]
	ds_read_b128 v[188:191], v157 offset:32768
	ds_read_b128 v[192:195], v157 offset:33792
	ds_read_b128 v[196:199], v157 offset:34816
	ds_read_b128 v[200:203], v157 offset:35840
	ds_read_b128 v[204:207], v157 offset:36864
	ds_read_b128 v[208:211], v157 offset:37888
	ds_read_b128 v[212:215], v157 offset:38912
	ds_read_b128 v[216:219], v157 offset:39936
	global_load_lds_dwordx4 v[228:229], off
	v_lshl_add_u64 v[228:229], s[34:35], 0, v[136:137]
	s_mov_b32 m0, s55
	s_nop 0
	global_load_lds_dwordx4 v[228:229], off
	s_cmp_lg_u32 s66, 1
	s_cbranch_scc1 .Lmy_rl_9_2
	s_waitcnt vmcnt(8)
	s_branch .Lmy_rj_9_2

.Lmy_rj_9_2:
	s_waitcnt lgkmcnt(0)
	s_barrier
	s_setprio 1
	s_waitcnt lgkmcnt(0)
	v_mfma_f32_16x16x32_bf16 v[124:127], v[148:151], v[188:191], v[124:127]
	v_mfma_f32_16x16x32_bf16 v[120:123], v[164:167], v[188:191], v[120:123]
	v_mfma_f32_16x16x32_bf16 v[108:111], v[148:151], v[196:199], v[108:111]
	v_mfma_f32_16x16x32_bf16 v[104:107], v[164:167], v[196:199], v[104:107]
	v_mfma_f32_16x16x32_bf16 v[92:95], v[148:151], v[204:207], v[92:95]
	v_mfma_f32_16x16x32_bf16 v[88:91], v[164:167], v[204:207], v[88:91]
	v_mfma_f32_16x16x32_bf16 v[76:79], v[148:151], v[212:215], v[76:79]
	v_mfma_f32_16x16x32_bf16 v[72:75], v[164:167], v[212:215], v[72:75]
	v_mfma_f32_16x16x32_bf16 v[124:127], v[160:163], v[192:195], v[124:127]
	v_mfma_f32_16x16x32_bf16 v[120:123], v[168:171], v[192:195], v[120:123]
	v_mfma_f32_16x16x32_bf16 v[108:111], v[160:163], v[200:203], v[108:111]
	v_mfma_f32_16x16x32_bf16 v[104:107], v[168:171], v[200:203], v[104:107]
	v_mfma_f32_16x16x32_bf16 v[92:95], v[160:163], v[208:211], v[92:95]
	v_mfma_f32_16x16x32_bf16 v[88:91], v[168:171], v[208:211], v[88:91]
	v_mfma_f32_16x16x32_bf16 v[76:79], v[160:163], v[216:219], v[76:79]
	v_mfma_f32_16x16x32_bf16 v[72:75], v[168:171], v[216:219], v[72:75]
	s_setprio 0
	s_setprio 1
	v_mfma_f32_16x16x32_bf16 v[116:119], v[172:175], v[188:191], v[116:119]
	v_mfma_f32_16x16x32_bf16 v[112:115], v[180:183], v[188:191], v[112:115]
	v_mfma_f32_16x16x32_bf16 v[100:103], v[172:175], v[196:199], v[100:103]
	v_mfma_f32_16x16x32_bf16 v[96:99], v[180:183], v[196:199], v[96:99]
	v_mfma_f32_16x16x32_bf16 v[84:87], v[172:175], v[204:207], v[84:87]
	v_mfma_f32_16x16x32_bf16 v[80:83], v[180:183], v[204:207], v[80:83]
	v_mfma_f32_16x16x32_bf16 v[68:71], v[172:175], v[212:215], v[68:71]
	v_mfma_f32_16x16x32_bf16 v[64:67], v[180:183], v[212:215], v[64:67]
	v_mfma_f32_16x16x32_bf16 v[116:119], v[176:179], v[192:195], v[116:119]
	v_mfma_f32_16x16x32_bf16 v[112:115], v[184:187], v[192:195], v[112:115]
	v_mfma_f32_16x16x32_bf16 v[100:103], v[176:179], v[200:203], v[100:103]
	v_mfma_f32_16x16x32_bf16 v[96:99], v[184:187], v[200:203], v[96:99]
	v_mfma_f32_16x16x32_bf16 v[84:87], v[176:179], v[208:211], v[84:87]
	v_mfma_f32_16x16x32_bf16 v[80:83], v[184:187], v[208:211], v[80:83]
	v_mfma_f32_16x16x32_bf16 v[68:71], v[176:179], v[216:219], v[68:71]
	v_mfma_f32_16x16x32_bf16 v[64:67], v[184:187], v[216:219], v[64:67]
	s_setprio 0
	s_barrier
	s_add_i32 s34, s79, s51
	v_lshl_add_u64 v[220:221], v[220:221], 0, s[10:11]
	s_mov_b32 m0, s34
	ds_read_b128 v[188:191], v157 offset:49152
	ds_read_b128 v[192:195], v157 offset:50176
	ds_read_b128 v[196:199], v157 offset:51200
	ds_read_b128 v[200:203], v157 offset:52224
	ds_read_b128 v[204:207], v157 offset:53248
	ds_read_b128 v[208:211], v157 offset:54272
	ds_read_b128 v[212:215], v157 offset:55296
	ds_read_b128 v[216:219], v157 offset:56320
	global_load_lds_dwordx4 v[220:221], off
	s_add_i32 m0, s34, 0x2000
	s_add_u32 s34, s42, 0x40080
	v_lshl_add_u64 v[220:221], v[222:223], 0, s[10:11]
	s_addc_u32 s35, s43, 0
	s_add_i32 s42, s81, s51
	global_load_lds_dwordx4 v[220:221], off
	v_lshl_add_u64 v[220:221], s[34:35], 0, v[134:135]
	s_mov_b32 m0, s42
	s_nop 0
	global_load_lds_dwordx4 v[220:221], off
	v_lshl_add_u64 v[220:221], s[34:35], 0, v[138:139]
	s_add_i32 m0, s42, 0x2000
	s_nop 0
	global_load_lds_dwordx4 v[220:221], off
	v_lshl_add_u64 v[220:221], v[224:225], 0, s[10:11]
	s_mov_b32 m0, s57
	s_nop 0
	global_load_lds_dwordx4 v[220:221], off
	v_lshl_add_u64 v[220:221], v[226:227], 0, s[10:11]
	s_mov_b32 m0, s58
	s_nop 0
	global_load_lds_dwordx4 v[220:221], off
	s_waitcnt vmcnt(8)
	s_waitcnt lgkmcnt(0)
	s_barrier
	s_setprio 1
	s_waitcnt lgkmcnt(0)
	v_mfma_f32_16x16x32_bf16 v[60:63], v[148:151], v[188:191], v[60:63]
	v_mfma_f32_16x16x32_bf16 v[56:59], v[164:167], v[188:191], v[56:59]
	v_mfma_f32_16x16x32_bf16 v[44:47], v[148:151], v[196:199], v[44:47]
	v_mfma_f32_16x16x32_bf16 v[40:43], v[164:167], v[196:199], v[40:43]
	v_mfma_f32_16x16x32_bf16 v[28:31], v[148:151], v[204:207], v[28:31]
	v_mfma_f32_16x16x32_bf16 v[24:27], v[164:167], v[204:207], v[24:27]
	v_mfma_f32_16x16x32_bf16 v[12:15], v[148:151], v[212:215], v[12:15]
	v_mfma_f32_16x16x32_bf16 v[8:11], v[164:167], v[212:215], v[8:11]
	v_mfma_f32_16x16x32_bf16 v[60:63], v[160:163], v[192:195], v[60:63]
	v_mfma_f32_16x16x32_bf16 v[56:59], v[168:171], v[192:195], v[56:59]
	v_mfma_f32_16x16x32_bf16 v[44:47], v[160:163], v[200:203], v[44:47]
	v_mfma_f32_16x16x32_bf16 v[40:43], v[168:171], v[200:203], v[40:43]
	v_mfma_f32_16x16x32_bf16 v[28:31], v[160:163], v[208:211], v[28:31]
	v_mfma_f32_16x16x32_bf16 v[24:27], v[168:171], v[208:211], v[24:27]
	v_mfma_f32_16x16x32_bf16 v[12:15], v[160:163], v[216:219], v[12:15]
	v_mfma_f32_16x16x32_bf16 v[8:11], v[168:171], v[216:219], v[8:11]
	s_setprio 0
	s_setprio 1
	v_mfma_f32_16x16x32_bf16 v[52:55], v[172:175], v[188:191], v[52:55]
	v_mfma_f32_16x16x32_bf16 v[48:51], v[180:183], v[188:191], v[48:51]
	v_mfma_f32_16x16x32_bf16 v[36:39], v[172:175], v[196:199], v[36:39]
	v_mfma_f32_16x16x32_bf16 v[32:35], v[180:183], v[196:199], v[32:35]
	v_mfma_f32_16x16x32_bf16 v[20:23], v[172:175], v[204:207], v[20:23]
	v_mfma_f32_16x16x32_bf16 v[16:19], v[180:183], v[204:207], v[16:19]
	v_mfma_f32_16x16x32_bf16 v[4:7], v[172:175], v[212:215], v[4:7]
	v_mfma_f32_16x16x32_bf16 v[0:3], v[180:183], v[212:215], v[0:3]
	v_mfma_f32_16x16x32_bf16 v[52:55], v[176:179], v[192:195], v[52:55]
	v_mfma_f32_16x16x32_bf16 v[48:51], v[184:187], v[192:195], v[48:51]
	v_mfma_f32_16x16x32_bf16 v[36:39], v[176:179], v[200:203], v[36:39]
	v_mfma_f32_16x16x32_bf16 v[32:35], v[184:187], v[200:203], v[32:35]
	v_mfma_f32_16x16x32_bf16 v[20:23], v[176:179], v[208:211], v[20:23]
	v_mfma_f32_16x16x32_bf16 v[16:19], v[184:187], v[208:211], v[16:19]
	v_mfma_f32_16x16x32_bf16 v[4:7], v[176:179], v[216:219], v[4:7]
	v_mfma_f32_16x16x32_bf16 v[0:3], v[184:187], v[216:219], v[0:3]
	s_setprio 0
	s_barrier
	s_add_i32 s77, s77, 2
	s_add_u32 s40, s40, 0x100
	s_addc_u32 s41, s41, 0
	s_add_u32 s39, s39, 0x100
	s_addc_u32 s67, s67, 0

.Lmy_nobar_9:
	s_add_i32 s77, s77, 2
	s_add_u32 s40, s40, 0x100
	s_addc_u32 s41, s41, 0
	s_add_u32 s39, s39, 0x100
	s_addc_u32 s67, s67, 0
	s_cmp_gt_u32 s77, 13
	s_cbranch_scc0 .LBB0_969
	s_add_u32 s100, s13, 0x40080
	s_addc_u32 s101, s12, 0
	s_add_i32 m0, s52, 0xc000
	v_lshl_add_u64 v[220:221], s[100:101], 0, v[140:141]
	global_load_lds_dwordx4 v[220:221], off
	s_add_i32 m0, s52, 0xe000
	v_lshl_add_u64 v[220:221], s[100:101], 0, v[142:143]
	global_load_lds_dwordx4 v[220:221], off
	s_and_b64 vcc, exec, s[22:23]
	s_cbranch_vccz .LBB0_972
	s_nop 0

.Lmy_nobar2_10:
	ds_read_b128 v[148:151], v155
	ds_read_b128 v[160:163], v155 offset:1024
	ds_read_b128 v[164:167], v155 offset:2048
	ds_read_b128 v[168:171], v155 offset:3072
	ds_read_b128 v[172:175], v157
	ds_read_b128 v[176:179], v157 offset:1024
	ds_read_b128 v[180:183], v157 offset:2048
	ds_read_b128 v[184:187], v157 offset:3072
	s_add_u32 s34, s36, 0xfffc0080
	s_addc_u32 s35, s37, -1
	s_cmp_eq_u32 s77, 12
	s_cselect_b32 s41, s23, s35
	s_cselect_b32 s40, s64, s34
	s_cselect_b32 s39, s11, s67
	s_cselect_b32 s38, s65, s66
	v_lshl_add_u64 v[220:221], s[36:37], 0, v[140:141]
	s_add_i32 m0, s31, 0xc000
	ds_read_b128 v[188:191], v158
	ds_read_b128 v[192:195], v158 offset:1024
	ds_read_b128 v[196:199], v158 offset:2048
	ds_read_b128 v[200:203], v158 offset:3072
	ds_read_b128 v[204:207], v158 offset:4096
	ds_read_b128 v[208:211], v158 offset:5120
	ds_read_b128 v[212:215], v158 offset:6144
	ds_read_b128 v[216:219], v158 offset:7168
	s_cmp_lg_u32 s62, 1
	s_cbranch_scc1 .Lmy_sk_10_0
	global_load_lds_dwordx4 v[220:221], off
.Lmy_sk_10_0:
	v_lshl_add_u64 v[220:221], s[36:37], 0, v[142:143]
	s_add_i32 m0, s31, 0xe000
	s_nop 0
	s_cmp_lg_u32 s62, 1
	s_cbranch_scc1 .Lmy_sk_10_1
	global_load_lds_dwordx4 v[220:221], off
.Lmy_sk_10_1:
	s_cmp_lg_u32 s62, 1
	s_cbranch_scc1 .Lmy_rl_10_0
	s_waitcnt vmcnt(8)
	s_branch .Lmy_rj_10_0

.Lmy_rj_10_0:
	s_waitcnt lgkmcnt(0)
	s_barrier
	s_setprio 1
	s_waitcnt lgkmcnt(0)
	v_mfma_f32_16x16x32_bf16 v[124:127], v[148:151], v[188:191], 0
	v_mfma_f32_16x16x32_bf16 v[120:123], v[164:167], v[188:191], 0
	v_mfma_f32_16x16x32_bf16 v[108:111], v[148:151], v[196:199], 0
	v_mfma_f32_16x16x32_bf16 v[104:107], v[164:167], v[196:199], 0
	v_mfma_f32_16x16x32_bf16 v[92:95], v[148:151], v[204:207], 0
	v_mfma_f32_16x16x32_bf16 v[88:91], v[164:167], v[204:207], 0
	v_mfma_f32_16x16x32_bf16 v[76:79], v[148:151], v[212:215], 0
	v_mfma_f32_16x16x32_bf16 v[72:75], v[164:167], v[212:215], 0
	v_mfma_f32_16x16x32_bf16 v[124:127], v[160:163], v[192:195], v[124:127]
	v_mfma_f32_16x16x32_bf16 v[120:123], v[168:171], v[192:195], v[120:123]
	v_mfma_f32_16x16x32_bf16 v[108:111], v[160:163], v[200:203], v[108:111]
	v_mfma_f32_16x16x32_bf16 v[104:107], v[168:171], v[200:203], v[104:107]
	v_mfma_f32_16x16x32_bf16 v[92:95], v[160:163], v[208:211], v[92:95]
	v_mfma_f32_16x16x32_bf16 v[88:91], v[168:171], v[208:211], v[88:91]
	v_mfma_f32_16x16x32_bf16 v[76:79], v[160:163], v[216:219], v[76:79]
	v_mfma_f32_16x16x32_bf16 v[72:75], v[168:171], v[216:219], v[72:75]
	s_setprio 0
	s_setprio 1
	v_mfma_f32_16x16x32_bf16 v[116:119], v[172:175], v[188:191], 0
	v_mfma_f32_16x16x32_bf16 v[112:115], v[180:183], v[188:191], 0
	v_mfma_f32_16x16x32_bf16 v[100:103], v[172:175], v[196:199], 0
	v_mfma_f32_16x16x32_bf16 v[96:99], v[180:183], v[196:199], 0
	v_mfma_f32_16x16x32_bf16 v[84:87], v[172:175], v[204:207], 0
	v_mfma_f32_16x16x32_bf16 v[80:83], v[180:183], v[204:207], 0
	v_mfma_f32_16x16x32_bf16 v[68:71], v[172:175], v[212:215], 0
	v_mfma_f32_16x16x32_bf16 v[64:67], v[180:183], v[212:215], 0
	v_mfma_f32_16x16x32_bf16 v[116:119], v[176:179], v[192:195], v[116:119]
	v_mfma_f32_16x16x32_bf16 v[112:115], v[184:187], v[192:195], v[112:115]
	v_mfma_f32_16x16x32_bf16 v[100:103], v[176:179], v[200:203], v[100:103]
	v_mfma_f32_16x16x32_bf16 v[96:99], v[184:187], v[200:203], v[96:99]
	v_mfma_f32_16x16x32_bf16 v[84:87], v[176:179], v[208:211], v[84:87]
	v_mfma_f32_16x16x32_bf16 v[80:83], v[184:187], v[208:211], v[80:83]
	v_mfma_f32_16x16x32_bf16 v[68:71], v[176:179], v[216:219], v[68:71]
	v_mfma_f32_16x16x32_bf16 v[64:67], v[184:187], v[216:219], v[64:67]
	s_setprio 0
	s_barrier
	s_add_i32 s34, s57, s48
	v_lshl_add_u64 v[220:221], s[38:39], 0, v[136:137]
	s_mov_b32 m0, s34
	ds_read_b128 v[188:191], v158 offset:16384
	ds_read_b128 v[192:195], v158 offset:17408
	ds_read_b128 v[196:199], v158 offset:18432
	ds_read_b128 v[200:203], v158 offset:19456
	ds_read_b128 v[204:207], v158 offset:20480
	ds_read_b128 v[208:211], v158 offset:21504
	ds_read_b128 v[212:215], v158 offset:22528
	ds_read_b128 v[216:219], v158 offset:23552
	global_load_lds_dwordx4 v[220:221], off
	s_add_i32 m0, s34, 0x2000
	s_add_u32 s34, s38, 0x40000
	v_lshl_add_u64 v[222:223], s[38:39], 0, v[132:133]
	s_addc_u32 s35, s39, 0
	s_add_i32 s79, s58, s48
	global_load_lds_dwordx4 v[222:223], off
	v_lshl_add_u64 v[224:225], s[34:35], 0, v[136:137]
	s_mov_b32 m0, s79
	v_lshl_add_u64 v[226:227], s[40:41], 0, v[134:135]
	global_load_lds_dwordx4 v[224:225], off
	v_lshl_add_u64 v[224:225], s[34:35], 0, v[132:133]
	s_add_i32 m0, s79, 0x2000
	s_nop 0
	global_load_lds_dwordx4 v[224:225], off
	v_lshl_add_u64 v[224:225], s[40:41], 0, v[138:139]
	s_mov_b32 m0, s31
	s_nop 0
	global_load_lds_dwordx4 v[224:225], off
	s_mov_b32 m0, s52
	s_nop 0
	global_load_lds_dwordx4 v[226:227], off
	s_cmp_lg_u32 s62, 1
	s_cbranch_scc1 .Lmy_rl_10_1
	s_waitcnt vmcnt(8)
	s_branch .Lmy_rj_10_1

.Lmy_rj_10_1:
	s_waitcnt lgkmcnt(0)
	s_barrier
	s_setprio 1
	s_waitcnt lgkmcnt(0)
	v_mfma_f32_16x16x32_bf16 v[60:63], v[148:151], v[188:191], 0
	v_mfma_f32_16x16x32_bf16 v[56:59], v[164:167], v[188:191], 0
	v_mfma_f32_16x16x32_bf16 v[44:47], v[148:151], v[196:199], 0
	v_mfma_f32_16x16x32_bf16 v[40:43], v[164:167], v[196:199], 0
	v_mfma_f32_16x16x32_bf16 v[28:31], v[148:151], v[204:207], 0
	v_mfma_f32_16x16x32_bf16 v[24:27], v[164:167], v[204:207], 0
	v_mfma_f32_16x16x32_bf16 v[12:15], v[148:151], v[212:215], 0
	v_mfma_f32_16x16x32_bf16 v[8:11], v[164:167], v[212:215], 0
	v_mfma_f32_16x16x32_bf16 v[60:63], v[160:163], v[192:195], v[60:63]
	v_mfma_f32_16x16x32_bf16 v[56:59], v[168:171], v[192:195], v[56:59]
	v_mfma_f32_16x16x32_bf16 v[44:47], v[160:163], v[200:203], v[44:47]
	v_mfma_f32_16x16x32_bf16 v[40:43], v[168:171], v[200:203], v[40:43]
	v_mfma_f32_16x16x32_bf16 v[28:31], v[160:163], v[208:211], v[28:31]
	v_mfma_f32_16x16x32_bf16 v[24:27], v[168:171], v[208:211], v[24:27]
	v_mfma_f32_16x16x32_bf16 v[12:15], v[160:163], v[216:219], v[12:15]
	v_mfma_f32_16x16x32_bf16 v[8:11], v[168:171], v[216:219], v[8:11]
	s_setprio 0
	s_setprio 1
	v_mfma_f32_16x16x32_bf16 v[52:55], v[172:175], v[188:191], 0
	v_mfma_f32_16x16x32_bf16 v[48:51], v[180:183], v[188:191], 0
	v_mfma_f32_16x16x32_bf16 v[36:39], v[172:175], v[196:199], 0
	v_mfma_f32_16x16x32_bf16 v[32:35], v[180:183], v[196:199], 0
	v_mfma_f32_16x16x32_bf16 v[20:23], v[172:175], v[204:207], 0
	v_mfma_f32_16x16x32_bf16 v[16:19], v[180:183], v[204:207], 0
	v_mfma_f32_16x16x32_bf16 v[4:7], v[172:175], v[212:215], 0
	v_mfma_f32_16x16x32_bf16 v[0:3], v[180:183], v[212:215], 0
	v_mfma_f32_16x16x32_bf16 v[52:55], v[176:179], v[192:195], v[52:55]
	v_mfma_f32_16x16x32_bf16 v[48:51], v[184:187], v[192:195], v[48:51]
	v_mfma_f32_16x16x32_bf16 v[36:39], v[176:179], v[200:203], v[36:39]
	v_mfma_f32_16x16x32_bf16 v[32:35], v[184:187], v[200:203], v[32:35]
	v_mfma_f32_16x16x32_bf16 v[20:23], v[176:179], v[208:211], v[20:23]
	v_mfma_f32_16x16x32_bf16 v[16:19], v[184:187], v[208:211], v[16:19]
	v_mfma_f32_16x16x32_bf16 v[4:7], v[176:179], v[216:219], v[4:7]
	v_mfma_f32_16x16x32_bf16 v[0:3], v[184:187], v[216:219], v[0:3]
	s_setprio 0
	s_barrier
	s_add_i32 s79, 0, 0x18000
	v_add_u32_e32 v159, s79, v152
	s_add_i32 s81, 0, 0x1c000
	ds_read_b128 v[148:151], v159
	ds_read_b128 v[160:163], v159 offset:1024
	ds_read_b128 v[164:167], v159 offset:2048
	ds_read_b128 v[168:171], v159 offset:3072
	v_add_u32_e32 v159, s81, v152
	ds_read_b128 v[172:175], v159
	ds_read_b128 v[176:179], v159 offset:1024
	ds_read_b128 v[180:183], v159 offset:2048
	ds_read_b128 v[184:187], v159 offset:3072
	s_add_u32 s34, s40, 0x40000
	s_addc_u32 s35, s41, 0
	s_mov_b32 m0, s53
	v_lshl_add_u64 v[228:229], s[34:35], 0, v[138:139]
	ds_read_b128 v[188:191], v158 offset:32768
	ds_read_b128 v[192:195], v158 offset:33792
	ds_read_b128 v[196:199], v158 offset:34816
	ds_read_b128 v[200:203], v158 offset:35840
	ds_read_b128 v[204:207], v158 offset:36864
	ds_read_b128 v[208:211], v158 offset:37888
	ds_read_b128 v[212:215], v158 offset:38912
	ds_read_b128 v[216:219], v158 offset:39936
	global_load_lds_dwordx4 v[228:229], off
	v_lshl_add_u64 v[228:229], s[34:35], 0, v[134:135]
	s_mov_b32 m0, s54
	s_nop 0
	global_load_lds_dwordx4 v[228:229], off
	s_cmp_lg_u32 s62, 1
	s_cbranch_scc1 .Lmy_rl_10_2
	s_waitcnt vmcnt(8)
	s_branch .Lmy_rj_10_2

.Lmy_rj_10_2:
	s_waitcnt lgkmcnt(0)
	s_barrier
	s_setprio 1
	s_waitcnt lgkmcnt(0)
	v_mfma_f32_16x16x32_bf16 v[124:127], v[148:151], v[188:191], v[124:127]
	v_mfma_f32_16x16x32_bf16 v[120:123], v[164:167], v[188:191], v[120:123]
	v_mfma_f32_16x16x32_bf16 v[108:111], v[148:151], v[196:199], v[108:111]
	v_mfma_f32_16x16x32_bf16 v[104:107], v[164:167], v[196:199], v[104:107]
	v_mfma_f32_16x16x32_bf16 v[92:95], v[148:151], v[204:207], v[92:95]
	v_mfma_f32_16x16x32_bf16 v[88:91], v[164:167], v[204:207], v[88:91]
	v_mfma_f32_16x16x32_bf16 v[76:79], v[148:151], v[212:215], v[76:79]
	v_mfma_f32_16x16x32_bf16 v[72:75], v[164:167], v[212:215], v[72:75]
	v_mfma_f32_16x16x32_bf16 v[124:127], v[160:163], v[192:195], v[124:127]
	v_mfma_f32_16x16x32_bf16 v[120:123], v[168:171], v[192:195], v[120:123]
	v_mfma_f32_16x16x32_bf16 v[108:111], v[160:163], v[200:203], v[108:111]
	v_mfma_f32_16x16x32_bf16 v[104:107], v[168:171], v[200:203], v[104:107]
	v_mfma_f32_16x16x32_bf16 v[92:95], v[160:163], v[208:211], v[92:95]
	v_mfma_f32_16x16x32_bf16 v[88:91], v[168:171], v[208:211], v[88:91]
	v_mfma_f32_16x16x32_bf16 v[76:79], v[160:163], v[216:219], v[76:79]
	v_mfma_f32_16x16x32_bf16 v[72:75], v[168:171], v[216:219], v[72:75]
	s_setprio 0
	s_setprio 1
	v_mfma_f32_16x16x32_bf16 v[116:119], v[172:175], v[188:191], v[116:119]
	v_mfma_f32_16x16x32_bf16 v[112:115], v[180:183], v[188:191], v[112:115]
	v_mfma_f32_16x16x32_bf16 v[100:103], v[172:175], v[196:199], v[100:103]
	v_mfma_f32_16x16x32_bf16 v[96:99], v[180:183], v[196:199], v[96:99]
	v_mfma_f32_16x16x32_bf16 v[84:87], v[172:175], v[204:207], v[84:87]
	v_mfma_f32_16x16x32_bf16 v[80:83], v[180:183], v[204:207], v[80:83]
	v_mfma_f32_16x16x32_bf16 v[68:71], v[172:175], v[212:215], v[68:71]
	v_mfma_f32_16x16x32_bf16 v[64:67], v[180:183], v[212:215], v[64:67]
	v_mfma_f32_16x16x32_bf16 v[116:119], v[176:179], v[192:195], v[116:119]
	v_mfma_f32_16x16x32_bf16 v[112:115], v[184:187], v[192:195], v[112:115]
	v_mfma_f32_16x16x32_bf16 v[100:103], v[176:179], v[200:203], v[100:103]
	v_mfma_f32_16x16x32_bf16 v[96:99], v[184:187], v[200:203], v[96:99]
	v_mfma_f32_16x16x32_bf16 v[84:87], v[176:179], v[208:211], v[84:87]
	v_mfma_f32_16x16x32_bf16 v[80:83], v[184:187], v[208:211], v[80:83]
	v_mfma_f32_16x16x32_bf16 v[68:71], v[176:179], v[216:219], v[68:71]
	v_mfma_f32_16x16x32_bf16 v[64:67], v[184:187], v[216:219], v[64:67]
	s_setprio 0
	s_barrier
	s_add_i32 s34, s79, s48
	v_lshl_add_u64 v[220:221], v[220:221], 0, s[6:7]
	s_mov_b32 m0, s34
	ds_read_b128 v[188:191], v158 offset:49152
	ds_read_b128 v[192:195], v158 offset:50176
	ds_read_b128 v[196:199], v158 offset:51200
	ds_read_b128 v[200:203], v158 offset:52224
	ds_read_b128 v[204:207], v158 offset:53248
	ds_read_b128 v[208:211], v158 offset:54272
	ds_read_b128 v[212:215], v158 offset:55296
	ds_read_b128 v[216:219], v158 offset:56320
	global_load_lds_dwordx4 v[220:221], off
	s_add_i32 m0, s34, 0x2000
	s_add_u32 s34, s38, 0x40080
	v_lshl_add_u64 v[220:221], v[222:223], 0, s[6:7]
	s_addc_u32 s35, s39, 0
	s_add_i32 s38, s81, s48
	global_load_lds_dwordx4 v[220:221], off
	v_lshl_add_u64 v[220:221], s[34:35], 0, v[136:137]
	s_mov_b32 m0, s38
	s_nop 0
	global_load_lds_dwordx4 v[220:221], off
	v_lshl_add_u64 v[220:221], s[34:35], 0, v[132:133]
	s_add_i32 m0, s38, 0x2000
	s_nop 0
	global_load_lds_dwordx4 v[220:221], off
	v_lshl_add_u64 v[220:221], v[224:225], 0, s[6:7]
	s_mov_b32 m0, s55
	s_nop 0
	global_load_lds_dwordx4 v[220:221], off
	v_lshl_add_u64 v[220:221], v[226:227], 0, s[6:7]
	s_mov_b32 m0, s56
	s_nop 0
	global_load_lds_dwordx4 v[220:221], off
	s_waitcnt vmcnt(8)
	s_waitcnt lgkmcnt(0)
	s_barrier
	s_setprio 1
	s_waitcnt lgkmcnt(0)
	v_mfma_f32_16x16x32_bf16 v[60:63], v[148:151], v[188:191], v[60:63]
	v_mfma_f32_16x16x32_bf16 v[56:59], v[164:167], v[188:191], v[56:59]
	v_mfma_f32_16x16x32_bf16 v[44:47], v[148:151], v[196:199], v[44:47]
	v_mfma_f32_16x16x32_bf16 v[40:43], v[164:167], v[196:199], v[40:43]
	v_mfma_f32_16x16x32_bf16 v[28:31], v[148:151], v[204:207], v[28:31]
	v_mfma_f32_16x16x32_bf16 v[24:27], v[164:167], v[204:207], v[24:27]
	v_mfma_f32_16x16x32_bf16 v[12:15], v[148:151], v[212:215], v[12:15]
	v_mfma_f32_16x16x32_bf16 v[8:11], v[164:167], v[212:215], v[8:11]
	v_mfma_f32_16x16x32_bf16 v[60:63], v[160:163], v[192:195], v[60:63]
	v_mfma_f32_16x16x32_bf16 v[56:59], v[168:171], v[192:195], v[56:59]
	v_mfma_f32_16x16x32_bf16 v[44:47], v[160:163], v[200:203], v[44:47]
	v_mfma_f32_16x16x32_bf16 v[40:43], v[168:171], v[200:203], v[40:43]
	v_mfma_f32_16x16x32_bf16 v[28:31], v[160:163], v[208:211], v[28:31]
	v_mfma_f32_16x16x32_bf16 v[24:27], v[168:171], v[208:211], v[24:27]
	v_mfma_f32_16x16x32_bf16 v[12:15], v[160:163], v[216:219], v[12:15]
	v_mfma_f32_16x16x32_bf16 v[8:11], v[168:171], v[216:219], v[8:11]
	s_setprio 0
	s_setprio 1
	v_mfma_f32_16x16x32_bf16 v[52:55], v[172:175], v[188:191], v[52:55]
	v_mfma_f32_16x16x32_bf16 v[48:51], v[180:183], v[188:191], v[48:51]
	v_mfma_f32_16x16x32_bf16 v[36:39], v[172:175], v[196:199], v[36:39]
	v_mfma_f32_16x16x32_bf16 v[32:35], v[180:183], v[196:199], v[32:35]
	v_mfma_f32_16x16x32_bf16 v[20:23], v[172:175], v[204:207], v[20:23]
	v_mfma_f32_16x16x32_bf16 v[16:19], v[180:183], v[204:207], v[16:19]
	v_mfma_f32_16x16x32_bf16 v[4:7], v[172:175], v[212:215], v[4:7]
	v_mfma_f32_16x16x32_bf16 v[0:3], v[180:183], v[212:215], v[0:3]
	v_mfma_f32_16x16x32_bf16 v[52:55], v[176:179], v[192:195], v[52:55]
	v_mfma_f32_16x16x32_bf16 v[48:51], v[184:187], v[192:195], v[48:51]
	v_mfma_f32_16x16x32_bf16 v[36:39], v[176:179], v[200:203], v[36:39]
	v_mfma_f32_16x16x32_bf16 v[32:35], v[184:187], v[200:203], v[32:35]
	v_mfma_f32_16x16x32_bf16 v[20:23], v[176:179], v[208:211], v[20:23]
	v_mfma_f32_16x16x32_bf16 v[16:19], v[184:187], v[208:211], v[16:19]
	v_mfma_f32_16x16x32_bf16 v[4:7], v[176:179], v[216:219], v[4:7]
	v_mfma_f32_16x16x32_bf16 v[0:3], v[184:187], v[216:219], v[0:3]
	s_setprio 0
	s_barrier
	s_add_i32 s77, s77, 2
	s_add_u32 s36, s36, 0x100
	s_addc_u32 s37, s37, 0
	s_add_u32 s66, s66, 0x100
	s_addc_u32 s67, s67, 0

.Lmy_nobar_10:
	s_add_i32 s77, s77, 2
	s_add_u32 s36, s36, 0x100
	s_addc_u32 s37, s37, 0
	s_add_u32 s66, s66, 0x100
	s_addc_u32 s67, s67, 0
	s_cmp_gt_u32 s77, 13
	s_cbranch_scc0 .LBB0_1059
	s_add_u32 s100, s64, 0x40080
	s_addc_u32 s101, s23, 0
	s_add_i32 m0, s31, 0xc000
	v_lshl_add_u64 v[220:221], s[100:101], 0, v[140:141]
	global_load_lds_dwordx4 v[220:221], off
	s_add_i32 m0, s31, 0xe000
	v_lshl_add_u64 v[220:221], s[100:101], 0, v[142:143]
	global_load_lds_dwordx4 v[220:221], off
	s_and_b64 vcc, exec, s[8:9]
	s_cbranch_vccz .LBB0_1062
	s_nop 0

.Lmy_nobar2_11:
	ds_read_b128 v[148:151], v154
	ds_read_b128 v[160:163], v154 offset:1024
	ds_read_b128 v[164:167], v154 offset:2048
	ds_read_b128 v[168:171], v154 offset:3072
	ds_read_b128 v[172:175], v155
	ds_read_b128 v[176:179], v155 offset:1024
	ds_read_b128 v[180:183], v155 offset:2048
	ds_read_b128 v[184:187], v155 offset:3072
	s_add_u32 s34, s30, 0xfff50080
	s_addc_u32 s35, s31, -1
	s_cmp_eq_u32 s64, 40
	s_cselect_b32 s39, s1, s35
	s_cselect_b32 s38, s0, s34
	s_cselect_b32 s37, s29, s63
	s_cselect_b32 s36, s28, s13
	v_lshl_add_u64 v[220:221], s[30:31], 0, v[140:141]
	s_add_i32 m0, s42, 0xc000
	ds_read_b128 v[188:191], v157
	ds_read_b128 v[192:195], v157 offset:1024
	ds_read_b128 v[196:199], v157 offset:2048
	ds_read_b128 v[200:203], v157 offset:3072
	ds_read_b128 v[204:207], v157 offset:4096
	ds_read_b128 v[208:211], v157 offset:5120
	ds_read_b128 v[212:215], v157 offset:6144
	ds_read_b128 v[216:219], v157 offset:7168
	s_cmp_lg_u32 s58, 1
	s_cbranch_scc1 .Lmy_sk_11_0
	global_load_lds_dwordx4 v[220:221], off
.Lmy_sk_11_0:
	v_lshl_add_u64 v[220:221], s[30:31], 0, v[142:143]
	s_add_i32 m0, s42, 0xe000
	s_nop 0
	s_cmp_lg_u32 s58, 1
	s_cbranch_scc1 .Lmy_sk_11_1
	global_load_lds_dwordx4 v[220:221], off
.Lmy_sk_11_1:
	s_cmp_lg_u32 s58, 1
	s_cbranch_scc1 .Lmy_rl_11_0
	s_waitcnt vmcnt(8)
	s_branch .Lmy_rj_11_0

.Lmy_rj_11_0:
	s_waitcnt lgkmcnt(0)
	s_barrier
	s_setprio 1
	s_waitcnt lgkmcnt(0)
	v_mfma_f32_16x16x32_bf16 v[124:127], v[148:151], v[188:191], 0
	v_mfma_f32_16x16x32_bf16 v[120:123], v[164:167], v[188:191], 0
	v_mfma_f32_16x16x32_bf16 v[108:111], v[148:151], v[196:199], 0
	v_mfma_f32_16x16x32_bf16 v[104:107], v[164:167], v[196:199], 0
	v_mfma_f32_16x16x32_bf16 v[92:95], v[148:151], v[204:207], 0
	v_mfma_f32_16x16x32_bf16 v[88:91], v[164:167], v[204:207], 0
	v_mfma_f32_16x16x32_bf16 v[76:79], v[148:151], v[212:215], 0
	v_mfma_f32_16x16x32_bf16 v[72:75], v[164:167], v[212:215], 0
	v_mfma_f32_16x16x32_bf16 v[124:127], v[160:163], v[192:195], v[124:127]
	v_mfma_f32_16x16x32_bf16 v[120:123], v[168:171], v[192:195], v[120:123]
	v_mfma_f32_16x16x32_bf16 v[108:111], v[160:163], v[200:203], v[108:111]
	v_mfma_f32_16x16x32_bf16 v[104:107], v[168:171], v[200:203], v[104:107]
	v_mfma_f32_16x16x32_bf16 v[92:95], v[160:163], v[208:211], v[92:95]
	v_mfma_f32_16x16x32_bf16 v[88:91], v[168:171], v[208:211], v[88:91]
	v_mfma_f32_16x16x32_bf16 v[76:79], v[160:163], v[216:219], v[76:79]
	v_mfma_f32_16x16x32_bf16 v[72:75], v[168:171], v[216:219], v[72:75]
	s_setprio 0
	s_setprio 1
	v_mfma_f32_16x16x32_bf16 v[116:119], v[172:175], v[188:191], 0
	v_mfma_f32_16x16x32_bf16 v[112:115], v[180:183], v[188:191], 0
	v_mfma_f32_16x16x32_bf16 v[100:103], v[172:175], v[196:199], 0
	v_mfma_f32_16x16x32_bf16 v[96:99], v[180:183], v[196:199], 0
	v_mfma_f32_16x16x32_bf16 v[84:87], v[172:175], v[204:207], 0
	v_mfma_f32_16x16x32_bf16 v[80:83], v[180:183], v[204:207], 0
	v_mfma_f32_16x16x32_bf16 v[68:71], v[172:175], v[212:215], 0
	v_mfma_f32_16x16x32_bf16 v[64:67], v[180:183], v[212:215], 0
	v_mfma_f32_16x16x32_bf16 v[116:119], v[176:179], v[192:195], v[116:119]
	v_mfma_f32_16x16x32_bf16 v[112:115], v[184:187], v[192:195], v[112:115]
	v_mfma_f32_16x16x32_bf16 v[100:103], v[176:179], v[200:203], v[100:103]
	v_mfma_f32_16x16x32_bf16 v[96:99], v[184:187], v[200:203], v[96:99]
	v_mfma_f32_16x16x32_bf16 v[84:87], v[176:179], v[208:211], v[84:87]
	v_mfma_f32_16x16x32_bf16 v[80:83], v[184:187], v[208:211], v[80:83]
	v_mfma_f32_16x16x32_bf16 v[68:71], v[176:179], v[216:219], v[68:71]
	v_mfma_f32_16x16x32_bf16 v[64:67], v[184:187], v[216:219], v[64:67]
	s_setprio 0
	s_barrier
	s_add_i32 s34, s56, s41
	v_lshl_add_u64 v[220:221], s[36:37], 0, v[134:135]
	s_mov_b32 m0, s34
	ds_read_b128 v[188:191], v157 offset:16384
	ds_read_b128 v[192:195], v157 offset:17408
	ds_read_b128 v[196:199], v157 offset:18432
	ds_read_b128 v[200:203], v157 offset:19456
	ds_read_b128 v[204:207], v157 offset:20480
	ds_read_b128 v[208:211], v157 offset:21504
	ds_read_b128 v[212:215], v157 offset:22528
	ds_read_b128 v[216:219], v157 offset:23552
	global_load_lds_dwordx4 v[220:221], off
	s_add_i32 m0, s34, 0x2000
	s_add_u32 s34, s36, 0xb0000
	v_lshl_add_u64 v[222:223], s[36:37], 0, v[138:139]
	s_addc_u32 s35, s37, 0
	s_add_i32 s65, s57, s41
	global_load_lds_dwordx4 v[222:223], off
	v_lshl_add_u64 v[224:225], s[34:35], 0, v[134:135]
	s_mov_b32 m0, s65
	v_lshl_add_u64 v[226:227], s[38:39], 0, v[136:137]
	global_load_lds_dwordx4 v[224:225], off
	v_lshl_add_u64 v[224:225], s[34:35], 0, v[138:139]
	s_add_i32 m0, s65, 0x2000
	s_nop 0
	global_load_lds_dwordx4 v[224:225], off
	v_lshl_add_u64 v[224:225], s[38:39], 0, v[132:133]
	s_mov_b32 m0, s42
	s_nop 0
	global_load_lds_dwordx4 v[224:225], off
	s_mov_b32 m0, s43
	s_nop 0
	global_load_lds_dwordx4 v[226:227], off
	s_cmp_lg_u32 s58, 1
	s_cbranch_scc1 .Lmy_rl_11_1
	s_waitcnt vmcnt(8)
	s_branch .Lmy_rj_11_1

.Lmy_rj_11_1:
	s_waitcnt lgkmcnt(0)
	s_barrier
	s_setprio 1
	s_waitcnt lgkmcnt(0)
	v_mfma_f32_16x16x32_bf16 v[60:63], v[148:151], v[188:191], 0
	v_mfma_f32_16x16x32_bf16 v[56:59], v[164:167], v[188:191], 0
	v_mfma_f32_16x16x32_bf16 v[44:47], v[148:151], v[196:199], 0
	v_mfma_f32_16x16x32_bf16 v[40:43], v[164:167], v[196:199], 0
	v_mfma_f32_16x16x32_bf16 v[28:31], v[148:151], v[204:207], 0
	v_mfma_f32_16x16x32_bf16 v[24:27], v[164:167], v[204:207], 0
	v_mfma_f32_16x16x32_bf16 v[12:15], v[148:151], v[212:215], 0
	v_mfma_f32_16x16x32_bf16 v[8:11], v[164:167], v[212:215], 0
	v_mfma_f32_16x16x32_bf16 v[60:63], v[160:163], v[192:195], v[60:63]
	v_mfma_f32_16x16x32_bf16 v[56:59], v[168:171], v[192:195], v[56:59]
	v_mfma_f32_16x16x32_bf16 v[44:47], v[160:163], v[200:203], v[44:47]
	v_mfma_f32_16x16x32_bf16 v[40:43], v[168:171], v[200:203], v[40:43]
	v_mfma_f32_16x16x32_bf16 v[28:31], v[160:163], v[208:211], v[28:31]
	v_mfma_f32_16x16x32_bf16 v[24:27], v[168:171], v[208:211], v[24:27]
	v_mfma_f32_16x16x32_bf16 v[12:15], v[160:163], v[216:219], v[12:15]
	v_mfma_f32_16x16x32_bf16 v[8:11], v[168:171], v[216:219], v[8:11]
	s_setprio 0
	s_setprio 1
	v_mfma_f32_16x16x32_bf16 v[52:55], v[172:175], v[188:191], 0
	v_mfma_f32_16x16x32_bf16 v[48:51], v[180:183], v[188:191], 0
	v_mfma_f32_16x16x32_bf16 v[36:39], v[172:175], v[196:199], 0
	v_mfma_f32_16x16x32_bf16 v[32:35], v[180:183], v[196:199], 0
	v_mfma_f32_16x16x32_bf16 v[20:23], v[172:175], v[204:207], 0
	v_mfma_f32_16x16x32_bf16 v[16:19], v[180:183], v[204:207], 0
	v_mfma_f32_16x16x32_bf16 v[4:7], v[172:175], v[212:215], 0
	v_mfma_f32_16x16x32_bf16 v[0:3], v[180:183], v[212:215], 0
	v_mfma_f32_16x16x32_bf16 v[52:55], v[176:179], v[192:195], v[52:55]
	v_mfma_f32_16x16x32_bf16 v[48:51], v[184:187], v[192:195], v[48:51]
	v_mfma_f32_16x16x32_bf16 v[36:39], v[176:179], v[200:203], v[36:39]
	v_mfma_f32_16x16x32_bf16 v[32:35], v[184:187], v[200:203], v[32:35]
	v_mfma_f32_16x16x32_bf16 v[20:23], v[176:179], v[208:211], v[20:23]
	v_mfma_f32_16x16x32_bf16 v[16:19], v[184:187], v[208:211], v[16:19]
	v_mfma_f32_16x16x32_bf16 v[4:7], v[176:179], v[216:219], v[4:7]
	v_mfma_f32_16x16x32_bf16 v[0:3], v[184:187], v[216:219], v[0:3]
	s_setprio 0
	s_barrier
	s_add_i32 s65, 0, 0x18000
	v_add_u32_e32 v159, s65, v152
	s_add_i32 s66, 0, 0x1c000
	ds_read_b128 v[148:151], v159
	ds_read_b128 v[160:163], v159 offset:1024
	ds_read_b128 v[164:167], v159 offset:2048
	ds_read_b128 v[168:171], v159 offset:3072
	v_add_u32_e32 v159, s66, v152
	ds_read_b128 v[172:175], v159
	ds_read_b128 v[176:179], v159 offset:1024
	ds_read_b128 v[180:183], v159 offset:2048
	ds_read_b128 v[184:187], v159 offset:3072
	s_add_u32 s34, s38, 0xb0000
	s_addc_u32 s35, s39, 0
	s_mov_b32 m0, s48
	v_lshl_add_u64 v[228:229], s[34:35], 0, v[132:133]
	ds_read_b128 v[188:191], v157 offset:32768
	ds_read_b128 v[192:195], v157 offset:33792
	ds_read_b128 v[196:199], v157 offset:34816
	ds_read_b128 v[200:203], v157 offset:35840
	ds_read_b128 v[204:207], v157 offset:36864
	ds_read_b128 v[208:211], v157 offset:37888
	ds_read_b128 v[212:215], v157 offset:38912
	ds_read_b128 v[216:219], v157 offset:39936
	global_load_lds_dwordx4 v[228:229], off
	v_lshl_add_u64 v[228:229], s[34:35], 0, v[136:137]
	s_mov_b32 m0, s49
	s_nop 0
	global_load_lds_dwordx4 v[228:229], off
	s_cmp_lg_u32 s58, 1
	s_cbranch_scc1 .Lmy_rl_11_2
	s_waitcnt vmcnt(8)
	s_branch .Lmy_rj_11_2

.Lmy_rj_11_2:
	s_waitcnt lgkmcnt(0)
	s_barrier
	s_setprio 1
	s_waitcnt lgkmcnt(0)
	v_mfma_f32_16x16x32_bf16 v[124:127], v[148:151], v[188:191], v[124:127]
	v_mfma_f32_16x16x32_bf16 v[120:123], v[164:167], v[188:191], v[120:123]
	v_mfma_f32_16x16x32_bf16 v[108:111], v[148:151], v[196:199], v[108:111]
	v_mfma_f32_16x16x32_bf16 v[104:107], v[164:167], v[196:199], v[104:107]
	v_mfma_f32_16x16x32_bf16 v[92:95], v[148:151], v[204:207], v[92:95]
	v_mfma_f32_16x16x32_bf16 v[88:91], v[164:167], v[204:207], v[88:91]
	v_mfma_f32_16x16x32_bf16 v[76:79], v[148:151], v[212:215], v[76:79]
	v_mfma_f32_16x16x32_bf16 v[72:75], v[164:167], v[212:215], v[72:75]
	v_mfma_f32_16x16x32_bf16 v[124:127], v[160:163], v[192:195], v[124:127]
	v_mfma_f32_16x16x32_bf16 v[120:123], v[168:171], v[192:195], v[120:123]
	v_mfma_f32_16x16x32_bf16 v[108:111], v[160:163], v[200:203], v[108:111]
	v_mfma_f32_16x16x32_bf16 v[104:107], v[168:171], v[200:203], v[104:107]
	v_mfma_f32_16x16x32_bf16 v[92:95], v[160:163], v[208:211], v[92:95]
	v_mfma_f32_16x16x32_bf16 v[88:91], v[168:171], v[208:211], v[88:91]
	v_mfma_f32_16x16x32_bf16 v[76:79], v[160:163], v[216:219], v[76:79]
	v_mfma_f32_16x16x32_bf16 v[72:75], v[168:171], v[216:219], v[72:75]
	s_setprio 0
	s_setprio 1
	v_mfma_f32_16x16x32_bf16 v[116:119], v[172:175], v[188:191], v[116:119]
	v_mfma_f32_16x16x32_bf16 v[112:115], v[180:183], v[188:191], v[112:115]
	v_mfma_f32_16x16x32_bf16 v[100:103], v[172:175], v[196:199], v[100:103]
	v_mfma_f32_16x16x32_bf16 v[96:99], v[180:183], v[196:199], v[96:99]
	v_mfma_f32_16x16x32_bf16 v[84:87], v[172:175], v[204:207], v[84:87]
	v_mfma_f32_16x16x32_bf16 v[80:83], v[180:183], v[204:207], v[80:83]
	v_mfma_f32_16x16x32_bf16 v[68:71], v[172:175], v[212:215], v[68:71]
	v_mfma_f32_16x16x32_bf16 v[64:67], v[180:183], v[212:215], v[64:67]
	v_mfma_f32_16x16x32_bf16 v[116:119], v[176:179], v[192:195], v[116:119]
	v_mfma_f32_16x16x32_bf16 v[112:115], v[184:187], v[192:195], v[112:115]
	v_mfma_f32_16x16x32_bf16 v[100:103], v[176:179], v[200:203], v[100:103]
	v_mfma_f32_16x16x32_bf16 v[96:99], v[184:187], v[200:203], v[96:99]
	v_mfma_f32_16x16x32_bf16 v[84:87], v[176:179], v[208:211], v[84:87]
	v_mfma_f32_16x16x32_bf16 v[80:83], v[184:187], v[208:211], v[80:83]
	v_mfma_f32_16x16x32_bf16 v[68:71], v[176:179], v[216:219], v[68:71]
	v_mfma_f32_16x16x32_bf16 v[64:67], v[184:187], v[216:219], v[64:67]
	s_setprio 0
	s_barrier
	s_add_i32 s34, s65, s41
	v_lshl_add_u64 v[220:221], v[220:221], 0, s[22:23]
	s_mov_b32 m0, s34
	ds_read_b128 v[188:191], v157 offset:49152
	ds_read_b128 v[192:195], v157 offset:50176
	ds_read_b128 v[196:199], v157 offset:51200
	ds_read_b128 v[200:203], v157 offset:52224
	ds_read_b128 v[204:207], v157 offset:53248
	ds_read_b128 v[208:211], v157 offset:54272
	ds_read_b128 v[212:215], v157 offset:55296
	ds_read_b128 v[216:219], v157 offset:56320
	global_load_lds_dwordx4 v[220:221], off
	s_add_i32 m0, s34, 0x2000
	s_add_u32 s34, s36, 0xb0080
	v_lshl_add_u64 v[220:221], v[222:223], 0, s[22:23]
	s_addc_u32 s35, s37, 0
	s_add_i32 s36, s66, s41
	global_load_lds_dwordx4 v[220:221], off
	v_lshl_add_u64 v[220:221], s[34:35], 0, v[134:135]
	s_mov_b32 m0, s36
	s_nop 0
	global_load_lds_dwordx4 v[220:221], off
	v_lshl_add_u64 v[220:221], s[34:35], 0, v[138:139]
	s_add_i32 m0, s36, 0x2000
	s_nop 0
	global_load_lds_dwordx4 v[220:221], off
	v_lshl_add_u64 v[220:221], v[224:225], 0, s[22:23]
	s_mov_b32 m0, s51
	s_nop 0
	global_load_lds_dwordx4 v[220:221], off
	v_lshl_add_u64 v[220:221], v[226:227], 0, s[22:23]
	s_mov_b32 m0, s52
	s_nop 0
	global_load_lds_dwordx4 v[220:221], off
	s_waitcnt vmcnt(8)
	s_waitcnt lgkmcnt(0)
	s_barrier
	s_setprio 1
	s_waitcnt lgkmcnt(0)
	v_mfma_f32_16x16x32_bf16 v[60:63], v[148:151], v[188:191], v[60:63]
	v_mfma_f32_16x16x32_bf16 v[56:59], v[164:167], v[188:191], v[56:59]
	v_mfma_f32_16x16x32_bf16 v[44:47], v[148:151], v[196:199], v[44:47]
	v_mfma_f32_16x16x32_bf16 v[40:43], v[164:167], v[196:199], v[40:43]
	v_mfma_f32_16x16x32_bf16 v[28:31], v[148:151], v[204:207], v[28:31]
	v_mfma_f32_16x16x32_bf16 v[24:27], v[164:167], v[204:207], v[24:27]
	v_mfma_f32_16x16x32_bf16 v[12:15], v[148:151], v[212:215], v[12:15]
	v_mfma_f32_16x16x32_bf16 v[8:11], v[164:167], v[212:215], v[8:11]
	v_mfma_f32_16x16x32_bf16 v[60:63], v[160:163], v[192:195], v[60:63]
	v_mfma_f32_16x16x32_bf16 v[56:59], v[168:171], v[192:195], v[56:59]
	v_mfma_f32_16x16x32_bf16 v[44:47], v[160:163], v[200:203], v[44:47]
	v_mfma_f32_16x16x32_bf16 v[40:43], v[168:171], v[200:203], v[40:43]
	v_mfma_f32_16x16x32_bf16 v[28:31], v[160:163], v[208:211], v[28:31]
	v_mfma_f32_16x16x32_bf16 v[24:27], v[168:171], v[208:211], v[24:27]
	v_mfma_f32_16x16x32_bf16 v[12:15], v[160:163], v[216:219], v[12:15]
	v_mfma_f32_16x16x32_bf16 v[8:11], v[168:171], v[216:219], v[8:11]
	s_setprio 0
	s_setprio 1
	v_mfma_f32_16x16x32_bf16 v[52:55], v[172:175], v[188:191], v[52:55]
	v_mfma_f32_16x16x32_bf16 v[48:51], v[180:183], v[188:191], v[48:51]
	v_mfma_f32_16x16x32_bf16 v[36:39], v[172:175], v[196:199], v[36:39]
	v_mfma_f32_16x16x32_bf16 v[32:35], v[180:183], v[196:199], v[32:35]
	v_mfma_f32_16x16x32_bf16 v[20:23], v[172:175], v[204:207], v[20:23]
	v_mfma_f32_16x16x32_bf16 v[16:19], v[180:183], v[204:207], v[16:19]
	v_mfma_f32_16x16x32_bf16 v[4:7], v[172:175], v[212:215], v[4:7]
	v_mfma_f32_16x16x32_bf16 v[0:3], v[180:183], v[212:215], v[0:3]
	v_mfma_f32_16x16x32_bf16 v[52:55], v[176:179], v[192:195], v[52:55]
	v_mfma_f32_16x16x32_bf16 v[48:51], v[184:187], v[192:195], v[48:51]
	v_mfma_f32_16x16x32_bf16 v[36:39], v[176:179], v[200:203], v[36:39]
	v_mfma_f32_16x16x32_bf16 v[32:35], v[184:187], v[200:203], v[32:35]
	v_mfma_f32_16x16x32_bf16 v[20:23], v[176:179], v[208:211], v[20:23]
	v_mfma_f32_16x16x32_bf16 v[16:19], v[184:187], v[208:211], v[16:19]
	v_mfma_f32_16x16x32_bf16 v[4:7], v[176:179], v[216:219], v[4:7]
	v_mfma_f32_16x16x32_bf16 v[0:3], v[184:187], v[216:219], v[0:3]
	s_setprio 0
	s_barrier
	s_add_i32 s64, s64, 2
	s_add_u32 s30, s30, 0x100
	s_addc_u32 s31, s31, 0
	s_add_u32 s13, s13, 0x100
	s_addc_u32 s63, s63, 0

.Lmy_nobar_11:
	s_add_i32 s64, s64, 2
	s_add_u32 s30, s30, 0x100
	s_addc_u32 s31, s31, 0
	s_add_u32 s13, s13, 0x100
	s_addc_u32 s63, s63, 0
	s_cmp_gt_u32 s64, 41
	s_cbranch_scc0 .LBB0_1145
	s_add_u32 s100, s0, 0xb0080
	s_addc_u32 s101, s1, 0
	s_add_i32 m0, s42, 0xc000
	v_lshl_add_u64 v[220:221], s[100:101], 0, v[140:141]
	global_load_lds_dwordx4 v[220:221], off
	s_add_i32 m0, s42, 0xe000
	v_lshl_add_u64 v[220:221], s[100:101], 0, v[142:143]
	global_load_lds_dwordx4 v[220:221], off
	s_and_b64 vcc, exec, s[26:27]
	s_cbranch_vccz .LBB0_1148
	s_nop 0

.Lmy_nobar2_12:
	ds_read_b128 v[148:151], v155
	ds_read_b128 v[160:163], v155 offset:1024
	ds_read_b128 v[164:167], v155 offset:2048
	ds_read_b128 v[168:171], v155 offset:3072
	ds_read_b128 v[172:175], v157
	ds_read_b128 v[176:179], v157 offset:1024
	ds_read_b128 v[180:183], v157 offset:2048
	ds_read_b128 v[184:187], v157 offset:3072
	s_add_u32 s34, s36, 0xfffc0080
	s_addc_u32 s35, s37, -1
	s_cmp_eq_u32 s77, 12
	s_cselect_b32 s41, s23, s35
	s_cselect_b32 s40, s64, s34
	s_cselect_b32 s39, s11, s67
	s_cselect_b32 s38, s65, s66
	v_lshl_add_u64 v[220:221], s[36:37], 0, v[140:141]
	s_add_i32 m0, s31, 0xc000
	ds_read_b128 v[188:191], v158
	ds_read_b128 v[192:195], v158 offset:1024
	ds_read_b128 v[196:199], v158 offset:2048
	ds_read_b128 v[200:203], v158 offset:3072
	ds_read_b128 v[204:207], v158 offset:4096
	ds_read_b128 v[208:211], v158 offset:5120
	ds_read_b128 v[212:215], v158 offset:6144
	ds_read_b128 v[216:219], v158 offset:7168
	s_cmp_lg_u32 s58, 1
	s_cbranch_scc1 .Lmy_sk_12_0
	global_load_lds_dwordx4 v[220:221], off
.Lmy_sk_12_0:
	v_lshl_add_u64 v[220:221], s[36:37], 0, v[142:143]
	s_add_i32 m0, s31, 0xe000
	s_nop 0
	s_cmp_lg_u32 s58, 1
	s_cbranch_scc1 .Lmy_sk_12_1
	global_load_lds_dwordx4 v[220:221], off

.Lmy_rj_12_0:
	s_waitcnt lgkmcnt(0)
	s_barrier
	s_setprio 1
	s_waitcnt lgkmcnt(0)
	v_mfma_f32_16x16x32_bf16 v[124:127], v[148:151], v[188:191], 0
	v_mfma_f32_16x16x32_bf16 v[120:123], v[164:167], v[188:191], 0
	v_mfma_f32_16x16x32_bf16 v[108:111], v[148:151], v[196:199], 0
	v_mfma_f32_16x16x32_bf16 v[104:107], v[164:167], v[196:199], 0
	v_mfma_f32_16x16x32_bf16 v[92:95], v[148:151], v[204:207], 0
	v_mfma_f32_16x16x32_bf16 v[88:91], v[164:167], v[204:207], 0
	v_mfma_f32_16x16x32_bf16 v[76:79], v[148:151], v[212:215], 0
	v_mfma_f32_16x16x32_bf16 v[72:75], v[164:167], v[212:215], 0
	v_mfma_f32_16x16x32_bf16 v[124:127], v[160:163], v[192:195], v[124:127]
	v_mfma_f32_16x16x32_bf16 v[120:123], v[168:171], v[192:195], v[120:123]
	v_mfma_f32_16x16x32_bf16 v[108:111], v[160:163], v[200:203], v[108:111]
	v_mfma_f32_16x16x32_bf16 v[104:107], v[168:171], v[200:203], v[104:107]
	v_mfma_f32_16x16x32_bf16 v[92:95], v[160:163], v[208:211], v[92:95]
	v_mfma_f32_16x16x32_bf16 v[88:91], v[168:171], v[208:211], v[88:91]
	v_mfma_f32_16x16x32_bf16 v[76:79], v[160:163], v[216:219], v[76:79]
	v_mfma_f32_16x16x32_bf16 v[72:75], v[168:171], v[216:219], v[72:75]
	s_setprio 0
	s_setprio 1
	v_mfma_f32_16x16x32_bf16 v[116:119], v[172:175], v[188:191], 0
	v_mfma_f32_16x16x32_bf16 v[112:115], v[180:183], v[188:191], 0
	v_mfma_f32_16x16x32_bf16 v[100:103], v[172:175], v[196:199], 0
	v_mfma_f32_16x16x32_bf16 v[96:99], v[180:183], v[196:199], 0
	v_mfma_f32_16x16x32_bf16 v[84:87], v[172:175], v[204:207], 0
	v_mfma_f32_16x16x32_bf16 v[80:83], v[180:183], v[204:207], 0
	v_mfma_f32_16x16x32_bf16 v[68:71], v[172:175], v[212:215], 0
	v_mfma_f32_16x16x32_bf16 v[64:67], v[180:183], v[212:215], 0
	v_mfma_f32_16x16x32_bf16 v[116:119], v[176:179], v[192:195], v[116:119]
	v_mfma_f32_16x16x32_bf16 v[112:115], v[184:187], v[192:195], v[112:115]
	v_mfma_f32_16x16x32_bf16 v[100:103], v[176:179], v[200:203], v[100:103]
	v_mfma_f32_16x16x32_bf16 v[96:99], v[184:187], v[200:203], v[96:99]
	v_mfma_f32_16x16x32_bf16 v[84:87], v[176:179], v[208:211], v[84:87]
	v_mfma_f32_16x16x32_bf16 v[80:83], v[184:187], v[208:211], v[80:83]
	v_mfma_f32_16x16x32_bf16 v[68:71], v[176:179], v[216:219], v[68:71]
	v_mfma_f32_16x16x32_bf16 v[64:67], v[184:187], v[216:219], v[64:67]
	s_setprio 0
	s_barrier
	s_add_i32 s34, s55, s48
	v_lshl_add_u64 v[220:221], s[38:39], 0, v[136:137]
	s_mov_b32 m0, s34
	ds_read_b128 v[188:191], v158 offset:16384
	ds_read_b128 v[192:195], v158 offset:17408
	ds_read_b128 v[196:199], v158 offset:18432
	ds_read_b128 v[200:203], v158 offset:19456
	ds_read_b128 v[204:207], v158 offset:20480
	ds_read_b128 v[208:211], v158 offset:21504
	ds_read_b128 v[212:215], v158 offset:22528
	ds_read_b128 v[216:219], v158 offset:23552
	global_load_lds_dwordx4 v[220:221], off
	s_add_i32 m0, s34, 0x2000
	s_add_u32 s34, s38, 0x40000
	v_lshl_add_u64 v[222:223], s[38:39], 0, v[132:133]
	s_addc_u32 s35, s39, 0
	s_add_i32 s79, s56, s48
	global_load_lds_dwordx4 v[222:223], off
	v_lshl_add_u64 v[224:225], s[34:35], 0, v[136:137]
	s_mov_b32 m0, s79
	v_lshl_add_u64 v[226:227], s[40:41], 0, v[134:135]
	global_load_lds_dwordx4 v[224:225], off
	v_lshl_add_u64 v[224:225], s[34:35], 0, v[132:133]
	s_add_i32 m0, s79, 0x2000
	s_nop 0
	global_load_lds_dwordx4 v[224:225], off
	v_lshl_add_u64 v[224:225], s[40:41], 0, v[138:139]
	s_mov_b32 m0, s31
	s_nop 0
	global_load_lds_dwordx4 v[224:225], off
	s_mov_b32 m0, s52
	s_nop 0
	global_load_lds_dwordx4 v[226:227], off
	s_cmp_lg_u32 s58, 1
	s_cbranch_scc1 .Lmy_rl_12_1
	s_waitcnt vmcnt(8)
	s_branch .Lmy_rj_12_1

.Lmy_rj_12_1:
	s_waitcnt lgkmcnt(0)
	s_barrier
	s_setprio 1
	s_waitcnt lgkmcnt(0)
	v_mfma_f32_16x16x32_bf16 v[60:63], v[148:151], v[188:191], 0
	v_mfma_f32_16x16x32_bf16 v[56:59], v[164:167], v[188:191], 0
	v_mfma_f32_16x16x32_bf16 v[44:47], v[148:151], v[196:199], 0
	v_mfma_f32_16x16x32_bf16 v[40:43], v[164:167], v[196:199], 0
	v_mfma_f32_16x16x32_bf16 v[28:31], v[148:151], v[204:207], 0
	v_mfma_f32_16x16x32_bf16 v[24:27], v[164:167], v[204:207], 0
	v_mfma_f32_16x16x32_bf16 v[12:15], v[148:151], v[212:215], 0
	v_mfma_f32_16x16x32_bf16 v[8:11], v[164:167], v[212:215], 0
	v_mfma_f32_16x16x32_bf16 v[60:63], v[160:163], v[192:195], v[60:63]
	v_mfma_f32_16x16x32_bf16 v[56:59], v[168:171], v[192:195], v[56:59]
	v_mfma_f32_16x16x32_bf16 v[44:47], v[160:163], v[200:203], v[44:47]
	v_mfma_f32_16x16x32_bf16 v[40:43], v[168:171], v[200:203], v[40:43]
	v_mfma_f32_16x16x32_bf16 v[28:31], v[160:163], v[208:211], v[28:31]
	v_mfma_f32_16x16x32_bf16 v[24:27], v[168:171], v[208:211], v[24:27]
	v_mfma_f32_16x16x32_bf16 v[12:15], v[160:163], v[216:219], v[12:15]
	v_mfma_f32_16x16x32_bf16 v[8:11], v[168:171], v[216:219], v[8:11]
	s_setprio 0
	s_setprio 1
	v_mfma_f32_16x16x32_bf16 v[52:55], v[172:175], v[188:191], 0
	v_mfma_f32_16x16x32_bf16 v[48:51], v[180:183], v[188:191], 0
	v_mfma_f32_16x16x32_bf16 v[36:39], v[172:175], v[196:199], 0
	v_mfma_f32_16x16x32_bf16 v[32:35], v[180:183], v[196:199], 0
	v_mfma_f32_16x16x32_bf16 v[20:23], v[172:175], v[204:207], 0
	v_mfma_f32_16x16x32_bf16 v[16:19], v[180:183], v[204:207], 0
	v_mfma_f32_16x16x32_bf16 v[4:7], v[172:175], v[212:215], 0
	v_mfma_f32_16x16x32_bf16 v[0:3], v[180:183], v[212:215], 0
	v_mfma_f32_16x16x32_bf16 v[52:55], v[176:179], v[192:195], v[52:55]
	v_mfma_f32_16x16x32_bf16 v[48:51], v[184:187], v[192:195], v[48:51]
	v_mfma_f32_16x16x32_bf16 v[36:39], v[176:179], v[200:203], v[36:39]
	v_mfma_f32_16x16x32_bf16 v[32:35], v[184:187], v[200:203], v[32:35]
	v_mfma_f32_16x16x32_bf16 v[20:23], v[176:179], v[208:211], v[20:23]
	v_mfma_f32_16x16x32_bf16 v[16:19], v[184:187], v[208:211], v[16:19]
	v_mfma_f32_16x16x32_bf16 v[4:7], v[176:179], v[216:219], v[4:7]
	v_mfma_f32_16x16x32_bf16 v[0:3], v[184:187], v[216:219], v[0:3]
	s_setprio 0
	s_barrier
	s_add_i32 s79, 0, 0x18000
	v_add_u32_e32 v159, s79, v152
	s_add_i32 s81, 0, 0x1c000
	ds_read_b128 v[148:151], v159
	ds_read_b128 v[160:163], v159 offset:1024
	ds_read_b128 v[164:167], v159 offset:2048
	ds_read_b128 v[168:171], v159 offset:3072
	v_add_u32_e32 v159, s81, v152
	ds_read_b128 v[172:175], v159
	ds_read_b128 v[176:179], v159 offset:1024
	ds_read_b128 v[180:183], v159 offset:2048
	ds_read_b128 v[184:187], v159 offset:3072
	s_add_u32 s34, s40, 0x40000
	s_addc_u32 s35, s41, 0
	s_mov_b32 m0, s53
	v_lshl_add_u64 v[228:229], s[34:35], 0, v[138:139]
	ds_read_b128 v[188:191], v158 offset:32768
	ds_read_b128 v[192:195], v158 offset:33792
	ds_read_b128 v[196:199], v158 offset:34816
	ds_read_b128 v[200:203], v158 offset:35840
	ds_read_b128 v[204:207], v158 offset:36864
	ds_read_b128 v[208:211], v158 offset:37888
	ds_read_b128 v[212:215], v158 offset:38912
	ds_read_b128 v[216:219], v158 offset:39936
	global_load_lds_dwordx4 v[228:229], off
	v_lshl_add_u64 v[228:229], s[34:35], 0, v[134:135]
	s_mov_b32 m0, s54
	s_nop 0
	global_load_lds_dwordx4 v[228:229], off
	s_cmp_lg_u32 s58, 1
	s_cbranch_scc1 .Lmy_rl_12_2
	s_waitcnt vmcnt(8)
	s_branch .Lmy_rj_12_2

.Lmy_rj_12_2:
	s_waitcnt lgkmcnt(0)
	s_barrier
	s_setprio 1
	s_waitcnt lgkmcnt(0)
	v_mfma_f32_16x16x32_bf16 v[124:127], v[148:151], v[188:191], v[124:127]
	v_mfma_f32_16x16x32_bf16 v[120:123], v[164:167], v[188:191], v[120:123]
	v_mfma_f32_16x16x32_bf16 v[108:111], v[148:151], v[196:199], v[108:111]
	v_mfma_f32_16x16x32_bf16 v[104:107], v[164:167], v[196:199], v[104:107]
	v_mfma_f32_16x16x32_bf16 v[92:95], v[148:151], v[204:207], v[92:95]
	v_mfma_f32_16x16x32_bf16 v[88:91], v[164:167], v[204:207], v[88:91]
	v_mfma_f32_16x16x32_bf16 v[76:79], v[148:151], v[212:215], v[76:79]
	v_mfma_f32_16x16x32_bf16 v[72:75], v[164:167], v[212:215], v[72:75]
	v_mfma_f32_16x16x32_bf16 v[124:127], v[160:163], v[192:195], v[124:127]
	v_mfma_f32_16x16x32_bf16 v[120:123], v[168:171], v[192:195], v[120:123]
	v_mfma_f32_16x16x32_bf16 v[108:111], v[160:163], v[200:203], v[108:111]
	v_mfma_f32_16x16x32_bf16 v[104:107], v[168:171], v[200:203], v[104:107]
	v_mfma_f32_16x16x32_bf16 v[92:95], v[160:163], v[208:211], v[92:95]
	v_mfma_f32_16x16x32_bf16 v[88:91], v[168:171], v[208:211], v[88:91]
	v_mfma_f32_16x16x32_bf16 v[76:79], v[160:163], v[216:219], v[76:79]
	v_mfma_f32_16x16x32_bf16 v[72:75], v[168:171], v[216:219], v[72:75]
	s_setprio 0
	s_setprio 1
	v_mfma_f32_16x16x32_bf16 v[116:119], v[172:175], v[188:191], v[116:119]
	v_mfma_f32_16x16x32_bf16 v[112:115], v[180:183], v[188:191], v[112:115]
	v_mfma_f32_16x16x32_bf16 v[100:103], v[172:175], v[196:199], v[100:103]
	v_mfma_f32_16x16x32_bf16 v[96:99], v[180:183], v[196:199], v[96:99]
	v_mfma_f32_16x16x32_bf16 v[84:87], v[172:175], v[204:207], v[84:87]
	v_mfma_f32_16x16x32_bf16 v[80:83], v[180:183], v[204:207], v[80:83]
	v_mfma_f32_16x16x32_bf16 v[68:71], v[172:175], v[212:215], v[68:71]
	v_mfma_f32_16x16x32_bf16 v[64:67], v[180:183], v[212:215], v[64:67]
	v_mfma_f32_16x16x32_bf16 v[116:119], v[176:179], v[192:195], v[116:119]
	v_mfma_f32_16x16x32_bf16 v[112:115], v[184:187], v[192:195], v[112:115]
	v_mfma_f32_16x16x32_bf16 v[100:103], v[176:179], v[200:203], v[100:103]
	v_mfma_f32_16x16x32_bf16 v[96:99], v[184:187], v[200:203], v[96:99]
	v_mfma_f32_16x16x32_bf16 v[84:87], v[176:179], v[208:211], v[84:87]
	v_mfma_f32_16x16x32_bf16 v[80:83], v[184:187], v[208:211], v[80:83]
	v_mfma_f32_16x16x32_bf16 v[68:71], v[176:179], v[216:219], v[68:71]
	v_mfma_f32_16x16x32_bf16 v[64:67], v[184:187], v[216:219], v[64:67]
	s_setprio 0
	s_barrier
	s_add_i32 s34, s79, s48
	v_lshl_add_u64 v[220:221], v[220:221], 0, s[6:7]
	s_mov_b32 m0, s34
	ds_read_b128 v[188:191], v158 offset:49152
	ds_read_b128 v[192:195], v158 offset:50176
	ds_read_b128 v[196:199], v158 offset:51200
	ds_read_b128 v[200:203], v158 offset:52224
	ds_read_b128 v[204:207], v158 offset:53248
	ds_read_b128 v[208:211], v158 offset:54272
	ds_read_b128 v[212:215], v158 offset:55296
	ds_read_b128 v[216:219], v158 offset:56320
	global_load_lds_dwordx4 v[220:221], off
	s_add_i32 m0, s34, 0x2000
	s_add_u32 s34, s38, 0x40080
	v_lshl_add_u64 v[220:221], v[222:223], 0, s[6:7]
	s_addc_u32 s35, s39, 0
	s_add_i32 s38, s81, s48
	global_load_lds_dwordx4 v[220:221], off
	v_lshl_add_u64 v[220:221], s[34:35], 0, v[136:137]
	s_mov_b32 m0, s38
	s_nop 0
	global_load_lds_dwordx4 v[220:221], off
	v_lshl_add_u64 v[220:221], s[34:35], 0, v[132:133]
	s_add_i32 m0, s38, 0x2000
	s_nop 0
	global_load_lds_dwordx4 v[220:221], off
	v_lshl_add_u64 v[220:221], v[224:225], 0, s[6:7]
	s_mov_b32 m0, s12
	s_nop 0
	global_load_lds_dwordx4 v[220:221], off
	v_lshl_add_u64 v[220:221], v[226:227], 0, s[6:7]
	s_mov_b32 m0, s13
	s_nop 0
	global_load_lds_dwordx4 v[220:221], off
	s_waitcnt vmcnt(8)
	s_waitcnt lgkmcnt(0)
	s_barrier
	s_setprio 1
	s_waitcnt lgkmcnt(0)
	v_mfma_f32_16x16x32_bf16 v[60:63], v[148:151], v[188:191], v[60:63]
	v_mfma_f32_16x16x32_bf16 v[56:59], v[164:167], v[188:191], v[56:59]
	v_mfma_f32_16x16x32_bf16 v[44:47], v[148:151], v[196:199], v[44:47]
	v_mfma_f32_16x16x32_bf16 v[40:43], v[164:167], v[196:199], v[40:43]
	v_mfma_f32_16x16x32_bf16 v[28:31], v[148:151], v[204:207], v[28:31]
	v_mfma_f32_16x16x32_bf16 v[24:27], v[164:167], v[204:207], v[24:27]
	v_mfma_f32_16x16x32_bf16 v[12:15], v[148:151], v[212:215], v[12:15]
	v_mfma_f32_16x16x32_bf16 v[8:11], v[164:167], v[212:215], v[8:11]
	v_mfma_f32_16x16x32_bf16 v[60:63], v[160:163], v[192:195], v[60:63]
	v_mfma_f32_16x16x32_bf16 v[56:59], v[168:171], v[192:195], v[56:59]
	v_mfma_f32_16x16x32_bf16 v[44:47], v[160:163], v[200:203], v[44:47]
	v_mfma_f32_16x16x32_bf16 v[40:43], v[168:171], v[200:203], v[40:43]
	v_mfma_f32_16x16x32_bf16 v[28:31], v[160:163], v[208:211], v[28:31]
	v_mfma_f32_16x16x32_bf16 v[24:27], v[168:171], v[208:211], v[24:27]
	v_mfma_f32_16x16x32_bf16 v[12:15], v[160:163], v[216:219], v[12:15]
	v_mfma_f32_16x16x32_bf16 v[8:11], v[168:171], v[216:219], v[8:11]
	s_setprio 0
	s_setprio 1
	v_mfma_f32_16x16x32_bf16 v[52:55], v[172:175], v[188:191], v[52:55]
	v_mfma_f32_16x16x32_bf16 v[48:51], v[180:183], v[188:191], v[48:51]
	v_mfma_f32_16x16x32_bf16 v[36:39], v[172:175], v[196:199], v[36:39]
	v_mfma_f32_16x16x32_bf16 v[32:35], v[180:183], v[196:199], v[32:35]
	v_mfma_f32_16x16x32_bf16 v[20:23], v[172:175], v[204:207], v[20:23]
	v_mfma_f32_16x16x32_bf16 v[16:19], v[180:183], v[204:207], v[16:19]
	v_mfma_f32_16x16x32_bf16 v[4:7], v[172:175], v[212:215], v[4:7]
	v_mfma_f32_16x16x32_bf16 v[0:3], v[180:183], v[212:215], v[0:3]
	v_mfma_f32_16x16x32_bf16 v[52:55], v[176:179], v[192:195], v[52:55]
	v_mfma_f32_16x16x32_bf16 v[48:51], v[184:187], v[192:195], v[48:51]
	v_mfma_f32_16x16x32_bf16 v[36:39], v[176:179], v[200:203], v[36:39]
	v_mfma_f32_16x16x32_bf16 v[32:35], v[184:187], v[200:203], v[32:35]
	v_mfma_f32_16x16x32_bf16 v[20:23], v[176:179], v[208:211], v[20:23]
	v_mfma_f32_16x16x32_bf16 v[16:19], v[184:187], v[208:211], v[16:19]
	v_mfma_f32_16x16x32_bf16 v[4:7], v[176:179], v[216:219], v[4:7]
	v_mfma_f32_16x16x32_bf16 v[0:3], v[184:187], v[216:219], v[0:3]
	s_setprio 0
	s_barrier
	s_add_i32 s77, s77, 2
	s_add_u32 s36, s36, 0x100
	s_addc_u32 s37, s37, 0
	s_add_u32 s66, s66, 0x100
	s_addc_u32 s67, s67, 0

.Lmy_nobar2_16:
	ds_read_b128 v[146:149], v153
	ds_read_b128 v[158:161], v153 offset:1024
	ds_read_b128 v[162:165], v153 offset:2048
	ds_read_b128 v[166:169], v153 offset:3072
	ds_read_b128 v[170:173], v154
	ds_read_b128 v[174:177], v154 offset:1024
	ds_read_b128 v[178:181], v154 offset:2048
	ds_read_b128 v[182:185], v154 offset:3072
	s_add_u32 s34, s40, 0xfffc0080
	s_addc_u32 s35, s41, -1
	s_cmp_eq_u32 s62, 12
	s_cselect_b32 s45, s12, s35
	s_cselect_b32 s44, s13, s34
	s_cselect_b32 s43, s27, s61
	s_cselect_b32 s42, s29, s39
	v_lshl_add_u64 v[218:219], s[40:41], 0, v[138:139]
	s_add_i32 m0, s48, 0xc000
	ds_read_b128 v[186:189], v155
	ds_read_b128 v[190:193], v155 offset:1024
	ds_read_b128 v[194:197], v155 offset:2048
	ds_read_b128 v[198:201], v155 offset:3072
	ds_read_b128 v[202:205], v155 offset:4096
	ds_read_b128 v[206:209], v155 offset:5120
	ds_read_b128 v[210:213], v155 offset:6144
	ds_read_b128 v[214:217], v155 offset:7168
	s_cmp_lg_u32 s60, 1
	s_cbranch_scc1 .Lmy_sk_16_0
	global_load_lds_dwordx4 v[218:219], off
.Lmy_sk_16_0:
	v_lshl_add_u64 v[218:219], s[40:41], 0, v[140:141]
	s_add_i32 m0, s48, 0xe000
	s_nop 0
	s_cmp_lg_u32 s60, 1
	s_cbranch_scc1 .Lmy_sk_16_1
	global_load_lds_dwordx4 v[218:219], off
.Lmy_sk_16_1:
	s_cmp_lg_u32 s60, 1
	s_cbranch_scc1 .Lmy_rl_16_0
	s_waitcnt vmcnt(8)
	s_branch .Lmy_rj_16_0

.Lmy_rj_16_0:
	s_waitcnt lgkmcnt(0)
	s_barrier
	s_setprio 1
	s_waitcnt lgkmcnt(0)
	v_mfma_f32_16x16x32_bf16 v[124:127], v[146:149], v[186:189], 0
	v_mfma_f32_16x16x32_bf16 v[120:123], v[162:165], v[186:189], 0
	v_mfma_f32_16x16x32_bf16 v[108:111], v[146:149], v[194:197], 0
	v_mfma_f32_16x16x32_bf16 v[104:107], v[162:165], v[194:197], 0
	v_mfma_f32_16x16x32_bf16 v[92:95], v[146:149], v[202:205], 0
	v_mfma_f32_16x16x32_bf16 v[88:91], v[162:165], v[202:205], 0
	v_mfma_f32_16x16x32_bf16 v[76:79], v[146:149], v[210:213], 0
	v_mfma_f32_16x16x32_bf16 v[72:75], v[162:165], v[210:213], 0
	v_mfma_f32_16x16x32_bf16 v[124:127], v[158:161], v[190:193], v[124:127]
	v_mfma_f32_16x16x32_bf16 v[120:123], v[166:169], v[190:193], v[120:123]
	v_mfma_f32_16x16x32_bf16 v[108:111], v[158:161], v[198:201], v[108:111]
	v_mfma_f32_16x16x32_bf16 v[104:107], v[166:169], v[198:201], v[104:107]
	v_mfma_f32_16x16x32_bf16 v[92:95], v[158:161], v[206:209], v[92:95]
	v_mfma_f32_16x16x32_bf16 v[88:91], v[166:169], v[206:209], v[88:91]
	v_mfma_f32_16x16x32_bf16 v[76:79], v[158:161], v[214:217], v[76:79]
	v_mfma_f32_16x16x32_bf16 v[72:75], v[166:169], v[214:217], v[72:75]
	s_setprio 0
	s_setprio 1
	v_mfma_f32_16x16x32_bf16 v[116:119], v[170:173], v[186:189], 0
	v_mfma_f32_16x16x32_bf16 v[112:115], v[178:181], v[186:189], 0
	v_mfma_f32_16x16x32_bf16 v[100:103], v[170:173], v[194:197], 0
	v_mfma_f32_16x16x32_bf16 v[96:99], v[178:181], v[194:197], 0
	v_mfma_f32_16x16x32_bf16 v[84:87], v[170:173], v[202:205], 0
	v_mfma_f32_16x16x32_bf16 v[80:83], v[178:181], v[202:205], 0
	v_mfma_f32_16x16x32_bf16 v[68:71], v[170:173], v[210:213], 0
	v_mfma_f32_16x16x32_bf16 v[64:67], v[178:181], v[210:213], 0
	v_mfma_f32_16x16x32_bf16 v[116:119], v[174:177], v[190:193], v[116:119]
	v_mfma_f32_16x16x32_bf16 v[112:115], v[182:185], v[190:193], v[112:115]
	v_mfma_f32_16x16x32_bf16 v[100:103], v[174:177], v[198:201], v[100:103]
	v_mfma_f32_16x16x32_bf16 v[96:99], v[182:185], v[198:201], v[96:99]
	v_mfma_f32_16x16x32_bf16 v[84:87], v[174:177], v[206:209], v[84:87]
	v_mfma_f32_16x16x32_bf16 v[80:83], v[182:185], v[206:209], v[80:83]
	v_mfma_f32_16x16x32_bf16 v[68:71], v[174:177], v[214:217], v[68:71]
	v_mfma_f32_16x16x32_bf16 v[64:67], v[182:185], v[214:217], v[64:67]
	s_setprio 0
	s_barrier
	s_add_i32 s34, s58, s47
	v_lshl_add_u64 v[218:219], s[42:43], 0, v[132:133]
	s_mov_b32 m0, s34
	ds_read_b128 v[186:189], v155 offset:16384
	ds_read_b128 v[190:193], v155 offset:17408
	ds_read_b128 v[194:197], v155 offset:18432
	ds_read_b128 v[198:201], v155 offset:19456
	ds_read_b128 v[202:205], v155 offset:20480
	ds_read_b128 v[206:209], v155 offset:21504
	ds_read_b128 v[210:213], v155 offset:22528
	ds_read_b128 v[214:217], v155 offset:23552
	global_load_lds_dwordx4 v[218:219], off
	s_add_i32 m0, s34, 0x2000
	s_add_u32 s34, s42, 0x40000
	v_lshl_add_u64 v[220:221], s[42:43], 0, v[136:137]
	s_addc_u32 s35, s43, 0
	s_add_i32 s63, s59, s47
	global_load_lds_dwordx4 v[220:221], off
	v_lshl_add_u64 v[222:223], s[34:35], 0, v[132:133]
	s_mov_b32 m0, s63
	v_lshl_add_u64 v[224:225], s[44:45], 0, v[134:135]
	global_load_lds_dwordx4 v[222:223], off
	v_lshl_add_u64 v[222:223], s[34:35], 0, v[136:137]
	s_add_i32 m0, s63, 0x2000
	s_nop 0
	global_load_lds_dwordx4 v[222:223], off
	v_lshl_add_u64 v[222:223], s[44:45], 0, v[130:131]
	s_mov_b32 m0, s48
	s_nop 0
	global_load_lds_dwordx4 v[222:223], off
	s_mov_b32 m0, s49
	s_nop 0
	global_load_lds_dwordx4 v[224:225], off
	s_cmp_lg_u32 s60, 1
	s_cbranch_scc1 .Lmy_rl_16_1
	s_waitcnt vmcnt(8)
	s_branch .Lmy_rj_16_1

.Lmy_rj_16_1:
	s_waitcnt lgkmcnt(0)
	s_barrier
	s_setprio 1
	s_waitcnt lgkmcnt(0)
	v_mfma_f32_16x16x32_bf16 v[60:63], v[146:149], v[186:189], 0
	v_mfma_f32_16x16x32_bf16 v[56:59], v[162:165], v[186:189], 0
	v_mfma_f32_16x16x32_bf16 v[44:47], v[146:149], v[194:197], 0
	v_mfma_f32_16x16x32_bf16 v[40:43], v[162:165], v[194:197], 0
	v_mfma_f32_16x16x32_bf16 v[28:31], v[146:149], v[202:205], 0
	v_mfma_f32_16x16x32_bf16 v[24:27], v[162:165], v[202:205], 0
	v_mfma_f32_16x16x32_bf16 v[12:15], v[146:149], v[210:213], 0
	v_mfma_f32_16x16x32_bf16 v[8:11], v[162:165], v[210:213], 0
	v_mfma_f32_16x16x32_bf16 v[60:63], v[158:161], v[190:193], v[60:63]
	v_mfma_f32_16x16x32_bf16 v[56:59], v[166:169], v[190:193], v[56:59]
	v_mfma_f32_16x16x32_bf16 v[44:47], v[158:161], v[198:201], v[44:47]
	v_mfma_f32_16x16x32_bf16 v[40:43], v[166:169], v[198:201], v[40:43]
	v_mfma_f32_16x16x32_bf16 v[28:31], v[158:161], v[206:209], v[28:31]
	v_mfma_f32_16x16x32_bf16 v[24:27], v[166:169], v[206:209], v[24:27]
	v_mfma_f32_16x16x32_bf16 v[12:15], v[158:161], v[214:217], v[12:15]
	v_mfma_f32_16x16x32_bf16 v[8:11], v[166:169], v[214:217], v[8:11]
	s_setprio 0
	s_setprio 1
	v_mfma_f32_16x16x32_bf16 v[52:55], v[170:173], v[186:189], 0
	v_mfma_f32_16x16x32_bf16 v[48:51], v[178:181], v[186:189], 0
	v_mfma_f32_16x16x32_bf16 v[36:39], v[170:173], v[194:197], 0
	v_mfma_f32_16x16x32_bf16 v[32:35], v[178:181], v[194:197], 0
	v_mfma_f32_16x16x32_bf16 v[20:23], v[170:173], v[202:205], 0
	v_mfma_f32_16x16x32_bf16 v[16:19], v[178:181], v[202:205], 0
	v_mfma_f32_16x16x32_bf16 v[4:7], v[170:173], v[210:213], 0
	v_mfma_f32_16x16x32_bf16 v[0:3], v[178:181], v[210:213], 0
	v_mfma_f32_16x16x32_bf16 v[52:55], v[174:177], v[190:193], v[52:55]
	v_mfma_f32_16x16x32_bf16 v[48:51], v[182:185], v[190:193], v[48:51]
	v_mfma_f32_16x16x32_bf16 v[36:39], v[174:177], v[198:201], v[36:39]
	v_mfma_f32_16x16x32_bf16 v[32:35], v[182:185], v[198:201], v[32:35]
	v_mfma_f32_16x16x32_bf16 v[20:23], v[174:177], v[206:209], v[20:23]
	v_mfma_f32_16x16x32_bf16 v[16:19], v[182:185], v[206:209], v[16:19]
	v_mfma_f32_16x16x32_bf16 v[4:7], v[174:177], v[214:217], v[4:7]
	v_mfma_f32_16x16x32_bf16 v[0:3], v[182:185], v[214:217], v[0:3]
	s_setprio 0
	s_barrier
	s_add_i32 s63, 0, 0x18000
	s_add_i32 s64, 0, 0x1c000
	v_add_u32_e32 v166, s63, v151
	v_add_u32_e32 v182, s64, v151
	ds_read_b128 v[146:149], v166
	ds_read_b128 v[158:161], v166 offset:1024
	ds_read_b128 v[162:165], v166 offset:2048
	ds_read_b128 v[166:169], v166 offset:3072
	ds_read_b128 v[170:173], v182
	ds_read_b128 v[174:177], v182 offset:1024
	ds_read_b128 v[178:181], v182 offset:2048
	ds_read_b128 v[182:185], v182 offset:3072
	s_add_u32 s34, s44, 0x40000
	s_addc_u32 s35, s45, 0
	s_mov_b32 m0, s50
	v_lshl_add_u64 v[226:227], s[34:35], 0, v[130:131]
	ds_read_b128 v[186:189], v155 offset:32768
	ds_read_b128 v[190:193], v155 offset:33792
	ds_read_b128 v[194:197], v155 offset:34816
	ds_read_b128 v[198:201], v155 offset:35840
	ds_read_b128 v[202:205], v155 offset:36864
	ds_read_b128 v[206:209], v155 offset:37888
	ds_read_b128 v[210:213], v155 offset:38912
	ds_read_b128 v[214:217], v155 offset:39936
	global_load_lds_dwordx4 v[226:227], off
	v_lshl_add_u64 v[226:227], s[34:35], 0, v[134:135]
	s_mov_b32 m0, s51
	s_nop 0
	global_load_lds_dwordx4 v[226:227], off
	s_cmp_lg_u32 s60, 1
	s_cbranch_scc1 .Lmy_rl_16_2
	s_waitcnt vmcnt(8)
	s_branch .Lmy_rj_16_2

.Lmy_rj_16_2:
	s_waitcnt lgkmcnt(0)
	s_barrier
	s_setprio 1
	s_waitcnt lgkmcnt(0)
	v_mfma_f32_16x16x32_bf16 v[124:127], v[146:149], v[186:189], v[124:127]
	v_mfma_f32_16x16x32_bf16 v[120:123], v[162:165], v[186:189], v[120:123]
	v_mfma_f32_16x16x32_bf16 v[108:111], v[146:149], v[194:197], v[108:111]
	v_mfma_f32_16x16x32_bf16 v[104:107], v[162:165], v[194:197], v[104:107]
	v_mfma_f32_16x16x32_bf16 v[92:95], v[146:149], v[202:205], v[92:95]
	v_mfma_f32_16x16x32_bf16 v[88:91], v[162:165], v[202:205], v[88:91]
	v_mfma_f32_16x16x32_bf16 v[76:79], v[146:149], v[210:213], v[76:79]
	v_mfma_f32_16x16x32_bf16 v[72:75], v[162:165], v[210:213], v[72:75]
	v_mfma_f32_16x16x32_bf16 v[124:127], v[158:161], v[190:193], v[124:127]
	v_mfma_f32_16x16x32_bf16 v[120:123], v[166:169], v[190:193], v[120:123]
	v_mfma_f32_16x16x32_bf16 v[108:111], v[158:161], v[198:201], v[108:111]
	v_mfma_f32_16x16x32_bf16 v[104:107], v[166:169], v[198:201], v[104:107]
	v_mfma_f32_16x16x32_bf16 v[92:95], v[158:161], v[206:209], v[92:95]
	v_mfma_f32_16x16x32_bf16 v[88:91], v[166:169], v[206:209], v[88:91]
	v_mfma_f32_16x16x32_bf16 v[76:79], v[158:161], v[214:217], v[76:79]
	v_mfma_f32_16x16x32_bf16 v[72:75], v[166:169], v[214:217], v[72:75]
	s_setprio 0
	s_setprio 1
	v_mfma_f32_16x16x32_bf16 v[116:119], v[170:173], v[186:189], v[116:119]
	v_mfma_f32_16x16x32_bf16 v[112:115], v[178:181], v[186:189], v[112:115]
	v_mfma_f32_16x16x32_bf16 v[100:103], v[170:173], v[194:197], v[100:103]
	v_mfma_f32_16x16x32_bf16 v[96:99], v[178:181], v[194:197], v[96:99]
	v_mfma_f32_16x16x32_bf16 v[84:87], v[170:173], v[202:205], v[84:87]
	v_mfma_f32_16x16x32_bf16 v[80:83], v[178:181], v[202:205], v[80:83]
	v_mfma_f32_16x16x32_bf16 v[68:71], v[170:173], v[210:213], v[68:71]
	v_mfma_f32_16x16x32_bf16 v[64:67], v[178:181], v[210:213], v[64:67]
	v_mfma_f32_16x16x32_bf16 v[116:119], v[174:177], v[190:193], v[116:119]
	v_mfma_f32_16x16x32_bf16 v[112:115], v[182:185], v[190:193], v[112:115]
	v_mfma_f32_16x16x32_bf16 v[100:103], v[174:177], v[198:201], v[100:103]
	v_mfma_f32_16x16x32_bf16 v[96:99], v[182:185], v[198:201], v[96:99]
	v_mfma_f32_16x16x32_bf16 v[84:87], v[174:177], v[206:209], v[84:87]
	v_mfma_f32_16x16x32_bf16 v[80:83], v[182:185], v[206:209], v[80:83]
	v_mfma_f32_16x16x32_bf16 v[68:71], v[174:177], v[214:217], v[68:71]
	v_mfma_f32_16x16x32_bf16 v[64:67], v[182:185], v[214:217], v[64:67]
	s_setprio 0
	s_barrier
	s_add_i32 s34, s63, s47
	v_lshl_add_u64 v[218:219], v[218:219], 0, s[10:11]
	s_mov_b32 m0, s34
	ds_read_b128 v[186:189], v155 offset:49152
	ds_read_b128 v[190:193], v155 offset:50176
	ds_read_b128 v[194:197], v155 offset:51200
	ds_read_b128 v[198:201], v155 offset:52224
	ds_read_b128 v[202:205], v155 offset:53248
	ds_read_b128 v[206:209], v155 offset:54272
	ds_read_b128 v[210:213], v155 offset:55296
	ds_read_b128 v[214:217], v155 offset:56320
	global_load_lds_dwordx4 v[218:219], off
	s_add_i32 m0, s34, 0x2000
	s_add_u32 s34, s42, 0x40080
	v_lshl_add_u64 v[218:219], v[220:221], 0, s[10:11]
	s_addc_u32 s35, s43, 0
	s_add_i32 s42, s64, s47
	global_load_lds_dwordx4 v[218:219], off
	v_lshl_add_u64 v[218:219], s[34:35], 0, v[132:133]
	s_mov_b32 m0, s42
	s_nop 0
	global_load_lds_dwordx4 v[218:219], off
	v_lshl_add_u64 v[218:219], s[34:35], 0, v[136:137]
	s_add_i32 m0, s42, 0x2000
	s_nop 0
	global_load_lds_dwordx4 v[218:219], off
	v_lshl_add_u64 v[218:219], v[222:223], 0, s[10:11]
	s_mov_b32 m0, s53
	s_nop 0
	global_load_lds_dwordx4 v[218:219], off
	v_lshl_add_u64 v[218:219], v[224:225], 0, s[10:11]
	s_mov_b32 m0, s54
	s_nop 0
	global_load_lds_dwordx4 v[218:219], off
	s_waitcnt vmcnt(8)
	s_waitcnt lgkmcnt(0)
	s_barrier
	s_setprio 1
	s_waitcnt lgkmcnt(0)
	v_mfma_f32_16x16x32_bf16 v[60:63], v[146:149], v[186:189], v[60:63]
	v_mfma_f32_16x16x32_bf16 v[56:59], v[162:165], v[186:189], v[56:59]
	v_mfma_f32_16x16x32_bf16 v[44:47], v[146:149], v[194:197], v[44:47]
	v_mfma_f32_16x16x32_bf16 v[40:43], v[162:165], v[194:197], v[40:43]
	v_mfma_f32_16x16x32_bf16 v[28:31], v[146:149], v[202:205], v[28:31]
	v_mfma_f32_16x16x32_bf16 v[24:27], v[162:165], v[202:205], v[24:27]
	v_mfma_f32_16x16x32_bf16 v[12:15], v[146:149], v[210:213], v[12:15]
	v_mfma_f32_16x16x32_bf16 v[8:11], v[162:165], v[210:213], v[8:11]
	v_mfma_f32_16x16x32_bf16 v[60:63], v[158:161], v[190:193], v[60:63]
	v_mfma_f32_16x16x32_bf16 v[56:59], v[166:169], v[190:193], v[56:59]
	v_mfma_f32_16x16x32_bf16 v[44:47], v[158:161], v[198:201], v[44:47]
	v_mfma_f32_16x16x32_bf16 v[40:43], v[166:169], v[198:201], v[40:43]
	v_mfma_f32_16x16x32_bf16 v[28:31], v[158:161], v[206:209], v[28:31]
	v_mfma_f32_16x16x32_bf16 v[24:27], v[166:169], v[206:209], v[24:27]
	v_mfma_f32_16x16x32_bf16 v[12:15], v[158:161], v[214:217], v[12:15]
	v_mfma_f32_16x16x32_bf16 v[8:11], v[166:169], v[214:217], v[8:11]
	s_setprio 0
	s_setprio 1
	v_mfma_f32_16x16x32_bf16 v[52:55], v[170:173], v[186:189], v[52:55]
	v_mfma_f32_16x16x32_bf16 v[48:51], v[178:181], v[186:189], v[48:51]
	v_mfma_f32_16x16x32_bf16 v[36:39], v[170:173], v[194:197], v[36:39]
	v_mfma_f32_16x16x32_bf16 v[32:35], v[178:181], v[194:197], v[32:35]
	v_mfma_f32_16x16x32_bf16 v[20:23], v[170:173], v[202:205], v[20:23]
	v_mfma_f32_16x16x32_bf16 v[16:19], v[178:181], v[202:205], v[16:19]
	v_mfma_f32_16x16x32_bf16 v[4:7], v[170:173], v[210:213], v[4:7]
	v_mfma_f32_16x16x32_bf16 v[0:3], v[178:181], v[210:213], v[0:3]
	v_mfma_f32_16x16x32_bf16 v[52:55], v[174:177], v[190:193], v[52:55]
	v_mfma_f32_16x16x32_bf16 v[48:51], v[182:185], v[190:193], v[48:51]
	v_mfma_f32_16x16x32_bf16 v[36:39], v[174:177], v[198:201], v[36:39]
	v_mfma_f32_16x16x32_bf16 v[32:35], v[182:185], v[198:201], v[32:35]
	v_mfma_f32_16x16x32_bf16 v[20:23], v[174:177], v[206:209], v[20:23]
	v_mfma_f32_16x16x32_bf16 v[16:19], v[182:185], v[206:209], v[16:19]
	v_mfma_f32_16x16x32_bf16 v[4:7], v[174:177], v[214:217], v[4:7]
	v_mfma_f32_16x16x32_bf16 v[0:3], v[182:185], v[214:217], v[0:3]
	s_setprio 0
	s_barrier
	s_add_i32 s62, s62, 2
	s_add_u32 s40, s40, 0x100
	s_addc_u32 s41, s41, 0
	s_add_u32 s39, s39, 0x100
	s_addc_u32 s61, s61, 0

.Lmy_nobar_16:
	s_add_i32 s62, s62, 2
	s_add_u32 s40, s40, 0x100
	s_addc_u32 s41, s41, 0
	s_add_u32 s39, s39, 0x100
	s_addc_u32 s61, s61, 0
	s_cmp_gt_u32 s62, 13
	s_cbranch_scc0 .LBB0_1557
	s_add_u32 s100, s13, 0x40080
	s_addc_u32 s101, s12, 0
	s_add_i32 m0, s48, 0xc000
	v_lshl_add_u64 v[218:219], s[100:101], 0, v[138:139]
	global_load_lds_dwordx4 v[218:219], off
	s_add_i32 m0, s48, 0xe000
	v_lshl_add_u64 v[218:219], s[100:101], 0, v[140:141]
	global_load_lds_dwordx4 v[218:219], off
	s_and_b64 vcc, exec, s[22:23]
	s_cbranch_vccz .LBB0_1560
	s_nop 0

.Lmy_nobar2_17:
	ds_read_b128 v[146:149], v154
	ds_read_b128 v[158:161], v154 offset:1024
	ds_read_b128 v[162:165], v154 offset:2048
	ds_read_b128 v[166:169], v154 offset:3072
	ds_read_b128 v[170:173], v155
	ds_read_b128 v[174:177], v155 offset:1024
	ds_read_b128 v[178:181], v155 offset:2048
	ds_read_b128 v[182:185], v155 offset:3072
	s_add_u32 s34, s36, 0xfffc0080
	s_addc_u32 s35, s37, -1
	s_cmp_eq_u32 s62, 12
	s_cselect_b32 s41, s23, s35
	s_cselect_b32 s40, s58, s34
	s_cselect_b32 s39, s11, s61
	s_cselect_b32 s38, s59, s60
	v_lshl_add_u64 v[218:219], s[36:37], 0, v[138:139]
	s_add_i32 m0, s31, 0xc000
	ds_read_b128 v[186:189], v157
	ds_read_b128 v[190:193], v157 offset:1024
	ds_read_b128 v[194:197], v157 offset:2048
	ds_read_b128 v[198:201], v157 offset:3072
	ds_read_b128 v[202:205], v157 offset:4096
	ds_read_b128 v[206:209], v157 offset:5120
	ds_read_b128 v[210:213], v157 offset:6144
	ds_read_b128 v[214:217], v157 offset:7168
	s_cmp_lg_u32 s56, 1
	s_cbranch_scc1 .Lmy_sk_17_0
	global_load_lds_dwordx4 v[218:219], off
.Lmy_sk_17_0:
	v_lshl_add_u64 v[218:219], s[36:37], 0, v[140:141]
	s_add_i32 m0, s31, 0xe000
	s_nop 0
	s_cmp_lg_u32 s56, 1
	s_cbranch_scc1 .Lmy_sk_17_1
	global_load_lds_dwordx4 v[218:219], off
.Lmy_sk_17_1:
	s_cmp_lg_u32 s56, 1
	s_cbranch_scc1 .Lmy_rl_17_0
	s_waitcnt vmcnt(8)
	s_branch .Lmy_rj_17_0

.Lmy_rj_17_0:
	s_waitcnt lgkmcnt(0)
	s_barrier
	s_setprio 1
	s_waitcnt lgkmcnt(0)
	v_mfma_f32_16x16x32_bf16 v[124:127], v[146:149], v[186:189], 0
	v_mfma_f32_16x16x32_bf16 v[120:123], v[162:165], v[186:189], 0
	v_mfma_f32_16x16x32_bf16 v[108:111], v[146:149], v[194:197], 0
	v_mfma_f32_16x16x32_bf16 v[104:107], v[162:165], v[194:197], 0
	v_mfma_f32_16x16x32_bf16 v[92:95], v[146:149], v[202:205], 0
	v_mfma_f32_16x16x32_bf16 v[88:91], v[162:165], v[202:205], 0
	v_mfma_f32_16x16x32_bf16 v[76:79], v[146:149], v[210:213], 0
	v_mfma_f32_16x16x32_bf16 v[72:75], v[162:165], v[210:213], 0
	v_mfma_f32_16x16x32_bf16 v[124:127], v[158:161], v[190:193], v[124:127]
	v_mfma_f32_16x16x32_bf16 v[120:123], v[166:169], v[190:193], v[120:123]
	v_mfma_f32_16x16x32_bf16 v[108:111], v[158:161], v[198:201], v[108:111]
	v_mfma_f32_16x16x32_bf16 v[104:107], v[166:169], v[198:201], v[104:107]
	v_mfma_f32_16x16x32_bf16 v[92:95], v[158:161], v[206:209], v[92:95]
	v_mfma_f32_16x16x32_bf16 v[88:91], v[166:169], v[206:209], v[88:91]
	v_mfma_f32_16x16x32_bf16 v[76:79], v[158:161], v[214:217], v[76:79]
	v_mfma_f32_16x16x32_bf16 v[72:75], v[166:169], v[214:217], v[72:75]
	s_setprio 0
	s_setprio 1
	v_mfma_f32_16x16x32_bf16 v[116:119], v[170:173], v[186:189], 0
	v_mfma_f32_16x16x32_bf16 v[112:115], v[178:181], v[186:189], 0
	v_mfma_f32_16x16x32_bf16 v[100:103], v[170:173], v[194:197], 0
	v_mfma_f32_16x16x32_bf16 v[96:99], v[178:181], v[194:197], 0
	v_mfma_f32_16x16x32_bf16 v[84:87], v[170:173], v[202:205], 0
	v_mfma_f32_16x16x32_bf16 v[80:83], v[178:181], v[202:205], 0
	v_mfma_f32_16x16x32_bf16 v[68:71], v[170:173], v[210:213], 0
	v_mfma_f32_16x16x32_bf16 v[64:67], v[178:181], v[210:213], 0
	v_mfma_f32_16x16x32_bf16 v[116:119], v[174:177], v[190:193], v[116:119]
	v_mfma_f32_16x16x32_bf16 v[112:115], v[182:185], v[190:193], v[112:115]
	v_mfma_f32_16x16x32_bf16 v[100:103], v[174:177], v[198:201], v[100:103]
	v_mfma_f32_16x16x32_bf16 v[96:99], v[182:185], v[198:201], v[96:99]
	v_mfma_f32_16x16x32_bf16 v[84:87], v[174:177], v[206:209], v[84:87]
	v_mfma_f32_16x16x32_bf16 v[80:83], v[182:185], v[206:209], v[80:83]
	v_mfma_f32_16x16x32_bf16 v[68:71], v[174:177], v[214:217], v[68:71]
	v_mfma_f32_16x16x32_bf16 v[64:67], v[182:185], v[214:217], v[64:67]
	s_setprio 0
	s_barrier
	s_add_i32 s34, s53, s44
	v_lshl_add_u64 v[218:219], s[38:39], 0, v[134:135]
	s_mov_b32 m0, s34
	ds_read_b128 v[186:189], v157 offset:16384
	ds_read_b128 v[190:193], v157 offset:17408
	ds_read_b128 v[194:197], v157 offset:18432
	ds_read_b128 v[198:201], v157 offset:19456
	ds_read_b128 v[202:205], v157 offset:20480
	ds_read_b128 v[206:209], v157 offset:21504
	ds_read_b128 v[210:213], v157 offset:22528
	ds_read_b128 v[214:217], v157 offset:23552
	global_load_lds_dwordx4 v[218:219], off
	s_add_i32 m0, s34, 0x2000
	s_add_u32 s34, s38, 0x40000
	v_lshl_add_u64 v[220:221], s[38:39], 0, v[130:131]
	s_addc_u32 s35, s39, 0
	s_add_i32 s63, s54, s44
	global_load_lds_dwordx4 v[220:221], off
	v_lshl_add_u64 v[222:223], s[34:35], 0, v[134:135]
	s_mov_b32 m0, s63
	v_lshl_add_u64 v[224:225], s[40:41], 0, v[132:133]
	global_load_lds_dwordx4 v[222:223], off
	v_lshl_add_u64 v[222:223], s[34:35], 0, v[130:131]
	s_add_i32 m0, s63, 0x2000
	s_nop 0
	global_load_lds_dwordx4 v[222:223], off
	v_lshl_add_u64 v[222:223], s[40:41], 0, v[136:137]
	s_mov_b32 m0, s31
	s_nop 0
	global_load_lds_dwordx4 v[222:223], off
	s_mov_b32 m0, s48
	s_nop 0
	global_load_lds_dwordx4 v[224:225], off
	s_cmp_lg_u32 s56, 1
	s_cbranch_scc1 .Lmy_rl_17_1
	s_waitcnt vmcnt(8)
	s_branch .Lmy_rj_17_1

.Lmy_rj_17_1:
	s_waitcnt lgkmcnt(0)
	s_barrier
	s_setprio 1
	s_waitcnt lgkmcnt(0)
	v_mfma_f32_16x16x32_bf16 v[60:63], v[146:149], v[186:189], 0
	v_mfma_f32_16x16x32_bf16 v[56:59], v[162:165], v[186:189], 0
	v_mfma_f32_16x16x32_bf16 v[44:47], v[146:149], v[194:197], 0
	v_mfma_f32_16x16x32_bf16 v[40:43], v[162:165], v[194:197], 0
	v_mfma_f32_16x16x32_bf16 v[28:31], v[146:149], v[202:205], 0
	v_mfma_f32_16x16x32_bf16 v[24:27], v[162:165], v[202:205], 0
	v_mfma_f32_16x16x32_bf16 v[12:15], v[146:149], v[210:213], 0
	v_mfma_f32_16x16x32_bf16 v[8:11], v[162:165], v[210:213], 0
	v_mfma_f32_16x16x32_bf16 v[60:63], v[158:161], v[190:193], v[60:63]
	v_mfma_f32_16x16x32_bf16 v[56:59], v[166:169], v[190:193], v[56:59]
	v_mfma_f32_16x16x32_bf16 v[44:47], v[158:161], v[198:201], v[44:47]
	v_mfma_f32_16x16x32_bf16 v[40:43], v[166:169], v[198:201], v[40:43]
	v_mfma_f32_16x16x32_bf16 v[28:31], v[158:161], v[206:209], v[28:31]
	v_mfma_f32_16x16x32_bf16 v[24:27], v[166:169], v[206:209], v[24:27]
	v_mfma_f32_16x16x32_bf16 v[12:15], v[158:161], v[214:217], v[12:15]
	v_mfma_f32_16x16x32_bf16 v[8:11], v[166:169], v[214:217], v[8:11]
	s_setprio 0
	s_setprio 1
	v_mfma_f32_16x16x32_bf16 v[52:55], v[170:173], v[186:189], 0
	v_mfma_f32_16x16x32_bf16 v[48:51], v[178:181], v[186:189], 0
	v_mfma_f32_16x16x32_bf16 v[36:39], v[170:173], v[194:197], 0
	v_mfma_f32_16x16x32_bf16 v[32:35], v[178:181], v[194:197], 0
	v_mfma_f32_16x16x32_bf16 v[20:23], v[170:173], v[202:205], 0
	v_mfma_f32_16x16x32_bf16 v[16:19], v[178:181], v[202:205], 0
	v_mfma_f32_16x16x32_bf16 v[4:7], v[170:173], v[210:213], 0
	v_mfma_f32_16x16x32_bf16 v[0:3], v[178:181], v[210:213], 0
	v_mfma_f32_16x16x32_bf16 v[52:55], v[174:177], v[190:193], v[52:55]
	v_mfma_f32_16x16x32_bf16 v[48:51], v[182:185], v[190:193], v[48:51]
	v_mfma_f32_16x16x32_bf16 v[36:39], v[174:177], v[198:201], v[36:39]
	v_mfma_f32_16x16x32_bf16 v[32:35], v[182:185], v[198:201], v[32:35]
	v_mfma_f32_16x16x32_bf16 v[20:23], v[174:177], v[206:209], v[20:23]
	v_mfma_f32_16x16x32_bf16 v[16:19], v[182:185], v[206:209], v[16:19]
	v_mfma_f32_16x16x32_bf16 v[4:7], v[174:177], v[214:217], v[4:7]
	v_mfma_f32_16x16x32_bf16 v[0:3], v[182:185], v[214:217], v[0:3]
	s_setprio 0
	s_barrier
	s_add_i32 s63, 0, 0x18000
	s_add_i32 s64, 0, 0x1c000
	v_add_u32_e32 v166, s63, v151
	v_add_u32_e32 v182, s64, v151
	ds_read_b128 v[146:149], v166
	ds_read_b128 v[158:161], v166 offset:1024
	ds_read_b128 v[162:165], v166 offset:2048
	ds_read_b128 v[166:169], v166 offset:3072
	ds_read_b128 v[170:173], v182
	ds_read_b128 v[174:177], v182 offset:1024
	ds_read_b128 v[178:181], v182 offset:2048
	ds_read_b128 v[182:185], v182 offset:3072
	s_add_u32 s34, s40, 0x40000
	s_addc_u32 s35, s41, 0
	s_mov_b32 m0, s49
	v_lshl_add_u64 v[226:227], s[34:35], 0, v[136:137]
	ds_read_b128 v[186:189], v157 offset:32768
	ds_read_b128 v[190:193], v157 offset:33792
	ds_read_b128 v[194:197], v157 offset:34816
	ds_read_b128 v[198:201], v157 offset:35840
	ds_read_b128 v[202:205], v157 offset:36864
	ds_read_b128 v[206:209], v157 offset:37888
	ds_read_b128 v[210:213], v157 offset:38912
	ds_read_b128 v[214:217], v157 offset:39936
	global_load_lds_dwordx4 v[226:227], off
	v_lshl_add_u64 v[226:227], s[34:35], 0, v[132:133]
	s_mov_b32 m0, s50
	s_nop 0
	global_load_lds_dwordx4 v[226:227], off
	s_cmp_lg_u32 s56, 1
	s_cbranch_scc1 .Lmy_rl_17_2
	s_waitcnt vmcnt(8)
	s_branch .Lmy_rj_17_2

.Lmy_rj_17_2:
	s_waitcnt lgkmcnt(0)
	s_barrier
	s_setprio 1
	s_waitcnt lgkmcnt(0)
	v_mfma_f32_16x16x32_bf16 v[124:127], v[146:149], v[186:189], v[124:127]
	v_mfma_f32_16x16x32_bf16 v[120:123], v[162:165], v[186:189], v[120:123]
	v_mfma_f32_16x16x32_bf16 v[108:111], v[146:149], v[194:197], v[108:111]
	v_mfma_f32_16x16x32_bf16 v[104:107], v[162:165], v[194:197], v[104:107]
	v_mfma_f32_16x16x32_bf16 v[92:95], v[146:149], v[202:205], v[92:95]
	v_mfma_f32_16x16x32_bf16 v[88:91], v[162:165], v[202:205], v[88:91]
	v_mfma_f32_16x16x32_bf16 v[76:79], v[146:149], v[210:213], v[76:79]
	v_mfma_f32_16x16x32_bf16 v[72:75], v[162:165], v[210:213], v[72:75]
	v_mfma_f32_16x16x32_bf16 v[124:127], v[158:161], v[190:193], v[124:127]
	v_mfma_f32_16x16x32_bf16 v[120:123], v[166:169], v[190:193], v[120:123]
	v_mfma_f32_16x16x32_bf16 v[108:111], v[158:161], v[198:201], v[108:111]
	v_mfma_f32_16x16x32_bf16 v[104:107], v[166:169], v[198:201], v[104:107]
	v_mfma_f32_16x16x32_bf16 v[92:95], v[158:161], v[206:209], v[92:95]
	v_mfma_f32_16x16x32_bf16 v[88:91], v[166:169], v[206:209], v[88:91]
	v_mfma_f32_16x16x32_bf16 v[76:79], v[158:161], v[214:217], v[76:79]
	v_mfma_f32_16x16x32_bf16 v[72:75], v[166:169], v[214:217], v[72:75]
	s_setprio 0
	s_setprio 1
	v_mfma_f32_16x16x32_bf16 v[116:119], v[170:173], v[186:189], v[116:119]
	v_mfma_f32_16x16x32_bf16 v[112:115], v[178:181], v[186:189], v[112:115]
	v_mfma_f32_16x16x32_bf16 v[100:103], v[170:173], v[194:197], v[100:103]
	v_mfma_f32_16x16x32_bf16 v[96:99], v[178:181], v[194:197], v[96:99]
	v_mfma_f32_16x16x32_bf16 v[84:87], v[170:173], v[202:205], v[84:87]
	v_mfma_f32_16x16x32_bf16 v[80:83], v[178:181], v[202:205], v[80:83]
	v_mfma_f32_16x16x32_bf16 v[68:71], v[170:173], v[210:213], v[68:71]
	v_mfma_f32_16x16x32_bf16 v[64:67], v[178:181], v[210:213], v[64:67]
	v_mfma_f32_16x16x32_bf16 v[116:119], v[174:177], v[190:193], v[116:119]
	v_mfma_f32_16x16x32_bf16 v[112:115], v[182:185], v[190:193], v[112:115]
	v_mfma_f32_16x16x32_bf16 v[100:103], v[174:177], v[198:201], v[100:103]
	v_mfma_f32_16x16x32_bf16 v[96:99], v[182:185], v[198:201], v[96:99]
	v_mfma_f32_16x16x32_bf16 v[84:87], v[174:177], v[206:209], v[84:87]
	v_mfma_f32_16x16x32_bf16 v[80:83], v[182:185], v[206:209], v[80:83]
	v_mfma_f32_16x16x32_bf16 v[68:71], v[174:177], v[214:217], v[68:71]
	v_mfma_f32_16x16x32_bf16 v[64:67], v[182:185], v[214:217], v[64:67]
	s_setprio 0
	s_barrier
	s_add_i32 s34, s63, s44
	v_lshl_add_u64 v[218:219], v[218:219], 0, s[6:7]
	s_mov_b32 m0, s34
	ds_read_b128 v[186:189], v157 offset:49152
	ds_read_b128 v[190:193], v157 offset:50176
	ds_read_b128 v[194:197], v157 offset:51200
	ds_read_b128 v[198:201], v157 offset:52224
	ds_read_b128 v[202:205], v157 offset:53248
	ds_read_b128 v[206:209], v157 offset:54272
	ds_read_b128 v[210:213], v157 offset:55296
	ds_read_b128 v[214:217], v157 offset:56320
	global_load_lds_dwordx4 v[218:219], off
	s_add_i32 m0, s34, 0x2000
	s_add_u32 s34, s38, 0x40080
	v_lshl_add_u64 v[218:219], v[220:221], 0, s[6:7]
	s_addc_u32 s35, s39, 0
	s_add_i32 s38, s64, s44
	global_load_lds_dwordx4 v[218:219], off
	v_lshl_add_u64 v[218:219], s[34:35], 0, v[134:135]
	s_mov_b32 m0, s38
	s_nop 0
	global_load_lds_dwordx4 v[218:219], off
	v_lshl_add_u64 v[218:219], s[34:35], 0, v[130:131]
	s_add_i32 m0, s38, 0x2000
	s_nop 0
	global_load_lds_dwordx4 v[218:219], off
	v_lshl_add_u64 v[218:219], v[222:223], 0, s[6:7]
	s_mov_b32 m0, s51
	s_nop 0
	global_load_lds_dwordx4 v[218:219], off
	v_lshl_add_u64 v[218:219], v[224:225], 0, s[6:7]
	s_mov_b32 m0, s52
	s_nop 0
	global_load_lds_dwordx4 v[218:219], off
	s_waitcnt vmcnt(8)
	s_waitcnt lgkmcnt(0)
	s_barrier
	s_setprio 1
	s_waitcnt lgkmcnt(0)
	v_mfma_f32_16x16x32_bf16 v[60:63], v[146:149], v[186:189], v[60:63]
	v_mfma_f32_16x16x32_bf16 v[56:59], v[162:165], v[186:189], v[56:59]
	v_mfma_f32_16x16x32_bf16 v[44:47], v[146:149], v[194:197], v[44:47]
	v_mfma_f32_16x16x32_bf16 v[40:43], v[162:165], v[194:197], v[40:43]
	v_mfma_f32_16x16x32_bf16 v[28:31], v[146:149], v[202:205], v[28:31]
	v_mfma_f32_16x16x32_bf16 v[24:27], v[162:165], v[202:205], v[24:27]
	v_mfma_f32_16x16x32_bf16 v[12:15], v[146:149], v[210:213], v[12:15]
	v_mfma_f32_16x16x32_bf16 v[8:11], v[162:165], v[210:213], v[8:11]
	v_mfma_f32_16x16x32_bf16 v[60:63], v[158:161], v[190:193], v[60:63]
	v_mfma_f32_16x16x32_bf16 v[56:59], v[166:169], v[190:193], v[56:59]
	v_mfma_f32_16x16x32_bf16 v[44:47], v[158:161], v[198:201], v[44:47]
	v_mfma_f32_16x16x32_bf16 v[40:43], v[166:169], v[198:201], v[40:43]
	v_mfma_f32_16x16x32_bf16 v[28:31], v[158:161], v[206:209], v[28:31]
	v_mfma_f32_16x16x32_bf16 v[24:27], v[166:169], v[206:209], v[24:27]
	v_mfma_f32_16x16x32_bf16 v[12:15], v[158:161], v[214:217], v[12:15]
	v_mfma_f32_16x16x32_bf16 v[8:11], v[166:169], v[214:217], v[8:11]
	s_setprio 0
	s_setprio 1
	v_mfma_f32_16x16x32_bf16 v[52:55], v[170:173], v[186:189], v[52:55]
	v_mfma_f32_16x16x32_bf16 v[48:51], v[178:181], v[186:189], v[48:51]
	v_mfma_f32_16x16x32_bf16 v[36:39], v[170:173], v[194:197], v[36:39]
	v_mfma_f32_16x16x32_bf16 v[32:35], v[178:181], v[194:197], v[32:35]
	v_mfma_f32_16x16x32_bf16 v[20:23], v[170:173], v[202:205], v[20:23]
	v_mfma_f32_16x16x32_bf16 v[16:19], v[178:181], v[202:205], v[16:19]
	v_mfma_f32_16x16x32_bf16 v[4:7], v[170:173], v[210:213], v[4:7]
	v_mfma_f32_16x16x32_bf16 v[0:3], v[178:181], v[210:213], v[0:3]
	v_mfma_f32_16x16x32_bf16 v[52:55], v[174:177], v[190:193], v[52:55]
	v_mfma_f32_16x16x32_bf16 v[48:51], v[182:185], v[190:193], v[48:51]
	v_mfma_f32_16x16x32_bf16 v[36:39], v[174:177], v[198:201], v[36:39]
	v_mfma_f32_16x16x32_bf16 v[32:35], v[182:185], v[198:201], v[32:35]
	v_mfma_f32_16x16x32_bf16 v[20:23], v[174:177], v[206:209], v[20:23]
	v_mfma_f32_16x16x32_bf16 v[16:19], v[182:185], v[206:209], v[16:19]
	v_mfma_f32_16x16x32_bf16 v[4:7], v[174:177], v[214:217], v[4:7]
	v_mfma_f32_16x16x32_bf16 v[0:3], v[182:185], v[214:217], v[0:3]
	s_setprio 0
	s_barrier
	s_add_i32 s62, s62, 2
	s_add_u32 s36, s36, 0x100
	s_addc_u32 s37, s37, 0
	s_add_u32 s60, s60, 0x100
	s_addc_u32 s61, s61, 0

.Lmy_nobar_17:
	s_add_i32 s62, s62, 2
	s_add_u32 s36, s36, 0x100
	s_addc_u32 s37, s37, 0
	s_add_u32 s60, s60, 0x100
	s_addc_u32 s61, s61, 0
	s_cmp_gt_u32 s62, 13
	s_cbranch_scc0 .LBB0_1647
	s_add_u32 s100, s58, 0x40080
	s_addc_u32 s101, s23, 0
	s_add_i32 m0, s31, 0xc000
	v_lshl_add_u64 v[218:219], s[100:101], 0, v[138:139]
	global_load_lds_dwordx4 v[218:219], off
	s_add_i32 m0, s31, 0xe000
	v_lshl_add_u64 v[218:219], s[100:101], 0, v[140:141]
	global_load_lds_dwordx4 v[218:219], off
	s_and_b64 vcc, exec, s[8:9]
	s_cbranch_vccz .LBB0_1650
	s_nop 0

.Lmy_nobar2_18:
	ds_read_b128 v[146:149], v153
	ds_read_b128 v[158:161], v153 offset:1024
	ds_read_b128 v[162:165], v153 offset:2048
	ds_read_b128 v[166:169], v153 offset:3072
	ds_read_b128 v[170:173], v154
	ds_read_b128 v[174:177], v154 offset:1024
	ds_read_b128 v[178:181], v154 offset:2048
	ds_read_b128 v[182:185], v154 offset:3072
	s_add_u32 s34, s30, 0xfff50080
	s_addc_u32 s35, s31, -1
	s_cmp_eq_u32 s58, 40
	s_cselect_b32 s39, s1, s35
	s_cselect_b32 s38, s0, s34
	s_cselect_b32 s37, s29, s57
	s_cselect_b32 s36, s28, s13
	v_lshl_add_u64 v[218:219], s[30:31], 0, v[138:139]
	s_add_i32 m0, s42, 0xc000
	ds_read_b128 v[186:189], v155
	ds_read_b128 v[190:193], v155 offset:1024
	ds_read_b128 v[194:197], v155 offset:2048
	ds_read_b128 v[198:201], v155 offset:3072
	ds_read_b128 v[202:205], v155 offset:4096
	ds_read_b128 v[206:209], v155 offset:5120
	ds_read_b128 v[210:213], v155 offset:6144
	ds_read_b128 v[214:217], v155 offset:7168
	s_cmp_lg_u32 s54, 1
	s_cbranch_scc1 .Lmy_sk_18_0
	global_load_lds_dwordx4 v[218:219], off
.Lmy_sk_18_0:
	v_lshl_add_u64 v[218:219], s[30:31], 0, v[140:141]
	s_add_i32 m0, s42, 0xe000
	s_nop 0
	s_cmp_lg_u32 s54, 1
	s_cbranch_scc1 .Lmy_sk_18_1
	global_load_lds_dwordx4 v[218:219], off
.Lmy_sk_18_1:
	s_cmp_lg_u32 s54, 1
	s_cbranch_scc1 .Lmy_rl_18_0
	s_waitcnt vmcnt(8)
	s_branch .Lmy_rj_18_0

.Lmy_rj_18_0:
	s_waitcnt lgkmcnt(0)
	s_barrier
	s_setprio 1
	s_waitcnt lgkmcnt(0)
	v_mfma_f32_16x16x32_bf16 v[124:127], v[146:149], v[186:189], 0
	v_mfma_f32_16x16x32_bf16 v[120:123], v[162:165], v[186:189], 0
	v_mfma_f32_16x16x32_bf16 v[108:111], v[146:149], v[194:197], 0
	v_mfma_f32_16x16x32_bf16 v[104:107], v[162:165], v[194:197], 0
	v_mfma_f32_16x16x32_bf16 v[92:95], v[146:149], v[202:205], 0
	v_mfma_f32_16x16x32_bf16 v[88:91], v[162:165], v[202:205], 0
	v_mfma_f32_16x16x32_bf16 v[76:79], v[146:149], v[210:213], 0
	v_mfma_f32_16x16x32_bf16 v[72:75], v[162:165], v[210:213], 0
	v_mfma_f32_16x16x32_bf16 v[124:127], v[158:161], v[190:193], v[124:127]
	v_mfma_f32_16x16x32_bf16 v[120:123], v[166:169], v[190:193], v[120:123]
	v_mfma_f32_16x16x32_bf16 v[108:111], v[158:161], v[198:201], v[108:111]
	v_mfma_f32_16x16x32_bf16 v[104:107], v[166:169], v[198:201], v[104:107]
	v_mfma_f32_16x16x32_bf16 v[92:95], v[158:161], v[206:209], v[92:95]
	v_mfma_f32_16x16x32_bf16 v[88:91], v[166:169], v[206:209], v[88:91]
	v_mfma_f32_16x16x32_bf16 v[76:79], v[158:161], v[214:217], v[76:79]
	v_mfma_f32_16x16x32_bf16 v[72:75], v[166:169], v[214:217], v[72:75]
	s_setprio 0
	s_setprio 1
	v_mfma_f32_16x16x32_bf16 v[116:119], v[170:173], v[186:189], 0
	v_mfma_f32_16x16x32_bf16 v[112:115], v[178:181], v[186:189], 0
	v_mfma_f32_16x16x32_bf16 v[100:103], v[170:173], v[194:197], 0
	v_mfma_f32_16x16x32_bf16 v[96:99], v[178:181], v[194:197], 0
	v_mfma_f32_16x16x32_bf16 v[84:87], v[170:173], v[202:205], 0
	v_mfma_f32_16x16x32_bf16 v[80:83], v[178:181], v[202:205], 0
	v_mfma_f32_16x16x32_bf16 v[68:71], v[170:173], v[210:213], 0
	v_mfma_f32_16x16x32_bf16 v[64:67], v[178:181], v[210:213], 0
	v_mfma_f32_16x16x32_bf16 v[116:119], v[174:177], v[190:193], v[116:119]
	v_mfma_f32_16x16x32_bf16 v[112:115], v[182:185], v[190:193], v[112:115]
	v_mfma_f32_16x16x32_bf16 v[100:103], v[174:177], v[198:201], v[100:103]
	v_mfma_f32_16x16x32_bf16 v[96:99], v[182:185], v[198:201], v[96:99]
	v_mfma_f32_16x16x32_bf16 v[84:87], v[174:177], v[206:209], v[84:87]
	v_mfma_f32_16x16x32_bf16 v[80:83], v[182:185], v[206:209], v[80:83]
	v_mfma_f32_16x16x32_bf16 v[68:71], v[174:177], v[214:217], v[68:71]
	v_mfma_f32_16x16x32_bf16 v[64:67], v[182:185], v[214:217], v[64:67]
	s_setprio 0
	s_barrier
	s_add_i32 s34, s52, s41
	v_lshl_add_u64 v[218:219], s[36:37], 0, v[132:133]
	s_mov_b32 m0, s34
	ds_read_b128 v[186:189], v155 offset:16384
	ds_read_b128 v[190:193], v155 offset:17408
	ds_read_b128 v[194:197], v155 offset:18432
	ds_read_b128 v[198:201], v155 offset:19456
	ds_read_b128 v[202:205], v155 offset:20480
	ds_read_b128 v[206:209], v155 offset:21504
	ds_read_b128 v[210:213], v155 offset:22528
	ds_read_b128 v[214:217], v155 offset:23552
	global_load_lds_dwordx4 v[218:219], off
	s_add_i32 m0, s34, 0x2000
	s_add_u32 s34, s36, 0xb0000
	v_lshl_add_u64 v[220:221], s[36:37], 0, v[136:137]
	s_addc_u32 s35, s37, 0
	s_add_i32 s59, s53, s41
	global_load_lds_dwordx4 v[220:221], off
	v_lshl_add_u64 v[222:223], s[34:35], 0, v[132:133]
	s_mov_b32 m0, s59
	v_lshl_add_u64 v[224:225], s[38:39], 0, v[134:135]
	global_load_lds_dwordx4 v[222:223], off
	v_lshl_add_u64 v[222:223], s[34:35], 0, v[136:137]
	s_add_i32 m0, s59, 0x2000
	s_nop 0
	global_load_lds_dwordx4 v[222:223], off
	v_lshl_add_u64 v[222:223], s[38:39], 0, v[130:131]
	s_mov_b32 m0, s42
	s_nop 0
	global_load_lds_dwordx4 v[222:223], off
	s_mov_b32 m0, s43
	s_nop 0
	global_load_lds_dwordx4 v[224:225], off
	s_cmp_lg_u32 s54, 1
	s_cbranch_scc1 .Lmy_rl_18_1
	s_waitcnt vmcnt(8)
	s_branch .Lmy_rj_18_1

.Lmy_rj_18_1:
	s_waitcnt lgkmcnt(0)
	s_barrier
	s_setprio 1
	s_waitcnt lgkmcnt(0)
	v_mfma_f32_16x16x32_bf16 v[60:63], v[146:149], v[186:189], 0
	v_mfma_f32_16x16x32_bf16 v[56:59], v[162:165], v[186:189], 0
	v_mfma_f32_16x16x32_bf16 v[44:47], v[146:149], v[194:197], 0
	v_mfma_f32_16x16x32_bf16 v[40:43], v[162:165], v[194:197], 0
	v_mfma_f32_16x16x32_bf16 v[28:31], v[146:149], v[202:205], 0
	v_mfma_f32_16x16x32_bf16 v[24:27], v[162:165], v[202:205], 0
	v_mfma_f32_16x16x32_bf16 v[12:15], v[146:149], v[210:213], 0
	v_mfma_f32_16x16x32_bf16 v[8:11], v[162:165], v[210:213], 0
	v_mfma_f32_16x16x32_bf16 v[60:63], v[158:161], v[190:193], v[60:63]
	v_mfma_f32_16x16x32_bf16 v[56:59], v[166:169], v[190:193], v[56:59]
	v_mfma_f32_16x16x32_bf16 v[44:47], v[158:161], v[198:201], v[44:47]
	v_mfma_f32_16x16x32_bf16 v[40:43], v[166:169], v[198:201], v[40:43]
	v_mfma_f32_16x16x32_bf16 v[28:31], v[158:161], v[206:209], v[28:31]
	v_mfma_f32_16x16x32_bf16 v[24:27], v[166:169], v[206:209], v[24:27]
	v_mfma_f32_16x16x32_bf16 v[12:15], v[158:161], v[214:217], v[12:15]
	v_mfma_f32_16x16x32_bf16 v[8:11], v[166:169], v[214:217], v[8:11]
	s_setprio 0
	s_setprio 1
	v_mfma_f32_16x16x32_bf16 v[52:55], v[170:173], v[186:189], 0
	v_mfma_f32_16x16x32_bf16 v[48:51], v[178:181], v[186:189], 0
	v_mfma_f32_16x16x32_bf16 v[36:39], v[170:173], v[194:197], 0
	v_mfma_f32_16x16x32_bf16 v[32:35], v[178:181], v[194:197], 0
	v_mfma_f32_16x16x32_bf16 v[20:23], v[170:173], v[202:205], 0
	v_mfma_f32_16x16x32_bf16 v[16:19], v[178:181], v[202:205], 0
	v_mfma_f32_16x16x32_bf16 v[4:7], v[170:173], v[210:213], 0
	v_mfma_f32_16x16x32_bf16 v[0:3], v[178:181], v[210:213], 0
	v_mfma_f32_16x16x32_bf16 v[52:55], v[174:177], v[190:193], v[52:55]
	v_mfma_f32_16x16x32_bf16 v[48:51], v[182:185], v[190:193], v[48:51]
	v_mfma_f32_16x16x32_bf16 v[36:39], v[174:177], v[198:201], v[36:39]
	v_mfma_f32_16x16x32_bf16 v[32:35], v[182:185], v[198:201], v[32:35]
	v_mfma_f32_16x16x32_bf16 v[20:23], v[174:177], v[206:209], v[20:23]
	v_mfma_f32_16x16x32_bf16 v[16:19], v[182:185], v[206:209], v[16:19]
	v_mfma_f32_16x16x32_bf16 v[4:7], v[174:177], v[214:217], v[4:7]
	v_mfma_f32_16x16x32_bf16 v[0:3], v[182:185], v[214:217], v[0:3]
	s_setprio 0
	s_barrier
	s_add_i32 s59, 0, 0x18000
	s_add_i32 s60, 0, 0x1c000
	v_add_u32_e32 v166, s59, v151
	v_add_u32_e32 v182, s60, v151
	ds_read_b128 v[146:149], v166
	ds_read_b128 v[158:161], v166 offset:1024
	ds_read_b128 v[162:165], v166 offset:2048
	ds_read_b128 v[166:169], v166 offset:3072
	ds_read_b128 v[170:173], v182
	ds_read_b128 v[174:177], v182 offset:1024
	ds_read_b128 v[178:181], v182 offset:2048
	ds_read_b128 v[182:185], v182 offset:3072
	s_add_u32 s34, s38, 0xb0000
	s_addc_u32 s35, s39, 0
	s_mov_b32 m0, s44
	v_lshl_add_u64 v[226:227], s[34:35], 0, v[130:131]
	ds_read_b128 v[186:189], v155 offset:32768
	ds_read_b128 v[190:193], v155 offset:33792
	ds_read_b128 v[194:197], v155 offset:34816
	ds_read_b128 v[198:201], v155 offset:35840
	ds_read_b128 v[202:205], v155 offset:36864
	ds_read_b128 v[206:209], v155 offset:37888
	ds_read_b128 v[210:213], v155 offset:38912
	ds_read_b128 v[214:217], v155 offset:39936
	global_load_lds_dwordx4 v[226:227], off
	v_lshl_add_u64 v[226:227], s[34:35], 0, v[134:135]
	s_mov_b32 m0, s45
	s_nop 0
	global_load_lds_dwordx4 v[226:227], off
	s_cmp_lg_u32 s54, 1
	s_cbranch_scc1 .Lmy_rl_18_2
	s_waitcnt vmcnt(8)
	s_branch .Lmy_rj_18_2

.Lmy_rj_18_2:
	s_waitcnt lgkmcnt(0)
	s_barrier
	s_setprio 1
	s_waitcnt lgkmcnt(0)
	v_mfma_f32_16x16x32_bf16 v[124:127], v[146:149], v[186:189], v[124:127]
	v_mfma_f32_16x16x32_bf16 v[120:123], v[162:165], v[186:189], v[120:123]
	v_mfma_f32_16x16x32_bf16 v[108:111], v[146:149], v[194:197], v[108:111]
	v_mfma_f32_16x16x32_bf16 v[104:107], v[162:165], v[194:197], v[104:107]
	v_mfma_f32_16x16x32_bf16 v[92:95], v[146:149], v[202:205], v[92:95]
	v_mfma_f32_16x16x32_bf16 v[88:91], v[162:165], v[202:205], v[88:91]
	v_mfma_f32_16x16x32_bf16 v[76:79], v[146:149], v[210:213], v[76:79]
	v_mfma_f32_16x16x32_bf16 v[72:75], v[162:165], v[210:213], v[72:75]
	v_mfma_f32_16x16x32_bf16 v[124:127], v[158:161], v[190:193], v[124:127]
	v_mfma_f32_16x16x32_bf16 v[120:123], v[166:169], v[190:193], v[120:123]
	v_mfma_f32_16x16x32_bf16 v[108:111], v[158:161], v[198:201], v[108:111]
	v_mfma_f32_16x16x32_bf16 v[104:107], v[166:169], v[198:201], v[104:107]
	v_mfma_f32_16x16x32_bf16 v[92:95], v[158:161], v[206:209], v[92:95]
	v_mfma_f32_16x16x32_bf16 v[88:91], v[166:169], v[206:209], v[88:91]
	v_mfma_f32_16x16x32_bf16 v[76:79], v[158:161], v[214:217], v[76:79]
	v_mfma_f32_16x16x32_bf16 v[72:75], v[166:169], v[214:217], v[72:75]
	s_setprio 0
	s_setprio 1
	v_mfma_f32_16x16x32_bf16 v[116:119], v[170:173], v[186:189], v[116:119]
	v_mfma_f32_16x16x32_bf16 v[112:115], v[178:181], v[186:189], v[112:115]
	v_mfma_f32_16x16x32_bf16 v[100:103], v[170:173], v[194:197], v[100:103]
	v_mfma_f32_16x16x32_bf16 v[96:99], v[178:181], v[194:197], v[96:99]
	v_mfma_f32_16x16x32_bf16 v[84:87], v[170:173], v[202:205], v[84:87]
	v_mfma_f32_16x16x32_bf16 v[80:83], v[178:181], v[202:205], v[80:83]
	v_mfma_f32_16x16x32_bf16 v[68:71], v[170:173], v[210:213], v[68:71]
	v_mfma_f32_16x16x32_bf16 v[64:67], v[178:181], v[210:213], v[64:67]
	v_mfma_f32_16x16x32_bf16 v[116:119], v[174:177], v[190:193], v[116:119]
	v_mfma_f32_16x16x32_bf16 v[112:115], v[182:185], v[190:193], v[112:115]
	v_mfma_f32_16x16x32_bf16 v[100:103], v[174:177], v[198:201], v[100:103]
	v_mfma_f32_16x16x32_bf16 v[96:99], v[182:185], v[198:201], v[96:99]
	v_mfma_f32_16x16x32_bf16 v[84:87], v[174:177], v[206:209], v[84:87]
	v_mfma_f32_16x16x32_bf16 v[80:83], v[182:185], v[206:209], v[80:83]
	v_mfma_f32_16x16x32_bf16 v[68:71], v[174:177], v[214:217], v[68:71]
	v_mfma_f32_16x16x32_bf16 v[64:67], v[182:185], v[214:217], v[64:67]
	s_setprio 0
	s_barrier
	s_add_i32 s34, s59, s41
	v_lshl_add_u64 v[218:219], v[218:219], 0, s[22:23]
	s_mov_b32 m0, s34
	ds_read_b128 v[186:189], v155 offset:49152
	ds_read_b128 v[190:193], v155 offset:50176
	ds_read_b128 v[194:197], v155 offset:51200
	ds_read_b128 v[198:201], v155 offset:52224
	ds_read_b128 v[202:205], v155 offset:53248
	ds_read_b128 v[206:209], v155 offset:54272
	ds_read_b128 v[210:213], v155 offset:55296
	ds_read_b128 v[214:217], v155 offset:56320
	global_load_lds_dwordx4 v[218:219], off
	s_add_i32 m0, s34, 0x2000
	s_add_u32 s34, s36, 0xb0080
	v_lshl_add_u64 v[218:219], v[220:221], 0, s[22:23]
	s_addc_u32 s35, s37, 0
	s_add_i32 s36, s60, s41
	global_load_lds_dwordx4 v[218:219], off
	v_lshl_add_u64 v[218:219], s[34:35], 0, v[132:133]
	s_mov_b32 m0, s36
	s_nop 0
	global_load_lds_dwordx4 v[218:219], off
	v_lshl_add_u64 v[218:219], s[34:35], 0, v[136:137]
	s_add_i32 m0, s36, 0x2000
	s_nop 0
	global_load_lds_dwordx4 v[218:219], off
	v_lshl_add_u64 v[218:219], v[222:223], 0, s[22:23]
	s_mov_b32 m0, s47
	s_nop 0
	global_load_lds_dwordx4 v[218:219], off
	v_lshl_add_u64 v[218:219], v[224:225], 0, s[22:23]
	s_mov_b32 m0, s48
	s_nop 0
	global_load_lds_dwordx4 v[218:219], off
	s_waitcnt vmcnt(8)
	s_waitcnt lgkmcnt(0)
	s_barrier
	s_setprio 1
	s_waitcnt lgkmcnt(0)
	v_mfma_f32_16x16x32_bf16 v[60:63], v[146:149], v[186:189], v[60:63]
	v_mfma_f32_16x16x32_bf16 v[56:59], v[162:165], v[186:189], v[56:59]
	v_mfma_f32_16x16x32_bf16 v[44:47], v[146:149], v[194:197], v[44:47]
	v_mfma_f32_16x16x32_bf16 v[40:43], v[162:165], v[194:197], v[40:43]
	v_mfma_f32_16x16x32_bf16 v[28:31], v[146:149], v[202:205], v[28:31]
	v_mfma_f32_16x16x32_bf16 v[24:27], v[162:165], v[202:205], v[24:27]
	v_mfma_f32_16x16x32_bf16 v[12:15], v[146:149], v[210:213], v[12:15]
	v_mfma_f32_16x16x32_bf16 v[8:11], v[162:165], v[210:213], v[8:11]
	v_mfma_f32_16x16x32_bf16 v[60:63], v[158:161], v[190:193], v[60:63]
	v_mfma_f32_16x16x32_bf16 v[56:59], v[166:169], v[190:193], v[56:59]
	v_mfma_f32_16x16x32_bf16 v[44:47], v[158:161], v[198:201], v[44:47]
	v_mfma_f32_16x16x32_bf16 v[40:43], v[166:169], v[198:201], v[40:43]
	v_mfma_f32_16x16x32_bf16 v[28:31], v[158:161], v[206:209], v[28:31]
	v_mfma_f32_16x16x32_bf16 v[24:27], v[166:169], v[206:209], v[24:27]
	v_mfma_f32_16x16x32_bf16 v[12:15], v[158:161], v[214:217], v[12:15]
	v_mfma_f32_16x16x32_bf16 v[8:11], v[166:169], v[214:217], v[8:11]
	s_setprio 0
	s_setprio 1
	v_mfma_f32_16x16x32_bf16 v[52:55], v[170:173], v[186:189], v[52:55]
	v_mfma_f32_16x16x32_bf16 v[48:51], v[178:181], v[186:189], v[48:51]
	v_mfma_f32_16x16x32_bf16 v[36:39], v[170:173], v[194:197], v[36:39]
	v_mfma_f32_16x16x32_bf16 v[32:35], v[178:181], v[194:197], v[32:35]
	v_mfma_f32_16x16x32_bf16 v[20:23], v[170:173], v[202:205], v[20:23]
	v_mfma_f32_16x16x32_bf16 v[16:19], v[178:181], v[202:205], v[16:19]
	v_mfma_f32_16x16x32_bf16 v[4:7], v[170:173], v[210:213], v[4:7]
	v_mfma_f32_16x16x32_bf16 v[0:3], v[178:181], v[210:213], v[0:3]
	v_mfma_f32_16x16x32_bf16 v[52:55], v[174:177], v[190:193], v[52:55]
	v_mfma_f32_16x16x32_bf16 v[48:51], v[182:185], v[190:193], v[48:51]
	v_mfma_f32_16x16x32_bf16 v[36:39], v[174:177], v[198:201], v[36:39]
	v_mfma_f32_16x16x32_bf16 v[32:35], v[182:185], v[198:201], v[32:35]
	v_mfma_f32_16x16x32_bf16 v[20:23], v[174:177], v[206:209], v[20:23]
	v_mfma_f32_16x16x32_bf16 v[16:19], v[182:185], v[206:209], v[16:19]
	v_mfma_f32_16x16x32_bf16 v[4:7], v[174:177], v[214:217], v[4:7]
	v_mfma_f32_16x16x32_bf16 v[0:3], v[182:185], v[214:217], v[0:3]
	s_setprio 0
	s_barrier
	s_add_i32 s58, s58, 2
	s_add_u32 s30, s30, 0x100
	s_addc_u32 s31, s31, 0
	s_add_u32 s13, s13, 0x100
	s_addc_u32 s57, s57, 0

.Lmy_nobar_18:
	s_add_i32 s58, s58, 2
	s_add_u32 s30, s30, 0x100
	s_addc_u32 s31, s31, 0
	s_add_u32 s13, s13, 0x100
	s_addc_u32 s57, s57, 0
	s_cmp_gt_u32 s58, 41
	s_cbranch_scc0 .LBB0_1733
	s_add_u32 s100, s0, 0xb0080
	s_addc_u32 s101, s1, 0
	s_add_i32 m0, s42, 0xc000
	v_lshl_add_u64 v[218:219], s[100:101], 0, v[138:139]
	global_load_lds_dwordx4 v[218:219], off
	s_add_i32 m0, s42, 0xe000
	v_lshl_add_u64 v[218:219], s[100:101], 0, v[140:141]
	global_load_lds_dwordx4 v[218:219], off
	s_and_b64 vcc, exec, s[26:27]
	s_cbranch_vccz .LBB0_1736
	s_nop 0

.Lmy_nobar2_19:
	ds_read_b128 v[150:153], v157
	ds_read_b128 v[160:163], v157 offset:1024
	ds_read_b128 v[164:167], v157 offset:2048
	ds_read_b128 v[168:171], v157 offset:3072
	ds_read_b128 v[172:175], v158
	ds_read_b128 v[176:179], v158 offset:1024
	ds_read_b128 v[180:183], v158 offset:2048
	ds_read_b128 v[184:187], v158 offset:3072
	s_add_u32 s34, s42, 0xfffc0080
	s_addc_u32 s35, s43, -1
	s_cmp_eq_u32 s65, 12
	s_cselect_b32 s47, s7, s35
	s_cselect_b32 s46, s8, s34
	s_cselect_b32 s45, s12, s37
	s_cselect_b32 s44, s13, s31
	v_lshl_add_u64 v[220:221], s[42:43], 0, v[142:143]
	s_add_i32 m0, s53, 0xc000
	ds_read_b128 v[188:191], v159
	ds_read_b128 v[192:195], v159 offset:1024
	ds_read_b128 v[196:199], v159 offset:2048
	ds_read_b128 v[200:203], v159 offset:3072
	ds_read_b128 v[204:207], v159 offset:4096
	ds_read_b128 v[208:211], v159 offset:5120
	ds_read_b128 v[212:215], v159 offset:6144
	ds_read_b128 v[216:219], v159 offset:7168
	s_cmp_lg_u32 s63, 1
	s_cbranch_scc1 .Lmy_sk_19_0
	global_load_lds_dwordx4 v[220:221], off
.Lmy_sk_19_0:
	v_lshl_add_u64 v[220:221], s[42:43], 0, v[144:145]
	s_add_i32 m0, s53, 0xe000
	s_nop 0
	s_cmp_lg_u32 s63, 1
	s_cbranch_scc1 .Lmy_sk_19_1
	global_load_lds_dwordx4 v[220:221], off
.Lmy_sk_19_1:
	s_cmp_lg_u32 s63, 1
	s_cbranch_scc1 .Lmy_rl_19_0
	s_waitcnt vmcnt(8)
	s_branch .Lmy_rj_19_0

.Lmy_rj_19_0:
	s_waitcnt lgkmcnt(0)
	s_barrier
	s_setprio 1
	s_waitcnt lgkmcnt(0)
	v_mfma_f32_16x16x32_bf16 v[124:127], v[150:153], v[188:191], 0
	v_mfma_f32_16x16x32_bf16 v[120:123], v[164:167], v[188:191], 0
	v_mfma_f32_16x16x32_bf16 v[108:111], v[150:153], v[196:199], 0
	v_mfma_f32_16x16x32_bf16 v[104:107], v[164:167], v[196:199], 0
	v_mfma_f32_16x16x32_bf16 v[92:95], v[150:153], v[204:207], 0
	v_mfma_f32_16x16x32_bf16 v[88:91], v[164:167], v[204:207], 0
	v_mfma_f32_16x16x32_bf16 v[76:79], v[150:153], v[212:215], 0
	v_mfma_f32_16x16x32_bf16 v[72:75], v[164:167], v[212:215], 0
	v_mfma_f32_16x16x32_bf16 v[124:127], v[160:163], v[192:195], v[124:127]
	v_mfma_f32_16x16x32_bf16 v[120:123], v[168:171], v[192:195], v[120:123]
	v_mfma_f32_16x16x32_bf16 v[108:111], v[160:163], v[200:203], v[108:111]
	v_mfma_f32_16x16x32_bf16 v[104:107], v[168:171], v[200:203], v[104:107]
	v_mfma_f32_16x16x32_bf16 v[92:95], v[160:163], v[208:211], v[92:95]
	v_mfma_f32_16x16x32_bf16 v[88:91], v[168:171], v[208:211], v[88:91]
	v_mfma_f32_16x16x32_bf16 v[76:79], v[160:163], v[216:219], v[76:79]
	v_mfma_f32_16x16x32_bf16 v[72:75], v[168:171], v[216:219], v[72:75]
	s_setprio 0
	s_setprio 1
	v_mfma_f32_16x16x32_bf16 v[116:119], v[172:175], v[188:191], 0
	v_mfma_f32_16x16x32_bf16 v[112:115], v[180:183], v[188:191], 0
	v_mfma_f32_16x16x32_bf16 v[100:103], v[172:175], v[196:199], 0
	v_mfma_f32_16x16x32_bf16 v[96:99], v[180:183], v[196:199], 0
	v_mfma_f32_16x16x32_bf16 v[84:87], v[172:175], v[204:207], 0
	v_mfma_f32_16x16x32_bf16 v[80:83], v[180:183], v[204:207], 0
	v_mfma_f32_16x16x32_bf16 v[68:71], v[172:175], v[212:215], 0
	v_mfma_f32_16x16x32_bf16 v[64:67], v[180:183], v[212:215], 0
	v_mfma_f32_16x16x32_bf16 v[116:119], v[176:179], v[192:195], v[116:119]
	v_mfma_f32_16x16x32_bf16 v[112:115], v[184:187], v[192:195], v[112:115]
	v_mfma_f32_16x16x32_bf16 v[100:103], v[176:179], v[200:203], v[100:103]
	v_mfma_f32_16x16x32_bf16 v[96:99], v[184:187], v[200:203], v[96:99]
	v_mfma_f32_16x16x32_bf16 v[84:87], v[176:179], v[208:211], v[84:87]
	v_mfma_f32_16x16x32_bf16 v[80:83], v[184:187], v[208:211], v[80:83]
	v_mfma_f32_16x16x32_bf16 v[68:71], v[176:179], v[216:219], v[68:71]
	v_mfma_f32_16x16x32_bf16 v[64:67], v[184:187], v[216:219], v[64:67]
	s_setprio 0
	s_barrier
	s_add_i32 s34, s61, s50
	v_lshl_add_u64 v[220:221], s[44:45], 0, v[134:135]
	s_mov_b32 m0, s34
	ds_read_b128 v[188:191], v159 offset:16384
	ds_read_b128 v[192:195], v159 offset:17408
	ds_read_b128 v[196:199], v159 offset:18432
	ds_read_b128 v[200:203], v159 offset:19456
	ds_read_b128 v[204:207], v159 offset:20480
	ds_read_b128 v[208:211], v159 offset:21504
	ds_read_b128 v[212:215], v159 offset:22528
	ds_read_b128 v[216:219], v159 offset:23552
	global_load_lds_dwordx4 v[220:221], off
	s_add_i32 m0, s34, 0x2000
	s_add_u32 s34, s44, 0x40000
	v_lshl_add_u64 v[222:223], s[44:45], 0, v[138:139]
	s_addc_u32 s35, s45, 0
	s_add_i32 s66, s62, s50
	global_load_lds_dwordx4 v[222:223], off
	v_lshl_add_u64 v[224:225], s[34:35], 0, v[134:135]
	s_mov_b32 m0, s66
	v_lshl_add_u64 v[226:227], s[46:47], 0, v[136:137]
	global_load_lds_dwordx4 v[224:225], off
	v_lshl_add_u64 v[224:225], s[34:35], 0, v[138:139]
	s_add_i32 m0, s66, 0x2000
	s_nop 0
	global_load_lds_dwordx4 v[224:225], off
	v_lshl_add_u64 v[224:225], s[46:47], 0, v[132:133]
	s_mov_b32 m0, s53
	s_nop 0
	global_load_lds_dwordx4 v[224:225], off
	s_mov_b32 m0, s54
	s_nop 0
	global_load_lds_dwordx4 v[226:227], off
	s_cmp_lg_u32 s63, 1
	s_cbranch_scc1 .Lmy_rl_19_1
	s_waitcnt vmcnt(8)
	s_branch .Lmy_rj_19_1

.Lmy_rj_19_1:
	s_waitcnt lgkmcnt(0)
	s_barrier
	s_setprio 1
	s_waitcnt lgkmcnt(0)
	v_mfma_f32_16x16x32_bf16 v[60:63], v[150:153], v[188:191], 0
	v_mfma_f32_16x16x32_bf16 v[56:59], v[164:167], v[188:191], 0
	v_mfma_f32_16x16x32_bf16 v[44:47], v[150:153], v[196:199], 0
	v_mfma_f32_16x16x32_bf16 v[40:43], v[164:167], v[196:199], 0
	v_mfma_f32_16x16x32_bf16 v[28:31], v[150:153], v[204:207], 0
	v_mfma_f32_16x16x32_bf16 v[24:27], v[164:167], v[204:207], 0
	v_mfma_f32_16x16x32_bf16 v[12:15], v[150:153], v[212:215], 0
	v_mfma_f32_16x16x32_bf16 v[8:11], v[164:167], v[212:215], 0
	v_mfma_f32_16x16x32_bf16 v[60:63], v[160:163], v[192:195], v[60:63]
	v_mfma_f32_16x16x32_bf16 v[56:59], v[168:171], v[192:195], v[56:59]
	v_mfma_f32_16x16x32_bf16 v[44:47], v[160:163], v[200:203], v[44:47]
	v_mfma_f32_16x16x32_bf16 v[40:43], v[168:171], v[200:203], v[40:43]
	v_mfma_f32_16x16x32_bf16 v[28:31], v[160:163], v[208:211], v[28:31]
	v_mfma_f32_16x16x32_bf16 v[24:27], v[168:171], v[208:211], v[24:27]
	v_mfma_f32_16x16x32_bf16 v[12:15], v[160:163], v[216:219], v[12:15]
	v_mfma_f32_16x16x32_bf16 v[8:11], v[168:171], v[216:219], v[8:11]
	s_setprio 0
	s_setprio 1
	v_mfma_f32_16x16x32_bf16 v[52:55], v[172:175], v[188:191], 0
	v_mfma_f32_16x16x32_bf16 v[48:51], v[180:183], v[188:191], 0
	v_mfma_f32_16x16x32_bf16 v[36:39], v[172:175], v[196:199], 0
	v_mfma_f32_16x16x32_bf16 v[32:35], v[180:183], v[196:199], 0
	v_mfma_f32_16x16x32_bf16 v[20:23], v[172:175], v[204:207], 0
	v_mfma_f32_16x16x32_bf16 v[16:19], v[180:183], v[204:207], 0
	v_mfma_f32_16x16x32_bf16 v[4:7], v[172:175], v[212:215], 0
	v_mfma_f32_16x16x32_bf16 v[0:3], v[180:183], v[212:215], 0
	v_mfma_f32_16x16x32_bf16 v[52:55], v[176:179], v[192:195], v[52:55]
	v_mfma_f32_16x16x32_bf16 v[48:51], v[184:187], v[192:195], v[48:51]
	v_mfma_f32_16x16x32_bf16 v[36:39], v[176:179], v[200:203], v[36:39]
	v_mfma_f32_16x16x32_bf16 v[32:35], v[184:187], v[200:203], v[32:35]
	v_mfma_f32_16x16x32_bf16 v[20:23], v[176:179], v[208:211], v[20:23]
	v_mfma_f32_16x16x32_bf16 v[16:19], v[184:187], v[208:211], v[16:19]
	v_mfma_f32_16x16x32_bf16 v[4:7], v[176:179], v[216:219], v[4:7]
	v_mfma_f32_16x16x32_bf16 v[0:3], v[184:187], v[216:219], v[0:3]
	s_setprio 0
	s_barrier
	s_add_i32 s66, 0, 0x18000
	v_add_u32_e32 v140, s66, v154
	s_add_i32 s67, 0, 0x1c000
	ds_read_b128 v[150:153], v140
	ds_read_b128 v[160:163], v140 offset:1024
	ds_read_b128 v[164:167], v140 offset:2048
	ds_read_b128 v[168:171], v140 offset:3072
	v_add_u32_e32 v140, s67, v154
	ds_read_b128 v[172:175], v140
	ds_read_b128 v[176:179], v140 offset:1024
	ds_read_b128 v[180:183], v140 offset:2048
	ds_read_b128 v[184:187], v140 offset:3072
	s_add_u32 s34, s46, 0x40000
	s_addc_u32 s35, s47, 0
	s_mov_b32 m0, s55
	v_lshl_add_u64 v[228:229], s[34:35], 0, v[132:133]
	ds_read_b128 v[188:191], v159 offset:32768
	ds_read_b128 v[192:195], v159 offset:33792
	ds_read_b128 v[196:199], v159 offset:34816
	ds_read_b128 v[200:203], v159 offset:35840
	ds_read_b128 v[204:207], v159 offset:36864
	ds_read_b128 v[208:211], v159 offset:37888
	ds_read_b128 v[212:215], v159 offset:38912
	ds_read_b128 v[216:219], v159 offset:39936
	global_load_lds_dwordx4 v[228:229], off
	v_lshl_add_u64 v[228:229], s[34:35], 0, v[136:137]
	s_mov_b32 m0, s56
	s_nop 0
	global_load_lds_dwordx4 v[228:229], off
	s_cmp_lg_u32 s63, 1
	s_cbranch_scc1 .Lmy_rl_19_2
	s_waitcnt vmcnt(8)
	s_branch .Lmy_rj_19_2

.Lmy_rj_19_2:
	s_waitcnt lgkmcnt(0)
	s_barrier
	s_setprio 1
	s_waitcnt lgkmcnt(0)
	v_mfma_f32_16x16x32_bf16 v[124:127], v[150:153], v[188:191], v[124:127]
	v_mfma_f32_16x16x32_bf16 v[120:123], v[164:167], v[188:191], v[120:123]
	v_mfma_f32_16x16x32_bf16 v[108:111], v[150:153], v[196:199], v[108:111]
	v_mfma_f32_16x16x32_bf16 v[104:107], v[164:167], v[196:199], v[104:107]
	v_mfma_f32_16x16x32_bf16 v[92:95], v[150:153], v[204:207], v[92:95]
	v_mfma_f32_16x16x32_bf16 v[88:91], v[164:167], v[204:207], v[88:91]
	v_mfma_f32_16x16x32_bf16 v[76:79], v[150:153], v[212:215], v[76:79]
	v_mfma_f32_16x16x32_bf16 v[72:75], v[164:167], v[212:215], v[72:75]
	v_mfma_f32_16x16x32_bf16 v[124:127], v[160:163], v[192:195], v[124:127]
	v_mfma_f32_16x16x32_bf16 v[120:123], v[168:171], v[192:195], v[120:123]
	v_mfma_f32_16x16x32_bf16 v[108:111], v[160:163], v[200:203], v[108:111]
	v_mfma_f32_16x16x32_bf16 v[104:107], v[168:171], v[200:203], v[104:107]
	v_mfma_f32_16x16x32_bf16 v[92:95], v[160:163], v[208:211], v[92:95]
	v_mfma_f32_16x16x32_bf16 v[88:91], v[168:171], v[208:211], v[88:91]
	v_mfma_f32_16x16x32_bf16 v[76:79], v[160:163], v[216:219], v[76:79]
	v_mfma_f32_16x16x32_bf16 v[72:75], v[168:171], v[216:219], v[72:75]
	s_setprio 0
	s_setprio 1
	v_mfma_f32_16x16x32_bf16 v[116:119], v[172:175], v[188:191], v[116:119]
	v_mfma_f32_16x16x32_bf16 v[112:115], v[180:183], v[188:191], v[112:115]
	v_mfma_f32_16x16x32_bf16 v[100:103], v[172:175], v[196:199], v[100:103]
	v_mfma_f32_16x16x32_bf16 v[96:99], v[180:183], v[196:199], v[96:99]
	v_mfma_f32_16x16x32_bf16 v[84:87], v[172:175], v[204:207], v[84:87]
	v_mfma_f32_16x16x32_bf16 v[80:83], v[180:183], v[204:207], v[80:83]
	v_mfma_f32_16x16x32_bf16 v[68:71], v[172:175], v[212:215], v[68:71]
	v_mfma_f32_16x16x32_bf16 v[64:67], v[180:183], v[212:215], v[64:67]
	v_mfma_f32_16x16x32_bf16 v[116:119], v[176:179], v[192:195], v[116:119]
	v_mfma_f32_16x16x32_bf16 v[112:115], v[184:187], v[192:195], v[112:115]
	v_mfma_f32_16x16x32_bf16 v[100:103], v[176:179], v[200:203], v[100:103]
	v_mfma_f32_16x16x32_bf16 v[96:99], v[184:187], v[200:203], v[96:99]
	v_mfma_f32_16x16x32_bf16 v[84:87], v[176:179], v[208:211], v[84:87]
	v_mfma_f32_16x16x32_bf16 v[80:83], v[184:187], v[208:211], v[80:83]
	v_mfma_f32_16x16x32_bf16 v[68:71], v[176:179], v[216:219], v[68:71]
	v_mfma_f32_16x16x32_bf16 v[64:67], v[184:187], v[216:219], v[64:67]
	s_setprio 0
	s_barrier
	s_add_i32 s34, s66, s50
	v_lshl_add_u64 v[220:221], v[220:221], 0, s[26:27]
	s_mov_b32 m0, s34
	ds_read_b128 v[188:191], v159 offset:49152
	ds_read_b128 v[192:195], v159 offset:50176
	ds_read_b128 v[196:199], v159 offset:51200
	ds_read_b128 v[200:203], v159 offset:52224
	ds_read_b128 v[204:207], v159 offset:53248
	ds_read_b128 v[208:211], v159 offset:54272
	ds_read_b128 v[212:215], v159 offset:55296
	ds_read_b128 v[216:219], v159 offset:56320
	global_load_lds_dwordx4 v[220:221], off
	s_add_i32 m0, s34, 0x2000
	s_add_u32 s34, s44, 0x40080
	v_lshl_add_u64 v[220:221], v[222:223], 0, s[26:27]
	s_addc_u32 s35, s45, 0
	s_add_i32 s44, s67, s50
	global_load_lds_dwordx4 v[220:221], off
	v_lshl_add_u64 v[220:221], s[34:35], 0, v[134:135]
	s_mov_b32 m0, s44
	s_nop 0
	global_load_lds_dwordx4 v[220:221], off
	v_lshl_add_u64 v[220:221], s[34:35], 0, v[138:139]
	s_add_i32 m0, s44, 0x2000
	s_nop 0
	global_load_lds_dwordx4 v[220:221], off
	v_lshl_add_u64 v[220:221], v[224:225], 0, s[26:27]
	s_mov_b32 m0, s58
	s_nop 0
	global_load_lds_dwordx4 v[220:221], off
	v_lshl_add_u64 v[220:221], v[226:227], 0, s[26:27]
	s_mov_b32 m0, s59
	s_nop 0
	global_load_lds_dwordx4 v[220:221], off
	s_waitcnt vmcnt(8)
	s_waitcnt lgkmcnt(0)
	s_barrier
	s_setprio 1
	s_waitcnt lgkmcnt(0)
	v_mfma_f32_16x16x32_bf16 v[60:63], v[150:153], v[188:191], v[60:63]
	v_mfma_f32_16x16x32_bf16 v[56:59], v[164:167], v[188:191], v[56:59]
	v_mfma_f32_16x16x32_bf16 v[44:47], v[150:153], v[196:199], v[44:47]
	v_mfma_f32_16x16x32_bf16 v[40:43], v[164:167], v[196:199], v[40:43]
	v_mfma_f32_16x16x32_bf16 v[28:31], v[150:153], v[204:207], v[28:31]
	v_mfma_f32_16x16x32_bf16 v[24:27], v[164:167], v[204:207], v[24:27]
	v_mfma_f32_16x16x32_bf16 v[12:15], v[150:153], v[212:215], v[12:15]
	v_mfma_f32_16x16x32_bf16 v[8:11], v[164:167], v[212:215], v[8:11]
	v_mfma_f32_16x16x32_bf16 v[60:63], v[160:163], v[192:195], v[60:63]
	v_mfma_f32_16x16x32_bf16 v[56:59], v[168:171], v[192:195], v[56:59]
	v_mfma_f32_16x16x32_bf16 v[44:47], v[160:163], v[200:203], v[44:47]
	v_mfma_f32_16x16x32_bf16 v[40:43], v[168:171], v[200:203], v[40:43]
	v_mfma_f32_16x16x32_bf16 v[28:31], v[160:163], v[208:211], v[28:31]
	v_mfma_f32_16x16x32_bf16 v[24:27], v[168:171], v[208:211], v[24:27]
	v_mfma_f32_16x16x32_bf16 v[12:15], v[160:163], v[216:219], v[12:15]
	v_mfma_f32_16x16x32_bf16 v[8:11], v[168:171], v[216:219], v[8:11]
	s_setprio 0
	s_setprio 1
	v_mfma_f32_16x16x32_bf16 v[52:55], v[172:175], v[188:191], v[52:55]
	v_mfma_f32_16x16x32_bf16 v[48:51], v[180:183], v[188:191], v[48:51]
	v_mfma_f32_16x16x32_bf16 v[36:39], v[172:175], v[196:199], v[36:39]
	v_mfma_f32_16x16x32_bf16 v[32:35], v[180:183], v[196:199], v[32:35]
	v_mfma_f32_16x16x32_bf16 v[20:23], v[172:175], v[204:207], v[20:23]
	v_mfma_f32_16x16x32_bf16 v[16:19], v[180:183], v[204:207], v[16:19]
	v_mfma_f32_16x16x32_bf16 v[4:7], v[172:175], v[212:215], v[4:7]
	v_mfma_f32_16x16x32_bf16 v[0:3], v[180:183], v[212:215], v[0:3]
	v_mfma_f32_16x16x32_bf16 v[52:55], v[176:179], v[192:195], v[52:55]
	v_mfma_f32_16x16x32_bf16 v[48:51], v[184:187], v[192:195], v[48:51]
	v_mfma_f32_16x16x32_bf16 v[36:39], v[176:179], v[200:203], v[36:39]
	v_mfma_f32_16x16x32_bf16 v[32:35], v[184:187], v[200:203], v[32:35]
	v_mfma_f32_16x16x32_bf16 v[20:23], v[176:179], v[208:211], v[20:23]
	v_mfma_f32_16x16x32_bf16 v[16:19], v[184:187], v[208:211], v[16:19]
	v_mfma_f32_16x16x32_bf16 v[4:7], v[176:179], v[216:219], v[4:7]
	v_mfma_f32_16x16x32_bf16 v[0:3], v[184:187], v[216:219], v[0:3]
	s_setprio 0
	s_barrier
	s_add_i32 s65, s65, 2
	s_add_u32 s42, s42, 0x100
	s_addc_u32 s43, s43, 0
	s_add_u32 s31, s31, 0x100
	s_addc_u32 s37, s37, 0

.Lmy_nobar_19:
	s_add_i32 s65, s65, 2
	s_add_u32 s42, s42, 0x100
	s_addc_u32 s43, s43, 0
	s_add_u32 s31, s31, 0x100
	s_addc_u32 s37, s37, 0
	s_cmp_gt_u32 s65, 13
	s_cbranch_scc0 .LBB0_1826
	s_add_u32 s100, s8, 0x40080
	s_addc_u32 s101, s7, 0
	s_add_i32 m0, s53, 0xc000
	v_lshl_add_u64 v[220:221], s[100:101], 0, v[142:143]
	global_load_lds_dwordx4 v[220:221], off
	s_add_i32 m0, s53, 0xe000
	v_lshl_add_u64 v[220:221], s[100:101], 0, v[144:145]
	global_load_lds_dwordx4 v[220:221], off
	s_and_b64 vcc, exec, s[28:29]
	s_cbranch_vccz .LBB0_1829
	s_nop 0

.Lmy_nobar2_21:
	ds_read_b128 v[146:149], v153
	ds_read_b128 v[158:161], v153 offset:1024
	ds_read_b128 v[162:165], v153 offset:2048
	ds_read_b128 v[166:169], v153 offset:3072
	ds_read_b128 v[170:173], v154
	ds_read_b128 v[174:177], v154 offset:1024
	ds_read_b128 v[178:181], v154 offset:2048
	ds_read_b128 v[182:185], v154 offset:3072
	s_add_u32 s34, s38, 0xfffc0080
	s_addc_u32 s35, s39, -1
	s_cmp_eq_u32 s60, 12
	s_cselect_b32 s43, s12, s35
	s_cselect_b32 s42, s13, s34
	s_cselect_b32 s41, s25, s59
	s_cselect_b32 s40, s27, s37
	v_lshl_add_u64 v[218:219], s[38:39], 0, v[138:139]
	s_add_i32 m0, s46, 0xc000
	ds_read_b128 v[186:189], v155
	ds_read_b128 v[190:193], v155 offset:1024
	ds_read_b128 v[194:197], v155 offset:2048
	ds_read_b128 v[198:201], v155 offset:3072
	ds_read_b128 v[202:205], v155 offset:4096
	ds_read_b128 v[206:209], v155 offset:5120
	ds_read_b128 v[210:213], v155 offset:6144
	ds_read_b128 v[214:217], v155 offset:7168
	s_cmp_lg_u32 s58, 1
	s_cbranch_scc1 .Lmy_sk_21_0
	global_load_lds_dwordx4 v[218:219], off
.Lmy_sk_21_0:
	v_lshl_add_u64 v[218:219], s[38:39], 0, v[140:141]
	s_add_i32 m0, s46, 0xe000
	s_nop 0
	s_cmp_lg_u32 s58, 1
	s_cbranch_scc1 .Lmy_sk_21_1
	global_load_lds_dwordx4 v[218:219], off

.Lmy_rj_21_0:
	s_waitcnt lgkmcnt(0)
	s_barrier
	s_setprio 1
	s_waitcnt lgkmcnt(0)
	v_mfma_f32_16x16x32_bf16 v[124:127], v[146:149], v[186:189], 0
	v_mfma_f32_16x16x32_bf16 v[120:123], v[162:165], v[186:189], 0
	v_mfma_f32_16x16x32_bf16 v[108:111], v[146:149], v[194:197], 0
	v_mfma_f32_16x16x32_bf16 v[104:107], v[162:165], v[194:197], 0
	v_mfma_f32_16x16x32_bf16 v[92:95], v[146:149], v[202:205], 0
	v_mfma_f32_16x16x32_bf16 v[88:91], v[162:165], v[202:205], 0
	v_mfma_f32_16x16x32_bf16 v[76:79], v[146:149], v[210:213], 0
	v_mfma_f32_16x16x32_bf16 v[72:75], v[162:165], v[210:213], 0
	v_mfma_f32_16x16x32_bf16 v[124:127], v[158:161], v[190:193], v[124:127]
	v_mfma_f32_16x16x32_bf16 v[120:123], v[166:169], v[190:193], v[120:123]
	v_mfma_f32_16x16x32_bf16 v[108:111], v[158:161], v[198:201], v[108:111]
	v_mfma_f32_16x16x32_bf16 v[104:107], v[166:169], v[198:201], v[104:107]
	v_mfma_f32_16x16x32_bf16 v[92:95], v[158:161], v[206:209], v[92:95]
	v_mfma_f32_16x16x32_bf16 v[88:91], v[166:169], v[206:209], v[88:91]
	v_mfma_f32_16x16x32_bf16 v[76:79], v[158:161], v[214:217], v[76:79]
	v_mfma_f32_16x16x32_bf16 v[72:75], v[166:169], v[214:217], v[72:75]
	s_setprio 0
	s_setprio 1
	v_mfma_f32_16x16x32_bf16 v[116:119], v[170:173], v[186:189], 0
	v_mfma_f32_16x16x32_bf16 v[112:115], v[178:181], v[186:189], 0
	v_mfma_f32_16x16x32_bf16 v[100:103], v[170:173], v[194:197], 0
	v_mfma_f32_16x16x32_bf16 v[96:99], v[178:181], v[194:197], 0
	v_mfma_f32_16x16x32_bf16 v[84:87], v[170:173], v[202:205], 0
	v_mfma_f32_16x16x32_bf16 v[80:83], v[178:181], v[202:205], 0
	v_mfma_f32_16x16x32_bf16 v[68:71], v[170:173], v[210:213], 0
	v_mfma_f32_16x16x32_bf16 v[64:67], v[178:181], v[210:213], 0
	v_mfma_f32_16x16x32_bf16 v[116:119], v[174:177], v[190:193], v[116:119]
	v_mfma_f32_16x16x32_bf16 v[112:115], v[182:185], v[190:193], v[112:115]
	v_mfma_f32_16x16x32_bf16 v[100:103], v[174:177], v[198:201], v[100:103]
	v_mfma_f32_16x16x32_bf16 v[96:99], v[182:185], v[198:201], v[96:99]
	v_mfma_f32_16x16x32_bf16 v[84:87], v[174:177], v[206:209], v[84:87]
	v_mfma_f32_16x16x32_bf16 v[80:83], v[182:185], v[206:209], v[80:83]
	v_mfma_f32_16x16x32_bf16 v[68:71], v[174:177], v[214:217], v[68:71]
	v_mfma_f32_16x16x32_bf16 v[64:67], v[182:185], v[214:217], v[64:67]
	s_setprio 0
	s_barrier
	s_add_i32 s34, s56, s45
	v_lshl_add_u64 v[218:219], s[40:41], 0, v[132:133]
	s_mov_b32 m0, s34
	ds_read_b128 v[186:189], v155 offset:16384
	ds_read_b128 v[190:193], v155 offset:17408
	ds_read_b128 v[194:197], v155 offset:18432
	ds_read_b128 v[198:201], v155 offset:19456
	ds_read_b128 v[202:205], v155 offset:20480
	ds_read_b128 v[206:209], v155 offset:21504
	ds_read_b128 v[210:213], v155 offset:22528
	ds_read_b128 v[214:217], v155 offset:23552
	global_load_lds_dwordx4 v[218:219], off
	s_add_i32 m0, s34, 0x2000
	s_add_u32 s34, s40, 0x40000
	v_lshl_add_u64 v[220:221], s[40:41], 0, v[136:137]
	s_addc_u32 s35, s41, 0
	s_add_i32 s61, s57, s45
	global_load_lds_dwordx4 v[220:221], off
	v_lshl_add_u64 v[222:223], s[34:35], 0, v[132:133]
	s_mov_b32 m0, s61
	v_lshl_add_u64 v[224:225], s[42:43], 0, v[134:135]
	global_load_lds_dwordx4 v[222:223], off
	v_lshl_add_u64 v[222:223], s[34:35], 0, v[136:137]
	s_add_i32 m0, s61, 0x2000
	s_nop 0
	global_load_lds_dwordx4 v[222:223], off
	v_lshl_add_u64 v[222:223], s[42:43], 0, v[130:131]
	s_mov_b32 m0, s46
	s_nop 0
	global_load_lds_dwordx4 v[222:223], off
	s_mov_b32 m0, s47
	s_nop 0
	global_load_lds_dwordx4 v[224:225], off
	s_cmp_lg_u32 s58, 1
	s_cbranch_scc1 .Lmy_rl_21_1
	s_waitcnt vmcnt(8)
	s_branch .Lmy_rj_21_1

.Lmy_rj_21_1:
	s_waitcnt lgkmcnt(0)
	s_barrier
	s_setprio 1
	s_waitcnt lgkmcnt(0)
	v_mfma_f32_16x16x32_bf16 v[60:63], v[146:149], v[186:189], 0
	v_mfma_f32_16x16x32_bf16 v[56:59], v[162:165], v[186:189], 0
	v_mfma_f32_16x16x32_bf16 v[44:47], v[146:149], v[194:197], 0
	v_mfma_f32_16x16x32_bf16 v[40:43], v[162:165], v[194:197], 0
	v_mfma_f32_16x16x32_bf16 v[28:31], v[146:149], v[202:205], 0
	v_mfma_f32_16x16x32_bf16 v[24:27], v[162:165], v[202:205], 0
	v_mfma_f32_16x16x32_bf16 v[12:15], v[146:149], v[210:213], 0
	v_mfma_f32_16x16x32_bf16 v[8:11], v[162:165], v[210:213], 0
	v_mfma_f32_16x16x32_bf16 v[60:63], v[158:161], v[190:193], v[60:63]
	v_mfma_f32_16x16x32_bf16 v[56:59], v[166:169], v[190:193], v[56:59]
	v_mfma_f32_16x16x32_bf16 v[44:47], v[158:161], v[198:201], v[44:47]
	v_mfma_f32_16x16x32_bf16 v[40:43], v[166:169], v[198:201], v[40:43]
	v_mfma_f32_16x16x32_bf16 v[28:31], v[158:161], v[206:209], v[28:31]
	v_mfma_f32_16x16x32_bf16 v[24:27], v[166:169], v[206:209], v[24:27]
	v_mfma_f32_16x16x32_bf16 v[12:15], v[158:161], v[214:217], v[12:15]
	v_mfma_f32_16x16x32_bf16 v[8:11], v[166:169], v[214:217], v[8:11]
	s_setprio 0
	s_setprio 1
	v_mfma_f32_16x16x32_bf16 v[52:55], v[170:173], v[186:189], 0
	v_mfma_f32_16x16x32_bf16 v[48:51], v[178:181], v[186:189], 0
	v_mfma_f32_16x16x32_bf16 v[36:39], v[170:173], v[194:197], 0
	v_mfma_f32_16x16x32_bf16 v[32:35], v[178:181], v[194:197], 0
	v_mfma_f32_16x16x32_bf16 v[20:23], v[170:173], v[202:205], 0
	v_mfma_f32_16x16x32_bf16 v[16:19], v[178:181], v[202:205], 0
	v_mfma_f32_16x16x32_bf16 v[4:7], v[170:173], v[210:213], 0
	v_mfma_f32_16x16x32_bf16 v[0:3], v[178:181], v[210:213], 0
	v_mfma_f32_16x16x32_bf16 v[52:55], v[174:177], v[190:193], v[52:55]
	v_mfma_f32_16x16x32_bf16 v[48:51], v[182:185], v[190:193], v[48:51]
	v_mfma_f32_16x16x32_bf16 v[36:39], v[174:177], v[198:201], v[36:39]
	v_mfma_f32_16x16x32_bf16 v[32:35], v[182:185], v[198:201], v[32:35]
	v_mfma_f32_16x16x32_bf16 v[20:23], v[174:177], v[206:209], v[20:23]
	v_mfma_f32_16x16x32_bf16 v[16:19], v[182:185], v[206:209], v[16:19]
	v_mfma_f32_16x16x32_bf16 v[4:7], v[174:177], v[214:217], v[4:7]
	v_mfma_f32_16x16x32_bf16 v[0:3], v[182:185], v[214:217], v[0:3]
	s_setprio 0
	s_barrier
	s_add_i32 s61, 0, 0x18000
	v_add_u32_e32 v157, s61, v151
	s_add_i32 s62, 0, 0x1c000
	ds_read_b128 v[146:149], v157
	ds_read_b128 v[158:161], v157 offset:1024
	ds_read_b128 v[162:165], v157 offset:2048
	ds_read_b128 v[166:169], v157 offset:3072
	v_add_u32_e32 v157, s62, v151
	ds_read_b128 v[170:173], v157
	ds_read_b128 v[174:177], v157 offset:1024
	ds_read_b128 v[178:181], v157 offset:2048
	ds_read_b128 v[182:185], v157 offset:3072
	s_add_u32 s34, s42, 0x40000
	s_addc_u32 s35, s43, 0
	s_mov_b32 m0, s48
	v_lshl_add_u64 v[226:227], s[34:35], 0, v[130:131]
	ds_read_b128 v[186:189], v155 offset:32768
	ds_read_b128 v[190:193], v155 offset:33792
	ds_read_b128 v[194:197], v155 offset:34816
	ds_read_b128 v[198:201], v155 offset:35840
	ds_read_b128 v[202:205], v155 offset:36864
	ds_read_b128 v[206:209], v155 offset:37888
	ds_read_b128 v[210:213], v155 offset:38912
	ds_read_b128 v[214:217], v155 offset:39936
	global_load_lds_dwordx4 v[226:227], off
	v_lshl_add_u64 v[226:227], s[34:35], 0, v[134:135]
	s_mov_b32 m0, s49
	s_nop 0
	global_load_lds_dwordx4 v[226:227], off
	s_cmp_lg_u32 s58, 1
	s_cbranch_scc1 .Lmy_rl_21_2
	s_waitcnt vmcnt(8)
	s_branch .Lmy_rj_21_2

.Lmy_rj_21_2:
	s_waitcnt lgkmcnt(0)
	s_barrier
	s_setprio 1
	s_waitcnt lgkmcnt(0)
	v_mfma_f32_16x16x32_bf16 v[124:127], v[146:149], v[186:189], v[124:127]
	v_mfma_f32_16x16x32_bf16 v[120:123], v[162:165], v[186:189], v[120:123]
	v_mfma_f32_16x16x32_bf16 v[108:111], v[146:149], v[194:197], v[108:111]
	v_mfma_f32_16x16x32_bf16 v[104:107], v[162:165], v[194:197], v[104:107]
	v_mfma_f32_16x16x32_bf16 v[92:95], v[146:149], v[202:205], v[92:95]
	v_mfma_f32_16x16x32_bf16 v[88:91], v[162:165], v[202:205], v[88:91]
	v_mfma_f32_16x16x32_bf16 v[76:79], v[146:149], v[210:213], v[76:79]
	v_mfma_f32_16x16x32_bf16 v[72:75], v[162:165], v[210:213], v[72:75]
	v_mfma_f32_16x16x32_bf16 v[124:127], v[158:161], v[190:193], v[124:127]
	v_mfma_f32_16x16x32_bf16 v[120:123], v[166:169], v[190:193], v[120:123]
	v_mfma_f32_16x16x32_bf16 v[108:111], v[158:161], v[198:201], v[108:111]
	v_mfma_f32_16x16x32_bf16 v[104:107], v[166:169], v[198:201], v[104:107]
	v_mfma_f32_16x16x32_bf16 v[92:95], v[158:161], v[206:209], v[92:95]
	v_mfma_f32_16x16x32_bf16 v[88:91], v[166:169], v[206:209], v[88:91]
	v_mfma_f32_16x16x32_bf16 v[76:79], v[158:161], v[214:217], v[76:79]
	v_mfma_f32_16x16x32_bf16 v[72:75], v[166:169], v[214:217], v[72:75]
	s_setprio 0
	s_setprio 1
	v_mfma_f32_16x16x32_bf16 v[116:119], v[170:173], v[186:189], v[116:119]
	v_mfma_f32_16x16x32_bf16 v[112:115], v[178:181], v[186:189], v[112:115]
	v_mfma_f32_16x16x32_bf16 v[100:103], v[170:173], v[194:197], v[100:103]
	v_mfma_f32_16x16x32_bf16 v[96:99], v[178:181], v[194:197], v[96:99]
	v_mfma_f32_16x16x32_bf16 v[84:87], v[170:173], v[202:205], v[84:87]
	v_mfma_f32_16x16x32_bf16 v[80:83], v[178:181], v[202:205], v[80:83]
	v_mfma_f32_16x16x32_bf16 v[68:71], v[170:173], v[210:213], v[68:71]
	v_mfma_f32_16x16x32_bf16 v[64:67], v[178:181], v[210:213], v[64:67]
	v_mfma_f32_16x16x32_bf16 v[116:119], v[174:177], v[190:193], v[116:119]
	v_mfma_f32_16x16x32_bf16 v[112:115], v[182:185], v[190:193], v[112:115]
	v_mfma_f32_16x16x32_bf16 v[100:103], v[174:177], v[198:201], v[100:103]
	v_mfma_f32_16x16x32_bf16 v[96:99], v[182:185], v[198:201], v[96:99]
	v_mfma_f32_16x16x32_bf16 v[84:87], v[174:177], v[206:209], v[84:87]
	v_mfma_f32_16x16x32_bf16 v[80:83], v[182:185], v[206:209], v[80:83]
	v_mfma_f32_16x16x32_bf16 v[68:71], v[174:177], v[214:217], v[68:71]
	v_mfma_f32_16x16x32_bf16 v[64:67], v[182:185], v[214:217], v[64:67]
	s_setprio 0
	s_barrier
	s_add_i32 s34, s61, s45
	v_lshl_add_u64 v[218:219], v[218:219], 0, s[10:11]
	s_mov_b32 m0, s34
	ds_read_b128 v[186:189], v155 offset:49152
	ds_read_b128 v[190:193], v155 offset:50176
	ds_read_b128 v[194:197], v155 offset:51200
	ds_read_b128 v[198:201], v155 offset:52224
	ds_read_b128 v[202:205], v155 offset:53248
	ds_read_b128 v[206:209], v155 offset:54272
	ds_read_b128 v[210:213], v155 offset:55296
	ds_read_b128 v[214:217], v155 offset:56320
	global_load_lds_dwordx4 v[218:219], off
	s_add_i32 m0, s34, 0x2000
	s_add_u32 s34, s40, 0x40080
	v_lshl_add_u64 v[218:219], v[220:221], 0, s[10:11]
	s_addc_u32 s35, s41, 0
	s_add_i32 s40, s62, s45
	global_load_lds_dwordx4 v[218:219], off
	v_lshl_add_u64 v[218:219], s[34:35], 0, v[132:133]
	s_mov_b32 m0, s40
	s_nop 0
	global_load_lds_dwordx4 v[218:219], off
	v_lshl_add_u64 v[218:219], s[34:35], 0, v[136:137]
	s_add_i32 m0, s40, 0x2000
	s_nop 0
	global_load_lds_dwordx4 v[218:219], off
	v_lshl_add_u64 v[218:219], v[222:223], 0, s[10:11]
	s_mov_b32 m0, s51
	s_nop 0
	global_load_lds_dwordx4 v[218:219], off
	v_lshl_add_u64 v[218:219], v[224:225], 0, s[10:11]
	s_mov_b32 m0, s52
	s_nop 0
	global_load_lds_dwordx4 v[218:219], off
	s_waitcnt vmcnt(8)
	s_waitcnt lgkmcnt(0)
	s_barrier
	s_setprio 1
	s_waitcnt lgkmcnt(0)
	v_mfma_f32_16x16x32_bf16 v[60:63], v[146:149], v[186:189], v[60:63]
	v_mfma_f32_16x16x32_bf16 v[56:59], v[162:165], v[186:189], v[56:59]
	v_mfma_f32_16x16x32_bf16 v[44:47], v[146:149], v[194:197], v[44:47]
	v_mfma_f32_16x16x32_bf16 v[40:43], v[162:165], v[194:197], v[40:43]
	v_mfma_f32_16x16x32_bf16 v[28:31], v[146:149], v[202:205], v[28:31]
	v_mfma_f32_16x16x32_bf16 v[24:27], v[162:165], v[202:205], v[24:27]
	v_mfma_f32_16x16x32_bf16 v[12:15], v[146:149], v[210:213], v[12:15]
	v_mfma_f32_16x16x32_bf16 v[8:11], v[162:165], v[210:213], v[8:11]
	v_mfma_f32_16x16x32_bf16 v[60:63], v[158:161], v[190:193], v[60:63]
	v_mfma_f32_16x16x32_bf16 v[56:59], v[166:169], v[190:193], v[56:59]
	v_mfma_f32_16x16x32_bf16 v[44:47], v[158:161], v[198:201], v[44:47]
	v_mfma_f32_16x16x32_bf16 v[40:43], v[166:169], v[198:201], v[40:43]
	v_mfma_f32_16x16x32_bf16 v[28:31], v[158:161], v[206:209], v[28:31]
	v_mfma_f32_16x16x32_bf16 v[24:27], v[166:169], v[206:209], v[24:27]
	v_mfma_f32_16x16x32_bf16 v[12:15], v[158:161], v[214:217], v[12:15]
	v_mfma_f32_16x16x32_bf16 v[8:11], v[166:169], v[214:217], v[8:11]
	s_setprio 0
	s_setprio 1
	v_mfma_f32_16x16x32_bf16 v[52:55], v[170:173], v[186:189], v[52:55]
	v_mfma_f32_16x16x32_bf16 v[48:51], v[178:181], v[186:189], v[48:51]
	v_mfma_f32_16x16x32_bf16 v[36:39], v[170:173], v[194:197], v[36:39]
	v_mfma_f32_16x16x32_bf16 v[32:35], v[178:181], v[194:197], v[32:35]
	v_mfma_f32_16x16x32_bf16 v[20:23], v[170:173], v[202:205], v[20:23]
	v_mfma_f32_16x16x32_bf16 v[16:19], v[178:181], v[202:205], v[16:19]
	v_mfma_f32_16x16x32_bf16 v[4:7], v[170:173], v[210:213], v[4:7]
	v_mfma_f32_16x16x32_bf16 v[0:3], v[178:181], v[210:213], v[0:3]
	v_mfma_f32_16x16x32_bf16 v[52:55], v[174:177], v[190:193], v[52:55]
	v_mfma_f32_16x16x32_bf16 v[48:51], v[182:185], v[190:193], v[48:51]
	v_mfma_f32_16x16x32_bf16 v[36:39], v[174:177], v[198:201], v[36:39]
	v_mfma_f32_16x16x32_bf16 v[32:35], v[182:185], v[198:201], v[32:35]
	v_mfma_f32_16x16x32_bf16 v[20:23], v[174:177], v[206:209], v[20:23]
	v_mfma_f32_16x16x32_bf16 v[16:19], v[182:185], v[206:209], v[16:19]
	v_mfma_f32_16x16x32_bf16 v[4:7], v[174:177], v[214:217], v[4:7]
	v_mfma_f32_16x16x32_bf16 v[0:3], v[182:185], v[214:217], v[0:3]
	s_setprio 0
	s_barrier
	s_add_i32 s60, s60, 2
	s_add_u32 s38, s38, 0x100
	s_addc_u32 s39, s39, 0
	s_add_u32 s37, s37, 0x100
	s_addc_u32 s59, s59, 0

.Lmy_nobar_21:
	s_add_i32 s60, s60, 2
	s_add_u32 s38, s38, 0x100
	s_addc_u32 s39, s39, 0
	s_add_u32 s37, s37, 0x100
	s_addc_u32 s59, s59, 0
	s_cmp_gt_u32 s60, 13
	s_cbranch_scc0 .LBB0_2001
	s_add_u32 s100, s13, 0x40080
	s_addc_u32 s101, s12, 0
	s_add_i32 m0, s46, 0xc000
	v_lshl_add_u64 v[218:219], s[100:101], 0, v[138:139]
	global_load_lds_dwordx4 v[218:219], off
	s_add_i32 m0, s46, 0xe000
	v_lshl_add_u64 v[218:219], s[100:101], 0, v[140:141]
	global_load_lds_dwordx4 v[218:219], off
	s_and_b64 vcc, exec, s[22:23]
	s_cbranch_vccz .LBB0_2004
	s_nop 0

.Lmy_nobar2_22:
	ds_read_b128 v[146:149], v153
	ds_read_b128 v[156:159], v153 offset:1024
	ds_read_b128 v[160:163], v153 offset:2048
	ds_read_b128 v[164:167], v153 offset:3072
	ds_read_b128 v[168:171], v154
	ds_read_b128 v[172:175], v154 offset:1024
	ds_read_b128 v[176:179], v154 offset:2048
	ds_read_b128 v[180:183], v154 offset:3072
	s_add_u32 s28, s26, 0xfffc0080
	s_addc_u32 s29, s27, -1
	s_cmp_eq_u32 s56, 12
	s_cselect_b32 s31, s19, s29
	s_cselect_b32 s30, s52, s28
	s_cselect_b32 s29, s11, s55
	s_cselect_b32 s28, s53, s54
	v_lshl_add_u64 v[216:217], s[26:27], 0, v[138:139]
	s_add_i32 m0, s25, 0xc000
	ds_read_b128 v[184:187], v155
	ds_read_b128 v[188:191], v155 offset:1024
	ds_read_b128 v[192:195], v155 offset:2048
	ds_read_b128 v[196:199], v155 offset:3072
	ds_read_b128 v[200:203], v155 offset:4096
	ds_read_b128 v[204:207], v155 offset:5120
	ds_read_b128 v[208:211], v155 offset:6144
	ds_read_b128 v[212:215], v155 offset:7168
	s_cmp_lg_u32 s50, 1
	s_cbranch_scc1 .Lmy_sk_22_0
	global_load_lds_dwordx4 v[216:217], off
.Lmy_sk_22_0:
	v_lshl_add_u64 v[216:217], s[26:27], 0, v[140:141]
	s_add_i32 m0, s25, 0xe000
	s_nop 0
	s_cmp_lg_u32 s50, 1
	s_cbranch_scc1 .Lmy_sk_22_1
	global_load_lds_dwordx4 v[216:217], off
.Lmy_sk_22_1:
	s_cmp_lg_u32 s50, 1
	s_cbranch_scc1 .Lmy_rl_22_0
	s_waitcnt vmcnt(8)
	s_branch .Lmy_rj_22_0

.Lmy_rj_22_0:
	s_waitcnt lgkmcnt(0)
	s_barrier
	s_setprio 1
	s_waitcnt lgkmcnt(0)
	v_mfma_f32_16x16x32_bf16 v[124:127], v[146:149], v[184:187], 0
	v_mfma_f32_16x16x32_bf16 v[120:123], v[160:163], v[184:187], 0
	v_mfma_f32_16x16x32_bf16 v[108:111], v[146:149], v[192:195], 0
	v_mfma_f32_16x16x32_bf16 v[104:107], v[160:163], v[192:195], 0
	v_mfma_f32_16x16x32_bf16 v[92:95], v[146:149], v[200:203], 0
	v_mfma_f32_16x16x32_bf16 v[88:91], v[160:163], v[200:203], 0
	v_mfma_f32_16x16x32_bf16 v[76:79], v[146:149], v[208:211], 0
	v_mfma_f32_16x16x32_bf16 v[72:75], v[160:163], v[208:211], 0
	v_mfma_f32_16x16x32_bf16 v[124:127], v[156:159], v[188:191], v[124:127]
	v_mfma_f32_16x16x32_bf16 v[120:123], v[164:167], v[188:191], v[120:123]
	v_mfma_f32_16x16x32_bf16 v[108:111], v[156:159], v[196:199], v[108:111]
	v_mfma_f32_16x16x32_bf16 v[104:107], v[164:167], v[196:199], v[104:107]
	v_mfma_f32_16x16x32_bf16 v[92:95], v[156:159], v[204:207], v[92:95]
	v_mfma_f32_16x16x32_bf16 v[88:91], v[164:167], v[204:207], v[88:91]
	v_mfma_f32_16x16x32_bf16 v[76:79], v[156:159], v[212:215], v[76:79]
	v_mfma_f32_16x16x32_bf16 v[72:75], v[164:167], v[212:215], v[72:75]
	s_setprio 0
	s_setprio 1
	v_mfma_f32_16x16x32_bf16 v[116:119], v[168:171], v[184:187], 0
	v_mfma_f32_16x16x32_bf16 v[112:115], v[176:179], v[184:187], 0
	v_mfma_f32_16x16x32_bf16 v[100:103], v[168:171], v[192:195], 0
	v_mfma_f32_16x16x32_bf16 v[96:99], v[176:179], v[192:195], 0
	v_mfma_f32_16x16x32_bf16 v[84:87], v[168:171], v[200:203], 0
	v_mfma_f32_16x16x32_bf16 v[80:83], v[176:179], v[200:203], 0
	v_mfma_f32_16x16x32_bf16 v[68:71], v[168:171], v[208:211], 0
	v_mfma_f32_16x16x32_bf16 v[64:67], v[176:179], v[208:211], 0
	v_mfma_f32_16x16x32_bf16 v[116:119], v[172:175], v[188:191], v[116:119]
	v_mfma_f32_16x16x32_bf16 v[112:115], v[180:183], v[188:191], v[112:115]
	v_mfma_f32_16x16x32_bf16 v[100:103], v[172:175], v[196:199], v[100:103]
	v_mfma_f32_16x16x32_bf16 v[96:99], v[180:183], v[196:199], v[96:99]
	v_mfma_f32_16x16x32_bf16 v[84:87], v[172:175], v[204:207], v[84:87]
	v_mfma_f32_16x16x32_bf16 v[80:83], v[180:183], v[204:207], v[80:83]
	v_mfma_f32_16x16x32_bf16 v[68:71], v[172:175], v[212:215], v[68:71]
	v_mfma_f32_16x16x32_bf16 v[64:67], v[180:183], v[212:215], v[64:67]
	s_setprio 0
	s_barrier
	s_add_i32 s34, s47, s38
	v_lshl_add_u64 v[216:217], s[28:29], 0, v[134:135]
	s_mov_b32 m0, s34
	ds_read_b128 v[184:187], v155 offset:16384
	ds_read_b128 v[188:191], v155 offset:17408
	ds_read_b128 v[192:195], v155 offset:18432
	ds_read_b128 v[196:199], v155 offset:19456
	ds_read_b128 v[200:203], v155 offset:20480
	ds_read_b128 v[204:207], v155 offset:21504
	ds_read_b128 v[208:211], v155 offset:22528
	ds_read_b128 v[212:215], v155 offset:23552
	global_load_lds_dwordx4 v[216:217], off
	s_add_i32 m0, s34, 0x2000
	s_add_u32 s34, s28, 0x40000
	v_lshl_add_u64 v[218:219], s[28:29], 0, v[130:131]
	s_addc_u32 s35, s29, 0
	s_add_i32 s57, s48, s38
	global_load_lds_dwordx4 v[218:219], off
	v_lshl_add_u64 v[220:221], s[34:35], 0, v[134:135]
	s_mov_b32 m0, s57
	v_lshl_add_u64 v[222:223], s[30:31], 0, v[132:133]
	global_load_lds_dwordx4 v[220:221], off
	v_lshl_add_u64 v[220:221], s[34:35], 0, v[130:131]
	s_add_i32 m0, s57, 0x2000
	s_nop 0
	global_load_lds_dwordx4 v[220:221], off
	v_lshl_add_u64 v[220:221], s[30:31], 0, v[136:137]
	s_mov_b32 m0, s25
	s_nop 0
	global_load_lds_dwordx4 v[220:221], off
	s_mov_b32 m0, s42
	s_nop 0
	global_load_lds_dwordx4 v[222:223], off
	s_cmp_lg_u32 s50, 1
	s_cbranch_scc1 .Lmy_rl_22_1
	s_waitcnt vmcnt(8)
	s_branch .Lmy_rj_22_1

.Lmy_rj_22_1:
	s_waitcnt lgkmcnt(0)
	s_barrier
	s_setprio 1
	s_waitcnt lgkmcnt(0)
	v_mfma_f32_16x16x32_bf16 v[60:63], v[146:149], v[184:187], 0
	v_mfma_f32_16x16x32_bf16 v[56:59], v[160:163], v[184:187], 0
	v_mfma_f32_16x16x32_bf16 v[44:47], v[146:149], v[192:195], 0
	v_mfma_f32_16x16x32_bf16 v[40:43], v[160:163], v[192:195], 0
	v_mfma_f32_16x16x32_bf16 v[28:31], v[146:149], v[200:203], 0
	v_mfma_f32_16x16x32_bf16 v[24:27], v[160:163], v[200:203], 0
	v_mfma_f32_16x16x32_bf16 v[12:15], v[146:149], v[208:211], 0
	v_mfma_f32_16x16x32_bf16 v[8:11], v[160:163], v[208:211], 0
	v_mfma_f32_16x16x32_bf16 v[60:63], v[156:159], v[188:191], v[60:63]
	v_mfma_f32_16x16x32_bf16 v[56:59], v[164:167], v[188:191], v[56:59]
	v_mfma_f32_16x16x32_bf16 v[44:47], v[156:159], v[196:199], v[44:47]
	v_mfma_f32_16x16x32_bf16 v[40:43], v[164:167], v[196:199], v[40:43]
	v_mfma_f32_16x16x32_bf16 v[28:31], v[156:159], v[204:207], v[28:31]
	v_mfma_f32_16x16x32_bf16 v[24:27], v[164:167], v[204:207], v[24:27]
	v_mfma_f32_16x16x32_bf16 v[12:15], v[156:159], v[212:215], v[12:15]
	v_mfma_f32_16x16x32_bf16 v[8:11], v[164:167], v[212:215], v[8:11]
	s_setprio 0
	s_setprio 1
	v_mfma_f32_16x16x32_bf16 v[52:55], v[168:171], v[184:187], 0
	v_mfma_f32_16x16x32_bf16 v[48:51], v[176:179], v[184:187], 0
	v_mfma_f32_16x16x32_bf16 v[36:39], v[168:171], v[192:195], 0
	v_mfma_f32_16x16x32_bf16 v[32:35], v[176:179], v[192:195], 0
	v_mfma_f32_16x16x32_bf16 v[20:23], v[168:171], v[200:203], 0
	v_mfma_f32_16x16x32_bf16 v[16:19], v[176:179], v[200:203], 0
	v_mfma_f32_16x16x32_bf16 v[4:7], v[168:171], v[208:211], 0
	v_mfma_f32_16x16x32_bf16 v[0:3], v[176:179], v[208:211], 0
	v_mfma_f32_16x16x32_bf16 v[52:55], v[172:175], v[188:191], v[52:55]
	v_mfma_f32_16x16x32_bf16 v[48:51], v[180:183], v[188:191], v[48:51]
	v_mfma_f32_16x16x32_bf16 v[36:39], v[172:175], v[196:199], v[36:39]
	v_mfma_f32_16x16x32_bf16 v[32:35], v[180:183], v[196:199], v[32:35]
	v_mfma_f32_16x16x32_bf16 v[20:23], v[172:175], v[204:207], v[20:23]
	v_mfma_f32_16x16x32_bf16 v[16:19], v[180:183], v[204:207], v[16:19]
	v_mfma_f32_16x16x32_bf16 v[4:7], v[172:175], v[212:215], v[4:7]
	v_mfma_f32_16x16x32_bf16 v[0:3], v[180:183], v[212:215], v[0:3]
	s_setprio 0
	s_barrier
	s_add_i32 s34, 0, 0x18000
	s_add_i32 s35, 0, 0x1c000
	v_add_u32_e32 v164, s34, v150
	v_add_u32_e32 v180, s35, v150
	ds_read_b128 v[146:149], v164
	ds_read_b128 v[156:159], v164 offset:1024
	ds_read_b128 v[160:163], v164 offset:2048
	ds_read_b128 v[164:167], v164 offset:3072
	ds_read_b128 v[168:171], v180
	ds_read_b128 v[172:175], v180 offset:1024
	ds_read_b128 v[176:179], v180 offset:2048
	ds_read_b128 v[180:183], v180 offset:3072
	s_add_u32 s30, s30, 0x40000
	s_addc_u32 s31, s31, 0
	s_mov_b32 m0, s43
	v_lshl_add_u64 v[224:225], s[30:31], 0, v[136:137]
	ds_read_b128 v[184:187], v155 offset:32768
	ds_read_b128 v[188:191], v155 offset:33792
	ds_read_b128 v[192:195], v155 offset:34816
	ds_read_b128 v[196:199], v155 offset:35840
	ds_read_b128 v[200:203], v155 offset:36864
	ds_read_b128 v[204:207], v155 offset:37888
	ds_read_b128 v[208:211], v155 offset:38912
	ds_read_b128 v[212:215], v155 offset:39936
	global_load_lds_dwordx4 v[224:225], off
	v_lshl_add_u64 v[224:225], s[30:31], 0, v[132:133]
	s_mov_b32 m0, s44
	s_nop 0
	global_load_lds_dwordx4 v[224:225], off
	s_cmp_lg_u32 s50, 1
	s_cbranch_scc1 .Lmy_rl_22_2
	s_waitcnt vmcnt(8)
	s_branch .Lmy_rj_22_2

.Lmy_rj_22_2:
	s_waitcnt lgkmcnt(0)
	s_barrier
	s_setprio 1
	s_waitcnt lgkmcnt(0)
	v_mfma_f32_16x16x32_bf16 v[124:127], v[146:149], v[184:187], v[124:127]
	v_mfma_f32_16x16x32_bf16 v[120:123], v[160:163], v[184:187], v[120:123]
	v_mfma_f32_16x16x32_bf16 v[108:111], v[146:149], v[192:195], v[108:111]
	v_mfma_f32_16x16x32_bf16 v[104:107], v[160:163], v[192:195], v[104:107]
	v_mfma_f32_16x16x32_bf16 v[92:95], v[146:149], v[200:203], v[92:95]
	v_mfma_f32_16x16x32_bf16 v[88:91], v[160:163], v[200:203], v[88:91]
	v_mfma_f32_16x16x32_bf16 v[76:79], v[146:149], v[208:211], v[76:79]
	v_mfma_f32_16x16x32_bf16 v[72:75], v[160:163], v[208:211], v[72:75]
	v_mfma_f32_16x16x32_bf16 v[124:127], v[156:159], v[188:191], v[124:127]
	v_mfma_f32_16x16x32_bf16 v[120:123], v[164:167], v[188:191], v[120:123]
	v_mfma_f32_16x16x32_bf16 v[108:111], v[156:159], v[196:199], v[108:111]
	v_mfma_f32_16x16x32_bf16 v[104:107], v[164:167], v[196:199], v[104:107]
	v_mfma_f32_16x16x32_bf16 v[92:95], v[156:159], v[204:207], v[92:95]
	v_mfma_f32_16x16x32_bf16 v[88:91], v[164:167], v[204:207], v[88:91]
	v_mfma_f32_16x16x32_bf16 v[76:79], v[156:159], v[212:215], v[76:79]
	v_mfma_f32_16x16x32_bf16 v[72:75], v[164:167], v[212:215], v[72:75]
	s_setprio 0
	s_setprio 1
	v_mfma_f32_16x16x32_bf16 v[116:119], v[168:171], v[184:187], v[116:119]
	v_mfma_f32_16x16x32_bf16 v[112:115], v[176:179], v[184:187], v[112:115]
	v_mfma_f32_16x16x32_bf16 v[100:103], v[168:171], v[192:195], v[100:103]
	v_mfma_f32_16x16x32_bf16 v[96:99], v[176:179], v[192:195], v[96:99]
	v_mfma_f32_16x16x32_bf16 v[84:87], v[168:171], v[200:203], v[84:87]
	v_mfma_f32_16x16x32_bf16 v[80:83], v[176:179], v[200:203], v[80:83]
	v_mfma_f32_16x16x32_bf16 v[68:71], v[168:171], v[208:211], v[68:71]
	v_mfma_f32_16x16x32_bf16 v[64:67], v[176:179], v[208:211], v[64:67]
	v_mfma_f32_16x16x32_bf16 v[116:119], v[172:175], v[188:191], v[116:119]
	v_mfma_f32_16x16x32_bf16 v[112:115], v[180:183], v[188:191], v[112:115]
	v_mfma_f32_16x16x32_bf16 v[100:103], v[172:175], v[196:199], v[100:103]
	v_mfma_f32_16x16x32_bf16 v[96:99], v[180:183], v[196:199], v[96:99]
	v_mfma_f32_16x16x32_bf16 v[84:87], v[172:175], v[204:207], v[84:87]
	v_mfma_f32_16x16x32_bf16 v[80:83], v[180:183], v[204:207], v[80:83]
	v_mfma_f32_16x16x32_bf16 v[68:71], v[172:175], v[212:215], v[68:71]
	v_mfma_f32_16x16x32_bf16 v[64:67], v[180:183], v[212:215], v[64:67]
	s_setprio 0
	s_barrier
	s_add_i32 s30, s34, s38
	v_lshl_add_u64 v[216:217], v[216:217], 0, s[6:7]
	s_mov_b32 m0, s30
	ds_read_b128 v[184:187], v155 offset:49152
	ds_read_b128 v[188:191], v155 offset:50176
	ds_read_b128 v[192:195], v155 offset:51200
	ds_read_b128 v[196:199], v155 offset:52224
	ds_read_b128 v[200:203], v155 offset:53248
	ds_read_b128 v[204:207], v155 offset:54272
	ds_read_b128 v[208:211], v155 offset:55296
	ds_read_b128 v[212:215], v155 offset:56320
	global_load_lds_dwordx4 v[216:217], off
	s_add_i32 m0, s30, 0x2000
	s_add_u32 s28, s28, 0x40080
	v_lshl_add_u64 v[216:217], v[218:219], 0, s[6:7]
	s_addc_u32 s29, s29, 0
	s_add_i32 s30, s35, s38
	global_load_lds_dwordx4 v[216:217], off
	v_lshl_add_u64 v[216:217], s[28:29], 0, v[134:135]
	s_mov_b32 m0, s30
	s_nop 0
	global_load_lds_dwordx4 v[216:217], off
	v_lshl_add_u64 v[216:217], s[28:29], 0, v[130:131]
	s_add_i32 m0, s30, 0x2000
	s_nop 0
	global_load_lds_dwordx4 v[216:217], off
	v_lshl_add_u64 v[216:217], v[220:221], 0, s[6:7]
	s_mov_b32 m0, s45
	s_nop 0
	global_load_lds_dwordx4 v[216:217], off
	v_lshl_add_u64 v[216:217], v[222:223], 0, s[6:7]
	s_mov_b32 m0, s46
	s_nop 0
	global_load_lds_dwordx4 v[216:217], off
	s_waitcnt vmcnt(8)
	s_waitcnt lgkmcnt(0)
	s_barrier
	s_setprio 1
	s_waitcnt lgkmcnt(0)
	v_mfma_f32_16x16x32_bf16 v[60:63], v[146:149], v[184:187], v[60:63]
	v_mfma_f32_16x16x32_bf16 v[56:59], v[160:163], v[184:187], v[56:59]
	v_mfma_f32_16x16x32_bf16 v[44:47], v[146:149], v[192:195], v[44:47]
	v_mfma_f32_16x16x32_bf16 v[40:43], v[160:163], v[192:195], v[40:43]
	v_mfma_f32_16x16x32_bf16 v[28:31], v[146:149], v[200:203], v[28:31]
	v_mfma_f32_16x16x32_bf16 v[24:27], v[160:163], v[200:203], v[24:27]
	v_mfma_f32_16x16x32_bf16 v[12:15], v[146:149], v[208:211], v[12:15]
	v_mfma_f32_16x16x32_bf16 v[8:11], v[160:163], v[208:211], v[8:11]
	v_mfma_f32_16x16x32_bf16 v[60:63], v[156:159], v[188:191], v[60:63]
	v_mfma_f32_16x16x32_bf16 v[56:59], v[164:167], v[188:191], v[56:59]
	v_mfma_f32_16x16x32_bf16 v[44:47], v[156:159], v[196:199], v[44:47]
	v_mfma_f32_16x16x32_bf16 v[40:43], v[164:167], v[196:199], v[40:43]
	v_mfma_f32_16x16x32_bf16 v[28:31], v[156:159], v[204:207], v[28:31]
	v_mfma_f32_16x16x32_bf16 v[24:27], v[164:167], v[204:207], v[24:27]
	v_mfma_f32_16x16x32_bf16 v[12:15], v[156:159], v[212:215], v[12:15]
	v_mfma_f32_16x16x32_bf16 v[8:11], v[164:167], v[212:215], v[8:11]
	s_setprio 0
	s_setprio 1
	v_mfma_f32_16x16x32_bf16 v[52:55], v[168:171], v[184:187], v[52:55]
	v_mfma_f32_16x16x32_bf16 v[48:51], v[176:179], v[184:187], v[48:51]
	v_mfma_f32_16x16x32_bf16 v[36:39], v[168:171], v[192:195], v[36:39]
	v_mfma_f32_16x16x32_bf16 v[32:35], v[176:179], v[192:195], v[32:35]
	v_mfma_f32_16x16x32_bf16 v[20:23], v[168:171], v[200:203], v[20:23]
	v_mfma_f32_16x16x32_bf16 v[16:19], v[176:179], v[200:203], v[16:19]
	v_mfma_f32_16x16x32_bf16 v[4:7], v[168:171], v[208:211], v[4:7]
	v_mfma_f32_16x16x32_bf16 v[0:3], v[176:179], v[208:211], v[0:3]
	v_mfma_f32_16x16x32_bf16 v[52:55], v[172:175], v[188:191], v[52:55]
	v_mfma_f32_16x16x32_bf16 v[48:51], v[180:183], v[188:191], v[48:51]
	v_mfma_f32_16x16x32_bf16 v[36:39], v[172:175], v[196:199], v[36:39]
	v_mfma_f32_16x16x32_bf16 v[32:35], v[180:183], v[196:199], v[32:35]
	v_mfma_f32_16x16x32_bf16 v[20:23], v[172:175], v[204:207], v[20:23]
	v_mfma_f32_16x16x32_bf16 v[16:19], v[180:183], v[204:207], v[16:19]
	v_mfma_f32_16x16x32_bf16 v[4:7], v[172:175], v[212:215], v[4:7]
	v_mfma_f32_16x16x32_bf16 v[0:3], v[180:183], v[212:215], v[0:3]
	s_setprio 0
	s_barrier
	s_add_i32 s56, s56, 2
	s_add_u32 s26, s26, 0x100
	s_addc_u32 s27, s27, 0
	s_add_u32 s54, s54, 0x100
	s_addc_u32 s55, s55, 0

.Lmy_nobar_22:
	s_add_i32 s56, s56, 2
	s_add_u32 s26, s26, 0x100
	s_addc_u32 s27, s27, 0
	s_add_u32 s54, s54, 0x100
	s_addc_u32 s55, s55, 0
	s_cmp_gt_u32 s56, 13
	s_cbranch_scc0 .LBB0_2091
	s_add_u32 s100, s52, 0x40080
	s_addc_u32 s101, s19, 0
	s_add_i32 m0, s25, 0xc000
	v_lshl_add_u64 v[216:217], s[100:101], 0, v[138:139]
	global_load_lds_dwordx4 v[216:217], off
	s_add_i32 m0, s25, 0xe000
	v_lshl_add_u64 v[216:217], s[100:101], 0, v[140:141]
	global_load_lds_dwordx4 v[216:217], off
	s_and_b64 vcc, exec, s[8:9]
	s_cbranch_vccz .LBB0_2094
	s_nop 0

.Lmy_nobar2_23:
	ds_read_b128 v[144:147], v153
	ds_read_b128 v[156:159], v153 offset:1024
	ds_read_b128 v[160:163], v153 offset:2048
	ds_read_b128 v[164:167], v153 offset:3072
	ds_read_b128 v[168:171], v154
	ds_read_b128 v[172:175], v154 offset:1024
	ds_read_b128 v[176:179], v154 offset:2048
	ds_read_b128 v[180:183], v154 offset:3072
	s_add_u32 s30, s28, 0xfff50080
	s_addc_u32 s31, s29, -1
	s_cmp_eq_u32 s56, 40
	s_cselect_b32 s37, s1, s31
	s_cselect_b32 s36, s0, s30
	s_cselect_b32 s31, s27, s55
	s_cselect_b32 s30, s26, s54
	v_lshl_add_u64 v[148:149], s[28:29], 0, v[128:129]
	s_add_i32 m0, s41, 0xc000
	ds_read_b128 v[184:187], v155
	ds_read_b128 v[188:191], v155 offset:1024
	ds_read_b128 v[192:195], v155 offset:2048
	ds_read_b128 v[196:199], v155 offset:3072
	ds_read_b128 v[200:203], v155 offset:4096
	ds_read_b128 v[204:207], v155 offset:5120
	ds_read_b128 v[208:211], v155 offset:6144
	ds_read_b128 v[212:215], v155 offset:7168
	s_cmp_lg_u32 s45, 1
	s_cbranch_scc1 .Lmy_sk_23_0
	global_load_lds_dwordx4 v[148:149], off
.Lmy_sk_23_0:
	v_lshl_add_u64 v[148:149], s[28:29], 0, v[138:139]
	s_add_i32 m0, s41, 0xe000
	s_nop 0
	s_cmp_lg_u32 s45, 1
	s_cbranch_scc1 .Lmy_sk_23_1
	global_load_lds_dwordx4 v[148:149], off
.Lmy_sk_23_1:
	s_cmp_lg_u32 s45, 1
	s_cbranch_scc1 .Lmy_rl_23_0
	s_waitcnt vmcnt(8)
	s_branch .Lmy_rj_23_0

.Lmy_rj_23_0:
	s_waitcnt lgkmcnt(0)
	s_barrier
	s_setprio 1
	s_waitcnt lgkmcnt(0)
	v_mfma_f32_16x16x32_bf16 v[124:127], v[144:147], v[184:187], 0
	v_mfma_f32_16x16x32_bf16 v[120:123], v[160:163], v[184:187], 0
	v_mfma_f32_16x16x32_bf16 v[108:111], v[144:147], v[192:195], 0
	v_mfma_f32_16x16x32_bf16 v[104:107], v[160:163], v[192:195], 0
	v_mfma_f32_16x16x32_bf16 v[92:95], v[144:147], v[200:203], 0
	v_mfma_f32_16x16x32_bf16 v[88:91], v[160:163], v[200:203], 0
	v_mfma_f32_16x16x32_bf16 v[76:79], v[144:147], v[208:211], 0
	v_mfma_f32_16x16x32_bf16 v[72:75], v[160:163], v[208:211], 0
	v_mfma_f32_16x16x32_bf16 v[124:127], v[156:159], v[188:191], v[124:127]
	v_mfma_f32_16x16x32_bf16 v[120:123], v[164:167], v[188:191], v[120:123]
	v_mfma_f32_16x16x32_bf16 v[108:111], v[156:159], v[196:199], v[108:111]
	v_mfma_f32_16x16x32_bf16 v[104:107], v[164:167], v[196:199], v[104:107]
	v_mfma_f32_16x16x32_bf16 v[92:95], v[156:159], v[204:207], v[92:95]
	v_mfma_f32_16x16x32_bf16 v[88:91], v[164:167], v[204:207], v[88:91]
	v_mfma_f32_16x16x32_bf16 v[76:79], v[156:159], v[212:215], v[76:79]
	v_mfma_f32_16x16x32_bf16 v[72:75], v[164:167], v[212:215], v[72:75]
	s_setprio 0
	s_setprio 1
	v_mfma_f32_16x16x32_bf16 v[116:119], v[168:171], v[184:187], 0
	v_mfma_f32_16x16x32_bf16 v[112:115], v[176:179], v[184:187], 0
	v_mfma_f32_16x16x32_bf16 v[100:103], v[168:171], v[192:195], 0
	v_mfma_f32_16x16x32_bf16 v[96:99], v[176:179], v[192:195], 0
	v_mfma_f32_16x16x32_bf16 v[84:87], v[168:171], v[200:203], 0
	v_mfma_f32_16x16x32_bf16 v[80:83], v[176:179], v[200:203], 0
	v_mfma_f32_16x16x32_bf16 v[68:71], v[168:171], v[208:211], 0
	v_mfma_f32_16x16x32_bf16 v[64:67], v[176:179], v[208:211], 0
	v_mfma_f32_16x16x32_bf16 v[116:119], v[172:175], v[188:191], v[116:119]
	v_mfma_f32_16x16x32_bf16 v[112:115], v[180:183], v[188:191], v[112:115]
	v_mfma_f32_16x16x32_bf16 v[100:103], v[172:175], v[196:199], v[100:103]
	v_mfma_f32_16x16x32_bf16 v[96:99], v[180:183], v[196:199], v[96:99]
	v_mfma_f32_16x16x32_bf16 v[84:87], v[172:175], v[204:207], v[84:87]
	v_mfma_f32_16x16x32_bf16 v[80:83], v[180:183], v[204:207], v[80:83]
	v_mfma_f32_16x16x32_bf16 v[68:71], v[172:175], v[212:215], v[68:71]
	v_mfma_f32_16x16x32_bf16 v[64:67], v[180:183], v[212:215], v[64:67]
	s_setprio 0
	s_barrier
	s_add_i32 s34, s50, s40
	v_lshl_add_u64 v[148:149], s[30:31], 0, v[132:133]
	s_mov_b32 m0, s34
	ds_read_b128 v[184:187], v155 offset:16384
	ds_read_b128 v[188:191], v155 offset:17408
	ds_read_b128 v[192:195], v155 offset:18432
	ds_read_b128 v[196:199], v155 offset:19456
	ds_read_b128 v[200:203], v155 offset:20480
	ds_read_b128 v[204:207], v155 offset:21504
	ds_read_b128 v[208:211], v155 offset:22528
	ds_read_b128 v[212:215], v155 offset:23552
	global_load_lds_dwordx4 v[148:149], off
	s_add_i32 m0, s34, 0x2000
	s_add_u32 s34, s30, 0xb0000
	v_lshl_add_u64 v[216:217], s[30:31], 0, v[136:137]
	s_addc_u32 s35, s31, 0
	s_add_i32 s57, s51, s40
	global_load_lds_dwordx4 v[216:217], off
	v_lshl_add_u64 v[218:219], s[34:35], 0, v[132:133]
	s_mov_b32 m0, s57
	v_lshl_add_u64 v[220:221], s[36:37], 0, v[134:135]
	global_load_lds_dwordx4 v[218:219], off
	v_lshl_add_u64 v[218:219], s[34:35], 0, v[136:137]
	s_add_i32 m0, s57, 0x2000
	s_nop 0
	global_load_lds_dwordx4 v[218:219], off
	v_lshl_add_u64 v[218:219], s[36:37], 0, v[130:131]
	s_mov_b32 m0, s41
	s_nop 0
	global_load_lds_dwordx4 v[218:219], off
	s_mov_b32 m0, s42
	s_nop 0
	global_load_lds_dwordx4 v[220:221], off
	s_cmp_lg_u32 s45, 1
	s_cbranch_scc1 .Lmy_rl_23_1
	s_waitcnt vmcnt(8)
	s_branch .Lmy_rj_23_1

.Lmy_rj_23_1:
	s_waitcnt lgkmcnt(0)
	s_barrier
	s_setprio 1
	s_waitcnt lgkmcnt(0)
	v_mfma_f32_16x16x32_bf16 v[60:63], v[144:147], v[184:187], 0
	v_mfma_f32_16x16x32_bf16 v[56:59], v[160:163], v[184:187], 0
	v_mfma_f32_16x16x32_bf16 v[44:47], v[144:147], v[192:195], 0
	v_mfma_f32_16x16x32_bf16 v[40:43], v[160:163], v[192:195], 0
	v_mfma_f32_16x16x32_bf16 v[28:31], v[144:147], v[200:203], 0
	v_mfma_f32_16x16x32_bf16 v[24:27], v[160:163], v[200:203], 0
	v_mfma_f32_16x16x32_bf16 v[12:15], v[144:147], v[208:211], 0
	v_mfma_f32_16x16x32_bf16 v[8:11], v[160:163], v[208:211], 0
	v_mfma_f32_16x16x32_bf16 v[60:63], v[156:159], v[188:191], v[60:63]
	v_mfma_f32_16x16x32_bf16 v[56:59], v[164:167], v[188:191], v[56:59]
	v_mfma_f32_16x16x32_bf16 v[44:47], v[156:159], v[196:199], v[44:47]
	v_mfma_f32_16x16x32_bf16 v[40:43], v[164:167], v[196:199], v[40:43]
	v_mfma_f32_16x16x32_bf16 v[28:31], v[156:159], v[204:207], v[28:31]
	v_mfma_f32_16x16x32_bf16 v[24:27], v[164:167], v[204:207], v[24:27]
	v_mfma_f32_16x16x32_bf16 v[12:15], v[156:159], v[212:215], v[12:15]
	v_mfma_f32_16x16x32_bf16 v[8:11], v[164:167], v[212:215], v[8:11]
	s_setprio 0
	s_setprio 1
	v_mfma_f32_16x16x32_bf16 v[52:55], v[168:171], v[184:187], 0
	v_mfma_f32_16x16x32_bf16 v[48:51], v[176:179], v[184:187], 0
	v_mfma_f32_16x16x32_bf16 v[36:39], v[168:171], v[192:195], 0
	v_mfma_f32_16x16x32_bf16 v[32:35], v[176:179], v[192:195], 0
	v_mfma_f32_16x16x32_bf16 v[20:23], v[168:171], v[200:203], 0
	v_mfma_f32_16x16x32_bf16 v[16:19], v[176:179], v[200:203], 0
	v_mfma_f32_16x16x32_bf16 v[4:7], v[168:171], v[208:211], 0
	v_mfma_f32_16x16x32_bf16 v[0:3], v[176:179], v[208:211], 0
	v_mfma_f32_16x16x32_bf16 v[52:55], v[172:175], v[188:191], v[52:55]
	v_mfma_f32_16x16x32_bf16 v[48:51], v[180:183], v[188:191], v[48:51]
	v_mfma_f32_16x16x32_bf16 v[36:39], v[172:175], v[196:199], v[36:39]
	v_mfma_f32_16x16x32_bf16 v[32:35], v[180:183], v[196:199], v[32:35]
	v_mfma_f32_16x16x32_bf16 v[20:23], v[172:175], v[204:207], v[20:23]
	v_mfma_f32_16x16x32_bf16 v[16:19], v[180:183], v[204:207], v[16:19]
	v_mfma_f32_16x16x32_bf16 v[4:7], v[172:175], v[212:215], v[4:7]
	v_mfma_f32_16x16x32_bf16 v[0:3], v[180:183], v[212:215], v[0:3]
	s_setprio 0
	s_barrier
	s_add_i32 s57, 0, 0x18000
	s_add_i32 s58, 0, 0x1c000
	v_add_u32_e32 v164, s57, v151
	v_add_u32_e32 v180, s58, v151
	ds_read_b128 v[144:147], v164
	ds_read_b128 v[156:159], v164 offset:1024
	ds_read_b128 v[160:163], v164 offset:2048
	ds_read_b128 v[164:167], v164 offset:3072
	ds_read_b128 v[168:171], v180
	ds_read_b128 v[172:175], v180 offset:1024
	ds_read_b128 v[176:179], v180 offset:2048
	ds_read_b128 v[180:183], v180 offset:3072
	s_add_u32 s34, s36, 0xb0000
	s_addc_u32 s35, s37, 0
	s_mov_b32 m0, s43
	v_lshl_add_u64 v[222:223], s[34:35], 0, v[130:131]
	ds_read_b128 v[184:187], v155 offset:32768
	ds_read_b128 v[188:191], v155 offset:33792
	ds_read_b128 v[192:195], v155 offset:34816
	ds_read_b128 v[196:199], v155 offset:35840
	ds_read_b128 v[200:203], v155 offset:36864
	ds_read_b128 v[204:207], v155 offset:37888
	ds_read_b128 v[208:211], v155 offset:38912
	ds_read_b128 v[212:215], v155 offset:39936
	global_load_lds_dwordx4 v[222:223], off
	v_lshl_add_u64 v[222:223], s[34:35], 0, v[134:135]
	s_mov_b32 m0, s44
	s_nop 0
	global_load_lds_dwordx4 v[222:223], off
	s_cmp_lg_u32 s45, 1
	s_cbranch_scc1 .Lmy_rl_23_2
	s_waitcnt vmcnt(8)
	s_branch .Lmy_rj_23_2

.Lmy_rj_23_2:
	s_waitcnt lgkmcnt(0)
	s_barrier
	s_setprio 1
	s_waitcnt lgkmcnt(0)
	v_mfma_f32_16x16x32_bf16 v[124:127], v[144:147], v[184:187], v[124:127]
	v_mfma_f32_16x16x32_bf16 v[120:123], v[160:163], v[184:187], v[120:123]
	v_mfma_f32_16x16x32_bf16 v[108:111], v[144:147], v[192:195], v[108:111]
	v_mfma_f32_16x16x32_bf16 v[104:107], v[160:163], v[192:195], v[104:107]
	v_mfma_f32_16x16x32_bf16 v[92:95], v[144:147], v[200:203], v[92:95]
	v_mfma_f32_16x16x32_bf16 v[88:91], v[160:163], v[200:203], v[88:91]
	v_mfma_f32_16x16x32_bf16 v[76:79], v[144:147], v[208:211], v[76:79]
	v_mfma_f32_16x16x32_bf16 v[72:75], v[160:163], v[208:211], v[72:75]
	v_mfma_f32_16x16x32_bf16 v[124:127], v[156:159], v[188:191], v[124:127]
	v_mfma_f32_16x16x32_bf16 v[120:123], v[164:167], v[188:191], v[120:123]
	v_mfma_f32_16x16x32_bf16 v[108:111], v[156:159], v[196:199], v[108:111]
	v_mfma_f32_16x16x32_bf16 v[104:107], v[164:167], v[196:199], v[104:107]
	v_mfma_f32_16x16x32_bf16 v[92:95], v[156:159], v[204:207], v[92:95]
	v_mfma_f32_16x16x32_bf16 v[88:91], v[164:167], v[204:207], v[88:91]
	v_mfma_f32_16x16x32_bf16 v[76:79], v[156:159], v[212:215], v[76:79]
	v_mfma_f32_16x16x32_bf16 v[72:75], v[164:167], v[212:215], v[72:75]
	s_setprio 0
	s_setprio 1
	v_mfma_f32_16x16x32_bf16 v[116:119], v[168:171], v[184:187], v[116:119]
	v_mfma_f32_16x16x32_bf16 v[112:115], v[176:179], v[184:187], v[112:115]
	v_mfma_f32_16x16x32_bf16 v[100:103], v[168:171], v[192:195], v[100:103]
	v_mfma_f32_16x16x32_bf16 v[96:99], v[176:179], v[192:195], v[96:99]
	v_mfma_f32_16x16x32_bf16 v[84:87], v[168:171], v[200:203], v[84:87]
	v_mfma_f32_16x16x32_bf16 v[80:83], v[176:179], v[200:203], v[80:83]
	v_mfma_f32_16x16x32_bf16 v[68:71], v[168:171], v[208:211], v[68:71]
	v_mfma_f32_16x16x32_bf16 v[64:67], v[176:179], v[208:211], v[64:67]
	v_mfma_f32_16x16x32_bf16 v[116:119], v[172:175], v[188:191], v[116:119]
	v_mfma_f32_16x16x32_bf16 v[112:115], v[180:183], v[188:191], v[112:115]
	v_mfma_f32_16x16x32_bf16 v[100:103], v[172:175], v[196:199], v[100:103]
	v_mfma_f32_16x16x32_bf16 v[96:99], v[180:183], v[196:199], v[96:99]
	v_mfma_f32_16x16x32_bf16 v[84:87], v[172:175], v[204:207], v[84:87]
	v_mfma_f32_16x16x32_bf16 v[80:83], v[180:183], v[204:207], v[80:83]
	v_mfma_f32_16x16x32_bf16 v[68:71], v[172:175], v[212:215], v[68:71]
	v_mfma_f32_16x16x32_bf16 v[64:67], v[180:183], v[212:215], v[64:67]
	s_setprio 0
	s_barrier
	s_add_i32 s34, s57, s40
	v_lshl_add_u64 v[148:149], v[148:149], 0, s[8:9]
	s_mov_b32 m0, s34
	ds_read_b128 v[184:187], v155 offset:49152
	ds_read_b128 v[188:191], v155 offset:50176
	ds_read_b128 v[192:195], v155 offset:51200
	ds_read_b128 v[196:199], v155 offset:52224
	ds_read_b128 v[200:203], v155 offset:53248
	ds_read_b128 v[204:207], v155 offset:54272
	ds_read_b128 v[208:211], v155 offset:55296
	ds_read_b128 v[212:215], v155 offset:56320
	global_load_lds_dwordx4 v[148:149], off
	s_add_i32 m0, s34, 0x2000
	s_add_u32 s30, s30, 0xb0080
	v_lshl_add_u64 v[148:149], v[216:217], 0, s[8:9]
	s_addc_u32 s31, s31, 0
	s_add_i32 s34, s58, s40
	global_load_lds_dwordx4 v[148:149], off
	v_lshl_add_u64 v[148:149], s[30:31], 0, v[132:133]
	s_mov_b32 m0, s34
	s_nop 0
	global_load_lds_dwordx4 v[148:149], off
	v_lshl_add_u64 v[148:149], s[30:31], 0, v[136:137]
	s_add_i32 m0, s34, 0x2000
	s_nop 0
	global_load_lds_dwordx4 v[148:149], off
	v_lshl_add_u64 v[148:149], v[218:219], 0, s[8:9]
	s_mov_b32 m0, s46
	s_nop 0
	global_load_lds_dwordx4 v[148:149], off
	v_lshl_add_u64 v[148:149], v[220:221], 0, s[8:9]
	s_mov_b32 m0, s47
	s_nop 0
	global_load_lds_dwordx4 v[148:149], off
	s_waitcnt vmcnt(8)
	s_waitcnt lgkmcnt(0)
	s_barrier
	s_setprio 1
	s_waitcnt lgkmcnt(0)
	v_mfma_f32_16x16x32_bf16 v[60:63], v[144:147], v[184:187], v[60:63]
	v_mfma_f32_16x16x32_bf16 v[56:59], v[160:163], v[184:187], v[56:59]
	v_mfma_f32_16x16x32_bf16 v[44:47], v[144:147], v[192:195], v[44:47]
	v_mfma_f32_16x16x32_bf16 v[40:43], v[160:163], v[192:195], v[40:43]
	v_mfma_f32_16x16x32_bf16 v[28:31], v[144:147], v[200:203], v[28:31]
	v_mfma_f32_16x16x32_bf16 v[24:27], v[160:163], v[200:203], v[24:27]
	v_mfma_f32_16x16x32_bf16 v[12:15], v[144:147], v[208:211], v[12:15]
	v_mfma_f32_16x16x32_bf16 v[8:11], v[160:163], v[208:211], v[8:11]
	v_mfma_f32_16x16x32_bf16 v[60:63], v[156:159], v[188:191], v[60:63]
	v_mfma_f32_16x16x32_bf16 v[56:59], v[164:167], v[188:191], v[56:59]
	v_mfma_f32_16x16x32_bf16 v[44:47], v[156:159], v[196:199], v[44:47]
	v_mfma_f32_16x16x32_bf16 v[40:43], v[164:167], v[196:199], v[40:43]
	v_mfma_f32_16x16x32_bf16 v[28:31], v[156:159], v[204:207], v[28:31]
	v_mfma_f32_16x16x32_bf16 v[24:27], v[164:167], v[204:207], v[24:27]
	v_mfma_f32_16x16x32_bf16 v[12:15], v[156:159], v[212:215], v[12:15]
	v_mfma_f32_16x16x32_bf16 v[8:11], v[164:167], v[212:215], v[8:11]
	s_setprio 0
	s_setprio 1
	v_mfma_f32_16x16x32_bf16 v[52:55], v[168:171], v[184:187], v[52:55]
	v_mfma_f32_16x16x32_bf16 v[48:51], v[176:179], v[184:187], v[48:51]
	v_mfma_f32_16x16x32_bf16 v[36:39], v[168:171], v[192:195], v[36:39]
	v_mfma_f32_16x16x32_bf16 v[32:35], v[176:179], v[192:195], v[32:35]
	v_mfma_f32_16x16x32_bf16 v[20:23], v[168:171], v[200:203], v[20:23]
	v_mfma_f32_16x16x32_bf16 v[16:19], v[176:179], v[200:203], v[16:19]
	v_mfma_f32_16x16x32_bf16 v[4:7], v[168:171], v[208:211], v[4:7]
	v_mfma_f32_16x16x32_bf16 v[0:3], v[176:179], v[208:211], v[0:3]
	v_mfma_f32_16x16x32_bf16 v[52:55], v[172:175], v[188:191], v[52:55]
	v_mfma_f32_16x16x32_bf16 v[48:51], v[180:183], v[188:191], v[48:51]
	v_mfma_f32_16x16x32_bf16 v[36:39], v[172:175], v[196:199], v[36:39]
	v_mfma_f32_16x16x32_bf16 v[32:35], v[180:183], v[196:199], v[32:35]
	v_mfma_f32_16x16x32_bf16 v[20:23], v[172:175], v[204:207], v[20:23]
	v_mfma_f32_16x16x32_bf16 v[16:19], v[180:183], v[204:207], v[16:19]
	v_mfma_f32_16x16x32_bf16 v[4:7], v[172:175], v[212:215], v[4:7]
	v_mfma_f32_16x16x32_bf16 v[0:3], v[180:183], v[212:215], v[0:3]
	s_setprio 0
	s_barrier
	s_add_i32 s56, s56, 2
	s_add_u32 s28, s28, 0x100
	s_addc_u32 s29, s29, 0
	s_add_u32 s54, s54, 0x100
	s_addc_u32 s55, s55, 0

.Lmy_nobar_23:
	s_add_i32 s56, s56, 2
	s_add_u32 s28, s28, 0x100
	s_addc_u32 s29, s29, 0
	s_add_u32 s54, s54, 0x100
	s_addc_u32 s55, s55, 0
	s_cmp_gt_u32 s56, 41
	s_cbranch_scc0 .LBB0_2174
	s_add_u32 s100, s0, 0xb0080
	s_addc_u32 s101, s1, 0
	s_add_i32 m0, s41, 0xc000
	v_lshl_add_u64 v[148:149], s[100:101], 0, v[128:129]
	global_load_lds_dwordx4 v[148:149], off
	s_add_i32 m0, s41, 0xe000
	v_lshl_add_u64 v[148:149], s[100:101], 0, v[138:139]
	global_load_lds_dwordx4 v[148:149], off
	s_and_b64 vcc, exec, s[10:11]
	s_cbranch_vccz .LBB0_2177
	s_nop 0
